# ssm_c WC loop + Kt staging + ssm_a loops: serialized global loads de-serialized (ring prefetch), on top of hand-scheduled attention
# speedup vs baseline: 1.0748x; 1.0104x over previous
; #define LAS __attribute__((address_space(3)))
; __device__ __forceinline__ void ssm_a_task(unsigned char* ws, LAS unsigned char* lds, int task, int tid) {
;     ...
;     for (int hh = 0; hh < 2; ++hh) {
;         ssm_stage_u(ws, lds, g, cb, hh, tid);
;         __syncthreads();
; #pragma unroll 4
;         for (int ks = 0; ks < 16; ++ks) {
;             bf16x8 bfr[4], afr[2];
; #pragma unroll
;             for (int a = 0; a < 2; ++a) afr[a] = *(const bf16x8*)(WA + (size_t)a * 16 * 1024 + (hh * 16 + ks) * 32);
; #pragma unroll
;             for (int c = 0; c < 4; ++c) bfr[c] = *(const LAS bf16x8*)(lds + SS_UB + (((2 * ks + (kk >> 1)) * 64 + c * 16 + rr) * 32 + (kk & 1) * 16));
; #pragma unroll
;             for (int a = 0; a < 2; ++a)
; #pragma unroll
;                 for (int c = 0; c < 4; ++c) acc[a][c] = __builtin_amdgcn_mfma_f32_16x16x32_bf16(afr[a], bfr[c], acc[a][c], 0, 0, 0);
;         }
.LBB0_604:
	v_add_co_u32_e32 v164, vcc, 0xffff8000, v40
	s_nop 1
	v_addc_co_u32_e32 v165, vcc, -1, v41, vcc
	v_add_u32_e32 v166, 0x10000, v47
	global_load_dwordx4 v[100:103], v[40:41], off offset:-192
	global_load_dwordx4 v[104:107], v[164:165], off offset:-192
	global_load_dwordx4 v[108:111], v[40:41], off offset:-128
	global_load_dwordx4 v[112:115], v[164:165], off offset:-128
	global_load_dwordx4 v[116:119], v[40:41], off offset:-64
	global_load_dwordx4 v[120:123], v[164:165], off offset:-64
	global_load_dwordx4 v[124:127], v[40:41], off offset:0
	global_load_dwordx4 v[128:131], v[164:165], off offset:0
	ds_read_b128 v[132:135], v166 offset:0
	ds_read_b128 v[136:139], v166 offset:512
	ds_read_b128 v[140:143], v166 offset:1024
	ds_read_b128 v[144:147], v166 offset:1536
	ds_read_b128 v[148:151], v166 offset:4096
	ds_read_b128 v[152:155], v166 offset:4608
	ds_read_b128 v[156:159], v166 offset:5120
	ds_read_b128 v[160:163], v166 offset:5632
	s_waitcnt lgkmcnt(4)
	s_waitcnt vmcnt(7)
	v_mfma_f32_16x16x32_bf16 v[12:15], v[100:103], v[132:135], v[12:15]
	v_mfma_f32_16x16x32_bf16 v[8:11], v[100:103], v[136:139], v[8:11]
	v_mfma_f32_16x16x32_bf16 v[4:7], v[100:103], v[140:143], v[4:7]
	v_mfma_f32_16x16x32_bf16 v[0:3], v[100:103], v[144:147], v[0:3]
	s_waitcnt vmcnt(6)
	v_mfma_f32_16x16x32_bf16 v[28:31], v[104:107], v[132:135], v[28:31]
	v_mfma_f32_16x16x32_bf16 v[24:27], v[104:107], v[136:139], v[24:27]
	v_mfma_f32_16x16x32_bf16 v[20:23], v[104:107], v[140:143], v[20:23]
	v_mfma_f32_16x16x32_bf16 v[16:19], v[104:107], v[144:147], v[16:19]
	global_load_dwordx4 v[100:103], v[40:41], off offset:64
	global_load_dwordx4 v[104:107], v[164:165], off offset:64
	ds_read_b128 v[132:135], v166 offset:8192
	ds_read_b128 v[136:139], v166 offset:8704
	ds_read_b128 v[140:143], v166 offset:9216
	ds_read_b128 v[144:147], v166 offset:9728
	s_waitcnt lgkmcnt(4)
	s_waitcnt vmcnt(7)
	v_mfma_f32_16x16x32_bf16 v[12:15], v[108:111], v[148:151], v[12:15]
	v_mfma_f32_16x16x32_bf16 v[8:11], v[108:111], v[152:155], v[8:11]
	v_mfma_f32_16x16x32_bf16 v[4:7], v[108:111], v[156:159], v[4:7]
	v_mfma_f32_16x16x32_bf16 v[0:3], v[108:111], v[160:163], v[0:3]
	s_waitcnt vmcnt(6)
	v_mfma_f32_16x16x32_bf16 v[28:31], v[112:115], v[148:151], v[28:31]
	v_mfma_f32_16x16x32_bf16 v[24:27], v[112:115], v[152:155], v[24:27]
	v_mfma_f32_16x16x32_bf16 v[20:23], v[112:115], v[156:159], v[20:23]
	v_mfma_f32_16x16x32_bf16 v[16:19], v[112:115], v[160:163], v[16:19]
	global_load_dwordx4 v[108:111], v[40:41], off offset:128
	global_load_dwordx4 v[112:115], v[164:165], off offset:128
	ds_read_b128 v[148:151], v166 offset:12288
	ds_read_b128 v[152:155], v166 offset:12800
	ds_read_b128 v[156:159], v166 offset:13312
	ds_read_b128 v[160:163], v166 offset:13824
	s_waitcnt lgkmcnt(4)
	s_waitcnt vmcnt(7)
	v_mfma_f32_16x16x32_bf16 v[12:15], v[116:119], v[132:135], v[12:15]
	v_mfma_f32_16x16x32_bf16 v[8:11], v[116:119], v[136:139], v[8:11]
	v_mfma_f32_16x16x32_bf16 v[4:7], v[116:119], v[140:143], v[4:7]
	v_mfma_f32_16x16x32_bf16 v[0:3], v[116:119], v[144:147], v[0:3]
	s_waitcnt vmcnt(6)
	v_mfma_f32_16x16x32_bf16 v[28:31], v[120:123], v[132:135], v[28:31]
	v_mfma_f32_16x16x32_bf16 v[24:27], v[120:123], v[136:139], v[24:27]
	v_mfma_f32_16x16x32_bf16 v[20:23], v[120:123], v[140:143], v[20:23]
	v_mfma_f32_16x16x32_bf16 v[16:19], v[120:123], v[144:147], v[16:19]
	global_load_dwordx4 v[116:119], v[40:41], off offset:192
	global_load_dwordx4 v[120:123], v[164:165], off offset:192
	ds_read_b128 v[132:135], v166 offset:16384
	ds_read_b128 v[136:139], v166 offset:16896
	ds_read_b128 v[140:143], v166 offset:17408
	ds_read_b128 v[144:147], v166 offset:17920
	s_waitcnt lgkmcnt(4)
	s_waitcnt vmcnt(7)
	v_mfma_f32_16x16x32_bf16 v[12:15], v[124:127], v[148:151], v[12:15]
	v_mfma_f32_16x16x32_bf16 v[8:11], v[124:127], v[152:155], v[8:11]
	v_mfma_f32_16x16x32_bf16 v[4:7], v[124:127], v[156:159], v[4:7]
	v_mfma_f32_16x16x32_bf16 v[0:3], v[124:127], v[160:163], v[0:3]
	s_waitcnt vmcnt(6)
	v_mfma_f32_16x16x32_bf16 v[28:31], v[128:131], v[148:151], v[28:31]
	v_mfma_f32_16x16x32_bf16 v[24:27], v[128:131], v[152:155], v[24:27]
	v_mfma_f32_16x16x32_bf16 v[20:23], v[128:131], v[156:159], v[20:23]
	v_mfma_f32_16x16x32_bf16 v[16:19], v[128:131], v[160:163], v[16:19]
	global_load_dwordx4 v[124:127], v[40:41], off offset:256
	global_load_dwordx4 v[128:131], v[164:165], off offset:256
	ds_read_b128 v[148:151], v166 offset:20480
	ds_read_b128 v[152:155], v166 offset:20992
	ds_read_b128 v[156:159], v166 offset:21504
	ds_read_b128 v[160:163], v166 offset:22016
	s_waitcnt lgkmcnt(4)
	s_waitcnt vmcnt(7)
	v_mfma_f32_16x16x32_bf16 v[12:15], v[100:103], v[132:135], v[12:15]
	v_mfma_f32_16x16x32_bf16 v[8:11], v[100:103], v[136:139], v[8:11]
	v_mfma_f32_16x16x32_bf16 v[4:7], v[100:103], v[140:143], v[4:7]
	v_mfma_f32_16x16x32_bf16 v[0:3], v[100:103], v[144:147], v[0:3]
	s_waitcnt vmcnt(6)
	v_mfma_f32_16x16x32_bf16 v[28:31], v[104:107], v[132:135], v[28:31]
	v_mfma_f32_16x16x32_bf16 v[24:27], v[104:107], v[136:139], v[24:27]
	v_mfma_f32_16x16x32_bf16 v[20:23], v[104:107], v[140:143], v[20:23]
	v_mfma_f32_16x16x32_bf16 v[16:19], v[104:107], v[144:147], v[16:19]
	global_load_dwordx4 v[100:103], v[40:41], off offset:320
	global_load_dwordx4 v[104:107], v[164:165], off offset:320
	ds_read_b128 v[132:135], v166 offset:24576
	ds_read_b128 v[136:139], v166 offset:25088
	ds_read_b128 v[140:143], v166 offset:25600
	ds_read_b128 v[144:147], v166 offset:26112
	s_waitcnt lgkmcnt(4)
	s_waitcnt vmcnt(7)
	v_mfma_f32_16x16x32_bf16 v[12:15], v[108:111], v[148:151], v[12:15]
	v_mfma_f32_16x16x32_bf16 v[8:11], v[108:111], v[152:155], v[8:11]
	v_mfma_f32_16x16x32_bf16 v[4:7], v[108:111], v[156:159], v[4:7]
	v_mfma_f32_16x16x32_bf16 v[0:3], v[108:111], v[160:163], v[0:3]
	s_waitcnt vmcnt(6)
; #define LAS __attribute__((address_space(3)))
; __device__ __forceinline__ void ssm_a_task(unsigned char* ws, LAS unsigned char* lds, int task, int tid) {
;     ...
;         for (int ks = 0; ks < 16; ++ks) {
;             bf16x8 bfr[4], afr[2];
; #pragma unroll
;             for (int a = 0; a < 2; ++a) afr[a] = *(const bf16x8*)(WA + (size_t)a * 16 * 1024 + (hh * 16 + ks) * 32);
; #pragma unroll
;             for (int c = 0; c < 4; ++c) bfr[c] = *(const LAS bf16x8*)(lds + SS_UB + (((2 * ks + (kk >> 1)) * 64 + c * 16 + rr) * 32 + (kk & 1) * 16));
; #pragma unroll
;             for (int a = 0; a < 2; ++a)
; #pragma unroll
;                 for (int c = 0; c < 4; ++c) acc[a][c] = __builtin_amdgcn_mfma_f32_16x16x32_bf16(afr[a], bfr[c], acc[a][c], 0, 0, 0);
;         }
	v_mfma_f32_16x16x32_bf16 v[28:31], v[112:115], v[148:151], v[28:31]
	v_mfma_f32_16x16x32_bf16 v[24:27], v[112:115], v[152:155], v[24:27]
	v_mfma_f32_16x16x32_bf16 v[20:23], v[112:115], v[156:159], v[20:23]
	v_mfma_f32_16x16x32_bf16 v[16:19], v[112:115], v[160:163], v[16:19]
	global_load_dwordx4 v[108:111], v[40:41], off offset:384
	global_load_dwordx4 v[112:115], v[164:165], off offset:384
	ds_read_b128 v[148:151], v166 offset:28672
	ds_read_b128 v[152:155], v166 offset:29184
	ds_read_b128 v[156:159], v166 offset:29696
	ds_read_b128 v[160:163], v166 offset:30208
	s_waitcnt lgkmcnt(4)
	s_waitcnt vmcnt(7)
	v_mfma_f32_16x16x32_bf16 v[12:15], v[116:119], v[132:135], v[12:15]
	v_mfma_f32_16x16x32_bf16 v[8:11], v[116:119], v[136:139], v[8:11]
	v_mfma_f32_16x16x32_bf16 v[4:7], v[116:119], v[140:143], v[4:7]
	v_mfma_f32_16x16x32_bf16 v[0:3], v[116:119], v[144:147], v[0:3]
	s_waitcnt vmcnt(6)
	v_mfma_f32_16x16x32_bf16 v[28:31], v[120:123], v[132:135], v[28:31]
	v_mfma_f32_16x16x32_bf16 v[24:27], v[120:123], v[136:139], v[24:27]
	v_mfma_f32_16x16x32_bf16 v[20:23], v[120:123], v[140:143], v[20:23]
	v_mfma_f32_16x16x32_bf16 v[16:19], v[120:123], v[144:147], v[16:19]
	global_load_dwordx4 v[116:119], v[40:41], off offset:448
	global_load_dwordx4 v[120:123], v[164:165], off offset:448
	ds_read_b128 v[132:135], v166 offset:32768
	ds_read_b128 v[136:139], v166 offset:33280
	ds_read_b128 v[140:143], v166 offset:33792
	ds_read_b128 v[144:147], v166 offset:34304
	s_waitcnt lgkmcnt(4)
	s_waitcnt vmcnt(7)
	v_mfma_f32_16x16x32_bf16 v[12:15], v[124:127], v[148:151], v[12:15]
	v_mfma_f32_16x16x32_bf16 v[8:11], v[124:127], v[152:155], v[8:11]
	v_mfma_f32_16x16x32_bf16 v[4:7], v[124:127], v[156:159], v[4:7]
	v_mfma_f32_16x16x32_bf16 v[0:3], v[124:127], v[160:163], v[0:3]
	s_waitcnt vmcnt(6)
	v_mfma_f32_16x16x32_bf16 v[28:31], v[128:131], v[148:151], v[28:31]
	v_mfma_f32_16x16x32_bf16 v[24:27], v[128:131], v[152:155], v[24:27]
	v_mfma_f32_16x16x32_bf16 v[20:23], v[128:131], v[156:159], v[20:23]
	v_mfma_f32_16x16x32_bf16 v[16:19], v[128:131], v[160:163], v[16:19]
	global_load_dwordx4 v[124:127], v[40:41], off offset:512
	global_load_dwordx4 v[128:131], v[164:165], off offset:512
	ds_read_b128 v[148:151], v166 offset:36864
	ds_read_b128 v[152:155], v166 offset:37376
	ds_read_b128 v[156:159], v166 offset:37888
	ds_read_b128 v[160:163], v166 offset:38400
	s_waitcnt lgkmcnt(4)
	s_waitcnt vmcnt(7)
	v_mfma_f32_16x16x32_bf16 v[12:15], v[100:103], v[132:135], v[12:15]
	v_mfma_f32_16x16x32_bf16 v[8:11], v[100:103], v[136:139], v[8:11]
	v_mfma_f32_16x16x32_bf16 v[4:7], v[100:103], v[140:143], v[4:7]
	v_mfma_f32_16x16x32_bf16 v[0:3], v[100:103], v[144:147], v[0:3]
	s_waitcnt vmcnt(6)
	v_mfma_f32_16x16x32_bf16 v[28:31], v[104:107], v[132:135], v[28:31]
	v_mfma_f32_16x16x32_bf16 v[24:27], v[104:107], v[136:139], v[24:27]
	v_mfma_f32_16x16x32_bf16 v[20:23], v[104:107], v[140:143], v[20:23]
	v_mfma_f32_16x16x32_bf16 v[16:19], v[104:107], v[144:147], v[16:19]
	global_load_dwordx4 v[100:103], v[40:41], off offset:576
	global_load_dwordx4 v[104:107], v[164:165], off offset:576
	ds_read_b128 v[132:135], v166 offset:40960
	ds_read_b128 v[136:139], v166 offset:41472
	ds_read_b128 v[140:143], v166 offset:41984
	ds_read_b128 v[144:147], v166 offset:42496
	s_waitcnt lgkmcnt(4)
	s_waitcnt vmcnt(7)
	v_mfma_f32_16x16x32_bf16 v[12:15], v[108:111], v[148:151], v[12:15]
	v_mfma_f32_16x16x32_bf16 v[8:11], v[108:111], v[152:155], v[8:11]
	v_mfma_f32_16x16x32_bf16 v[4:7], v[108:111], v[156:159], v[4:7]
	v_mfma_f32_16x16x32_bf16 v[0:3], v[108:111], v[160:163], v[0:3]
	s_waitcnt vmcnt(6)
	v_mfma_f32_16x16x32_bf16 v[28:31], v[112:115], v[148:151], v[28:31]
	v_mfma_f32_16x16x32_bf16 v[24:27], v[112:115], v[152:155], v[24:27]
	v_mfma_f32_16x16x32_bf16 v[20:23], v[112:115], v[156:159], v[20:23]
	v_mfma_f32_16x16x32_bf16 v[16:19], v[112:115], v[160:163], v[16:19]
	global_load_dwordx4 v[108:111], v[40:41], off offset:640
	global_load_dwordx4 v[112:115], v[164:165], off offset:640
	ds_read_b128 v[148:151], v166 offset:45056
	ds_read_b128 v[152:155], v166 offset:45568
	ds_read_b128 v[156:159], v166 offset:46080
	ds_read_b128 v[160:163], v166 offset:46592
	s_waitcnt lgkmcnt(4)
	s_waitcnt vmcnt(7)
	v_mfma_f32_16x16x32_bf16 v[12:15], v[116:119], v[132:135], v[12:15]
	v_mfma_f32_16x16x32_bf16 v[8:11], v[116:119], v[136:139], v[8:11]
	v_mfma_f32_16x16x32_bf16 v[4:7], v[116:119], v[140:143], v[4:7]
	v_mfma_f32_16x16x32_bf16 v[0:3], v[116:119], v[144:147], v[0:3]
	s_waitcnt vmcnt(6)
	v_mfma_f32_16x16x32_bf16 v[28:31], v[120:123], v[132:135], v[28:31]
	v_mfma_f32_16x16x32_bf16 v[24:27], v[120:123], v[136:139], v[24:27]
	v_mfma_f32_16x16x32_bf16 v[20:23], v[120:123], v[140:143], v[20:23]
	v_mfma_f32_16x16x32_bf16 v[16:19], v[120:123], v[144:147], v[16:19]
	global_load_dwordx4 v[116:119], v[40:41], off offset:704
	global_load_dwordx4 v[120:123], v[164:165], off offset:704
	ds_read_b128 v[132:135], v166 offset:49152
	ds_read_b128 v[136:139], v166 offset:49664
	ds_read_b128 v[140:143], v166 offset:50176
	ds_read_b128 v[144:147], v166 offset:50688
	s_waitcnt lgkmcnt(4)
	s_waitcnt vmcnt(7)
	v_mfma_f32_16x16x32_bf16 v[12:15], v[124:127], v[148:151], v[12:15]
	v_mfma_f32_16x16x32_bf16 v[8:11], v[124:127], v[152:155], v[8:11]
	v_mfma_f32_16x16x32_bf16 v[4:7], v[124:127], v[156:159], v[4:7]
	v_mfma_f32_16x16x32_bf16 v[0:3], v[124:127], v[160:163], v[0:3]
	s_waitcnt vmcnt(6)
; #define LAS __attribute__((address_space(3)))
; __device__ __forceinline__ void ssm_stage_u(unsigned char* ws, LAS unsigned char* lds, int g, int cb, int hh, int tid) {
;     asm volatile("" : "+v"(tid));
;     const bf16* U = (const bf16*)(ws + AR_U);
;     u32x4 v[8];
; #pragma unroll
;     for (int r = 0; r < 8; ++r) { const int c = r * 512 + tid, jj = c >> 7, col = (c >> 1) & 63, part = c & 1;
;         v[r] = *(const u32x4*)(U + ((size_t)((cb * 64 + col) * 64 + hh * 32 + jj) * 512 + g * 16 + part * 8)); }
; #pragma unroll
;     for (int r = 0; r < 8; ++r) { const int c = r * 512 + tid; *(LAS u32x4*)(lds + SS_UB + c * 16) = v[r]; }
; }
; __device__ __forceinline__ void ssm_a_task(unsigned char* ws, LAS unsigned char* lds, int task, int tid) {
;     ...
;         for (int ks = 0; ks < 16; ++ks) {
;             bf16x8 bfr[4], afr[2];
; #pragma unroll
;             for (int a = 0; a < 2; ++a) afr[a] = *(const bf16x8*)(WA + (size_t)a * 16 * 1024 + (hh * 16 + ks) * 32);
; #pragma unroll
;             for (int c = 0; c < 4; ++c) bfr[c] = *(const LAS bf16x8*)(lds + SS_UB + (((2 * ks + (kk >> 1)) * 64 + c * 16 + rr) * 32 + (kk & 1) * 16));
; #pragma unroll
;             for (int a = 0; a < 2; ++a)
; #pragma unroll
;                 for (int c = 0; c < 4; ++c) acc[a][c] = __builtin_amdgcn_mfma_f32_16x16x32_bf16(afr[a], bfr[c], acc[a][c], 0, 0, 0);
;         }
;         __syncthreads();
	v_mfma_f32_16x16x32_bf16 v[28:31], v[128:131], v[148:151], v[28:31]
	v_mfma_f32_16x16x32_bf16 v[24:27], v[128:131], v[152:155], v[24:27]
	v_mfma_f32_16x16x32_bf16 v[20:23], v[128:131], v[156:159], v[20:23]
	v_mfma_f32_16x16x32_bf16 v[16:19], v[128:131], v[160:163], v[16:19]
	global_load_dwordx4 v[124:127], v[40:41], off offset:768
	global_load_dwordx4 v[128:131], v[164:165], off offset:768
	ds_read_b128 v[148:151], v166 offset:53248
	ds_read_b128 v[152:155], v166 offset:53760
	ds_read_b128 v[156:159], v166 offset:54272
	ds_read_b128 v[160:163], v166 offset:54784
	s_waitcnt lgkmcnt(4)
	s_waitcnt vmcnt(7)
	v_mfma_f32_16x16x32_bf16 v[12:15], v[100:103], v[132:135], v[12:15]
	v_mfma_f32_16x16x32_bf16 v[8:11], v[100:103], v[136:139], v[8:11]
	v_mfma_f32_16x16x32_bf16 v[4:7], v[100:103], v[140:143], v[4:7]
	v_mfma_f32_16x16x32_bf16 v[0:3], v[100:103], v[144:147], v[0:3]
	s_waitcnt vmcnt(6)
	v_mfma_f32_16x16x32_bf16 v[28:31], v[104:107], v[132:135], v[28:31]
	v_mfma_f32_16x16x32_bf16 v[24:27], v[104:107], v[136:139], v[24:27]
	v_mfma_f32_16x16x32_bf16 v[20:23], v[104:107], v[140:143], v[20:23]
	v_mfma_f32_16x16x32_bf16 v[16:19], v[104:107], v[144:147], v[16:19]
	ds_read_b128 v[132:135], v166 offset:57344
	ds_read_b128 v[136:139], v166 offset:57856
	ds_read_b128 v[140:143], v166 offset:58368
	ds_read_b128 v[144:147], v166 offset:58880
	s_waitcnt lgkmcnt(4)
	s_waitcnt vmcnt(5)
	v_mfma_f32_16x16x32_bf16 v[12:15], v[108:111], v[148:151], v[12:15]
	v_mfma_f32_16x16x32_bf16 v[8:11], v[108:111], v[152:155], v[8:11]
	v_mfma_f32_16x16x32_bf16 v[4:7], v[108:111], v[156:159], v[4:7]
	v_mfma_f32_16x16x32_bf16 v[0:3], v[108:111], v[160:163], v[0:3]
	s_waitcnt vmcnt(4)
	v_mfma_f32_16x16x32_bf16 v[28:31], v[112:115], v[148:151], v[28:31]
	v_mfma_f32_16x16x32_bf16 v[24:27], v[112:115], v[152:155], v[24:27]
	v_mfma_f32_16x16x32_bf16 v[20:23], v[112:115], v[156:159], v[20:23]
	v_mfma_f32_16x16x32_bf16 v[16:19], v[112:115], v[160:163], v[16:19]
	ds_read_b128 v[148:151], v166 offset:61440
	ds_read_b128 v[152:155], v166 offset:61952
	ds_read_b128 v[156:159], v166 offset:62464
	ds_read_b128 v[160:163], v166 offset:62976
	s_waitcnt lgkmcnt(4)
	s_waitcnt vmcnt(3)
	v_mfma_f32_16x16x32_bf16 v[12:15], v[116:119], v[132:135], v[12:15]
	v_mfma_f32_16x16x32_bf16 v[8:11], v[116:119], v[136:139], v[8:11]
	v_mfma_f32_16x16x32_bf16 v[4:7], v[116:119], v[140:143], v[4:7]
	v_mfma_f32_16x16x32_bf16 v[0:3], v[116:119], v[144:147], v[0:3]
	s_waitcnt vmcnt(2)
	v_mfma_f32_16x16x32_bf16 v[28:31], v[120:123], v[132:135], v[28:31]
	v_mfma_f32_16x16x32_bf16 v[24:27], v[120:123], v[136:139], v[24:27]
	v_mfma_f32_16x16x32_bf16 v[20:23], v[120:123], v[140:143], v[20:23]
	v_mfma_f32_16x16x32_bf16 v[16:19], v[120:123], v[144:147], v[16:19]
	s_waitcnt lgkmcnt(0)
	s_waitcnt vmcnt(1)
	v_mfma_f32_16x16x32_bf16 v[12:15], v[124:127], v[148:151], v[12:15]
	v_mfma_f32_16x16x32_bf16 v[8:11], v[124:127], v[152:155], v[8:11]
	v_mfma_f32_16x16x32_bf16 v[4:7], v[124:127], v[156:159], v[4:7]
	v_mfma_f32_16x16x32_bf16 v[0:3], v[124:127], v[160:163], v[0:3]
	s_waitcnt vmcnt(0)
	v_mfma_f32_16x16x32_bf16 v[28:31], v[128:131], v[148:151], v[28:31]
	v_mfma_f32_16x16x32_bf16 v[24:27], v[128:131], v[152:155], v[24:27]
	v_mfma_f32_16x16x32_bf16 v[20:23], v[128:131], v[156:159], v[20:23]
	v_mfma_f32_16x16x32_bf16 v[16:19], v[128:131], v[160:163], v[16:19]
	s_mov_b32 s12, 0x10000
	v_mov_b32_e32 v72, v44
	s_barrier
	v_lshl_add_u64 v[38:39], v[36:37], 0, v[38:39]
	v_lshlrev_b32_e32 v40, 5, v72
	v_and_b32_e32 v40, 0xfc0, v40
	v_or3_b32 v73, s3, v40, 32
	v_lshlrev_b32_e32 v76, 4, v72
	v_ashrrev_i32_e32 v40, 7, v72
	v_add_u32_e32 v42, 0x200, v72
	v_add_u32_e32 v52, 0x400, v72
	v_add_u32_e32 v54, 0x600, v72
	v_add_u32_e32 v60, 0x800, v72
	v_add_u32_e32 v62, 0xa00, v72
	v_add_u32_e32 v70, 0xc00, v72
	v_add_u32_e32 v72, 0xe00, v72
	v_ashrrev_i32_e32 v42, 7, v42
	v_ashrrev_i32_e32 v52, 7, v52
	v_ashrrev_i32_e32 v54, 7, v54
	v_ashrrev_i32_e32 v60, 7, v60
	v_ashrrev_i32_e32 v62, 7, v62
	v_ashrrev_i32_e32 v70, 7, v70
	v_ashrrev_i32_e32 v72, 7, v72
	v_add_u32_e32 v40, v73, v40
	v_add_u32_e32 v42, v73, v42
	v_add_u32_e32 v52, v73, v52
	v_add_u32_e32 v54, v73, v54
	v_add_u32_e32 v60, v73, v60
	v_add_u32_e32 v62, v73, v62
	v_add_u32_e32 v70, v73, v70
	v_add_u32_e32 v72, v73, v72
	v_and_b32_e32 v184, 16, v76
	v_ashrrev_i32_e32 v41, 31, v40
	v_ashrrev_i32_e32 v43, 31, v42
	v_ashrrev_i32_e32 v53, 31, v52
	v_ashrrev_i32_e32 v55, 31, v54
	v_ashrrev_i32_e32 v61, 31, v60
	v_ashrrev_i32_e32 v63, 31, v62
	v_ashrrev_i32_e32 v71, 31, v70
	v_ashrrev_i32_e32 v73, 31, v72
	v_lshl_add_u64 v[68:69], s[34:35], 0, v[184:185]
	v_lshlrev_b64 v[40:41], 10, v[40:41]
	v_lshlrev_b64 v[42:43], 10, v[42:43]
	v_lshlrev_b64 v[52:53], 10, v[52:53]
	v_lshlrev_b64 v[54:55], 10, v[54:55]
	v_lshlrev_b64 v[60:61], 10, v[60:61]
	v_lshlrev_b64 v[62:63], 10, v[62:63]
	v_lshlrev_b64 v[70:71], 10, v[70:71]
	v_lshlrev_b64 v[72:73], 10, v[72:73]
	v_lshl_add_u64 v[40:41], v[68:69], 0, v[40:41]
	v_lshl_add_u64 v[48:49], v[68:69], 0, v[42:43]
	v_lshl_add_u64 v[52:53], v[68:69], 0, v[52:53]
	v_lshl_add_u64 v[56:57], v[68:69], 0, v[54:55]
	v_lshl_add_u64 v[60:61], v[68:69], 0, v[60:61]
	v_lshl_add_u64 v[64:65], v[68:69], 0, v[62:63]
	v_lshl_add_u64 v[70:71], v[68:69], 0, v[70:71]
	v_lshl_add_u64 v[72:73], v[68:69], 0, v[72:73]
	global_load_dwordx4 v[40:43], v[40:41], off
	s_nop 0
	global_load_dwordx4 v[48:51], v[48:49], off
	s_nop 0
	global_load_dwordx4 v[52:55], v[52:53], off
	s_nop 0
	global_load_dwordx4 v[56:59], v[56:57], off
	s_nop 0
	global_load_dwordx4 v[60:63], v[60:61], off
	s_nop 0
	global_load_dwordx4 v[64:67], v[64:65], off
	s_nop 0
	global_load_dwordx4 v[68:71], v[70:71], off
	s_nop 0
	global_load_dwordx4 v[72:75], v[72:73], off
	v_add_u32_e32 v76, 0, v76
	v_add_u32_e32 v76, 0x10000, v76
	s_mov_b32 s3, 0
	s_waitcnt vmcnt(7)
	ds_write_b128 v76, v[40:43]
	s_waitcnt vmcnt(6)
	ds_write_b128 v76, v[48:51] offset:8192
	s_waitcnt vmcnt(5)
	ds_write_b128 v76, v[52:55] offset:16384
	s_waitcnt vmcnt(4)
	ds_write_b128 v76, v[56:59] offset:24576
	s_waitcnt vmcnt(3)
	ds_write_b128 v76, v[60:63] offset:32768
	s_waitcnt vmcnt(2)
	ds_write_b128 v76, v[64:67] offset:40960
	s_waitcnt vmcnt(1)
	ds_write_b128 v76, v[68:71] offset:49152
	s_waitcnt vmcnt(0)
	ds_write_b128 v76, v[72:75] offset:57344
	s_waitcnt lgkmcnt(0)
	s_barrier
; #define LAS __attribute__((address_space(3)))
; __device__ __forceinline__ void ssm_a_task(unsigned char* ws, LAS unsigned char* lds, int task, int tid) {
;     ...
; #pragma unroll 4
;         for (int ks = 0; ks < 16; ++ks) {
;             bf16x8 bfr[4], afr[2];
; #pragma unroll
;             for (int a = 0; a < 2; ++a) afr[a] = *(const bf16x8*)(WA + (size_t)a * 16 * 1024 + (hh * 16 + ks) * 32);
; #pragma unroll
;             for (int c = 0; c < 4; ++c) bfr[c] = *(const LAS bf16x8*)(lds + SS_UB + (((2 * ks + (kk >> 1)) * 64 + c * 16 + rr) * 32 + (kk & 1) * 16));
; #pragma unroll
;             for (int a = 0; a < 2; ++a)
; #pragma unroll
;                 for (int c = 0; c < 4; ++c) acc[a][c] = __builtin_amdgcn_mfma_f32_16x16x32_bf16(afr[a], bfr[c], acc[a][c], 0, 0, 0);
;         }
.LBB0_606:
	v_add_co_u32_e32 v164, vcc, 0xffff8000, v38
	s_nop 1
	v_addc_co_u32_e32 v165, vcc, -1, v39, vcc
	v_add_u32_e32 v166, 0x10000, v47
	global_load_dwordx4 v[100:103], v[38:39], off offset:-192
	global_load_dwordx4 v[104:107], v[164:165], off offset:-192
	global_load_dwordx4 v[108:111], v[38:39], off offset:-128
	global_load_dwordx4 v[112:115], v[164:165], off offset:-128
	global_load_dwordx4 v[116:119], v[38:39], off offset:-64
	global_load_dwordx4 v[120:123], v[164:165], off offset:-64
	global_load_dwordx4 v[124:127], v[38:39], off offset:0
	global_load_dwordx4 v[128:131], v[164:165], off offset:0
	ds_read_b128 v[132:135], v166 offset:0
	ds_read_b128 v[136:139], v166 offset:512
	ds_read_b128 v[140:143], v166 offset:1024
	ds_read_b128 v[144:147], v166 offset:1536
	ds_read_b128 v[148:151], v166 offset:4096
	ds_read_b128 v[152:155], v166 offset:4608
	ds_read_b128 v[156:159], v166 offset:5120
	ds_read_b128 v[160:163], v166 offset:5632
	s_waitcnt lgkmcnt(4)
	s_waitcnt vmcnt(7)
	v_mfma_f32_16x16x32_bf16 v[12:15], v[100:103], v[132:135], v[12:15]
	v_mfma_f32_16x16x32_bf16 v[8:11], v[100:103], v[136:139], v[8:11]
	v_mfma_f32_16x16x32_bf16 v[4:7], v[100:103], v[140:143], v[4:7]
	v_mfma_f32_16x16x32_bf16 v[0:3], v[100:103], v[144:147], v[0:3]
	s_waitcnt vmcnt(6)
	v_mfma_f32_16x16x32_bf16 v[28:31], v[104:107], v[132:135], v[28:31]
	v_mfma_f32_16x16x32_bf16 v[24:27], v[104:107], v[136:139], v[24:27]
	v_mfma_f32_16x16x32_bf16 v[20:23], v[104:107], v[140:143], v[20:23]
	v_mfma_f32_16x16x32_bf16 v[16:19], v[104:107], v[144:147], v[16:19]
	global_load_dwordx4 v[100:103], v[38:39], off offset:64
	global_load_dwordx4 v[104:107], v[164:165], off offset:64
	ds_read_b128 v[132:135], v166 offset:8192
	ds_read_b128 v[136:139], v166 offset:8704
	ds_read_b128 v[140:143], v166 offset:9216
	ds_read_b128 v[144:147], v166 offset:9728
	s_waitcnt lgkmcnt(4)
	s_waitcnt vmcnt(7)
	v_mfma_f32_16x16x32_bf16 v[12:15], v[108:111], v[148:151], v[12:15]
	v_mfma_f32_16x16x32_bf16 v[8:11], v[108:111], v[152:155], v[8:11]
	v_mfma_f32_16x16x32_bf16 v[4:7], v[108:111], v[156:159], v[4:7]
	v_mfma_f32_16x16x32_bf16 v[0:3], v[108:111], v[160:163], v[0:3]
	s_waitcnt vmcnt(6)
	v_mfma_f32_16x16x32_bf16 v[28:31], v[112:115], v[148:151], v[28:31]
	v_mfma_f32_16x16x32_bf16 v[24:27], v[112:115], v[152:155], v[24:27]
	v_mfma_f32_16x16x32_bf16 v[20:23], v[112:115], v[156:159], v[20:23]
	v_mfma_f32_16x16x32_bf16 v[16:19], v[112:115], v[160:163], v[16:19]
	global_load_dwordx4 v[108:111], v[38:39], off offset:128
	global_load_dwordx4 v[112:115], v[164:165], off offset:128
	ds_read_b128 v[148:151], v166 offset:12288
	ds_read_b128 v[152:155], v166 offset:12800
	ds_read_b128 v[156:159], v166 offset:13312
	ds_read_b128 v[160:163], v166 offset:13824
	s_waitcnt lgkmcnt(4)
	s_waitcnt vmcnt(7)
	v_mfma_f32_16x16x32_bf16 v[12:15], v[116:119], v[132:135], v[12:15]
	v_mfma_f32_16x16x32_bf16 v[8:11], v[116:119], v[136:139], v[8:11]
	v_mfma_f32_16x16x32_bf16 v[4:7], v[116:119], v[140:143], v[4:7]
	v_mfma_f32_16x16x32_bf16 v[0:3], v[116:119], v[144:147], v[0:3]
	s_waitcnt vmcnt(6)
	v_mfma_f32_16x16x32_bf16 v[28:31], v[120:123], v[132:135], v[28:31]
	v_mfma_f32_16x16x32_bf16 v[24:27], v[120:123], v[136:139], v[24:27]
	v_mfma_f32_16x16x32_bf16 v[20:23], v[120:123], v[140:143], v[20:23]
	v_mfma_f32_16x16x32_bf16 v[16:19], v[120:123], v[144:147], v[16:19]
	global_load_dwordx4 v[116:119], v[38:39], off offset:192
	global_load_dwordx4 v[120:123], v[164:165], off offset:192
	ds_read_b128 v[132:135], v166 offset:16384
	ds_read_b128 v[136:139], v166 offset:16896
	ds_read_b128 v[140:143], v166 offset:17408
	ds_read_b128 v[144:147], v166 offset:17920
	s_waitcnt lgkmcnt(4)
	s_waitcnt vmcnt(7)
	v_mfma_f32_16x16x32_bf16 v[12:15], v[124:127], v[148:151], v[12:15]
	v_mfma_f32_16x16x32_bf16 v[8:11], v[124:127], v[152:155], v[8:11]
	v_mfma_f32_16x16x32_bf16 v[4:7], v[124:127], v[156:159], v[4:7]
	v_mfma_f32_16x16x32_bf16 v[0:3], v[124:127], v[160:163], v[0:3]
	s_waitcnt vmcnt(6)
	v_mfma_f32_16x16x32_bf16 v[28:31], v[128:131], v[148:151], v[28:31]
	v_mfma_f32_16x16x32_bf16 v[24:27], v[128:131], v[152:155], v[24:27]
	v_mfma_f32_16x16x32_bf16 v[20:23], v[128:131], v[156:159], v[20:23]
	v_mfma_f32_16x16x32_bf16 v[16:19], v[128:131], v[160:163], v[16:19]
	global_load_dwordx4 v[124:127], v[38:39], off offset:256
	global_load_dwordx4 v[128:131], v[164:165], off offset:256
	ds_read_b128 v[148:151], v166 offset:20480
	ds_read_b128 v[152:155], v166 offset:20992
	ds_read_b128 v[156:159], v166 offset:21504
	ds_read_b128 v[160:163], v166 offset:22016
	s_waitcnt lgkmcnt(4)
	s_waitcnt vmcnt(7)
	v_mfma_f32_16x16x32_bf16 v[12:15], v[100:103], v[132:135], v[12:15]
	v_mfma_f32_16x16x32_bf16 v[8:11], v[100:103], v[136:139], v[8:11]
	v_mfma_f32_16x16x32_bf16 v[4:7], v[100:103], v[140:143], v[4:7]
	v_mfma_f32_16x16x32_bf16 v[0:3], v[100:103], v[144:147], v[0:3]
	s_waitcnt vmcnt(6)
	v_mfma_f32_16x16x32_bf16 v[28:31], v[104:107], v[132:135], v[28:31]
	v_mfma_f32_16x16x32_bf16 v[24:27], v[104:107], v[136:139], v[24:27]
	v_mfma_f32_16x16x32_bf16 v[20:23], v[104:107], v[140:143], v[20:23]
	v_mfma_f32_16x16x32_bf16 v[16:19], v[104:107], v[144:147], v[16:19]
	global_load_dwordx4 v[100:103], v[38:39], off offset:320
	global_load_dwordx4 v[104:107], v[164:165], off offset:320
	ds_read_b128 v[132:135], v166 offset:24576
	ds_read_b128 v[136:139], v166 offset:25088
	ds_read_b128 v[140:143], v166 offset:25600
	ds_read_b128 v[144:147], v166 offset:26112
	s_waitcnt lgkmcnt(4)
	s_waitcnt vmcnt(7)
	v_mfma_f32_16x16x32_bf16 v[12:15], v[108:111], v[148:151], v[12:15]
	v_mfma_f32_16x16x32_bf16 v[8:11], v[108:111], v[152:155], v[8:11]
	v_mfma_f32_16x16x32_bf16 v[4:7], v[108:111], v[156:159], v[4:7]
	v_mfma_f32_16x16x32_bf16 v[0:3], v[108:111], v[160:163], v[0:3]
	s_waitcnt vmcnt(6)
; #define LAS __attribute__((address_space(3)))
; __device__ __forceinline__ void ssm_a_task(unsigned char* ws, LAS unsigned char* lds, int task, int tid) {
;     ...
; #pragma unroll 4
;         for (int ks = 0; ks < 16; ++ks) {
;             bf16x8 bfr[4], afr[2];
; #pragma unroll
;             for (int a = 0; a < 2; ++a) afr[a] = *(const bf16x8*)(WA + (size_t)a * 16 * 1024 + (hh * 16 + ks) * 32);
; #pragma unroll
;             for (int c = 0; c < 4; ++c) bfr[c] = *(const LAS bf16x8*)(lds + SS_UB + (((2 * ks + (kk >> 1)) * 64 + c * 16 + rr) * 32 + (kk & 1) * 16));
; #pragma unroll
;             for (int a = 0; a < 2; ++a)
; #pragma unroll
;                 for (int c = 0; c < 4; ++c) acc[a][c] = __builtin_amdgcn_mfma_f32_16x16x32_bf16(afr[a], bfr[c], acc[a][c], 0, 0, 0);
;         }
	v_mfma_f32_16x16x32_bf16 v[28:31], v[112:115], v[148:151], v[28:31]
	v_mfma_f32_16x16x32_bf16 v[24:27], v[112:115], v[152:155], v[24:27]
	v_mfma_f32_16x16x32_bf16 v[20:23], v[112:115], v[156:159], v[20:23]
	v_mfma_f32_16x16x32_bf16 v[16:19], v[112:115], v[160:163], v[16:19]
	global_load_dwordx4 v[108:111], v[38:39], off offset:384
	global_load_dwordx4 v[112:115], v[164:165], off offset:384
	ds_read_b128 v[148:151], v166 offset:28672
	ds_read_b128 v[152:155], v166 offset:29184
	ds_read_b128 v[156:159], v166 offset:29696
	ds_read_b128 v[160:163], v166 offset:30208
	s_waitcnt lgkmcnt(4)
	s_waitcnt vmcnt(7)
	v_mfma_f32_16x16x32_bf16 v[12:15], v[116:119], v[132:135], v[12:15]
	v_mfma_f32_16x16x32_bf16 v[8:11], v[116:119], v[136:139], v[8:11]
	v_mfma_f32_16x16x32_bf16 v[4:7], v[116:119], v[140:143], v[4:7]
	v_mfma_f32_16x16x32_bf16 v[0:3], v[116:119], v[144:147], v[0:3]
	s_waitcnt vmcnt(6)
	v_mfma_f32_16x16x32_bf16 v[28:31], v[120:123], v[132:135], v[28:31]
	v_mfma_f32_16x16x32_bf16 v[24:27], v[120:123], v[136:139], v[24:27]
	v_mfma_f32_16x16x32_bf16 v[20:23], v[120:123], v[140:143], v[20:23]
	v_mfma_f32_16x16x32_bf16 v[16:19], v[120:123], v[144:147], v[16:19]
	global_load_dwordx4 v[116:119], v[38:39], off offset:448
	global_load_dwordx4 v[120:123], v[164:165], off offset:448
	ds_read_b128 v[132:135], v166 offset:32768
	ds_read_b128 v[136:139], v166 offset:33280
	ds_read_b128 v[140:143], v166 offset:33792
	ds_read_b128 v[144:147], v166 offset:34304
	s_waitcnt lgkmcnt(4)
	s_waitcnt vmcnt(7)
	v_mfma_f32_16x16x32_bf16 v[12:15], v[124:127], v[148:151], v[12:15]
	v_mfma_f32_16x16x32_bf16 v[8:11], v[124:127], v[152:155], v[8:11]
	v_mfma_f32_16x16x32_bf16 v[4:7], v[124:127], v[156:159], v[4:7]
	v_mfma_f32_16x16x32_bf16 v[0:3], v[124:127], v[160:163], v[0:3]
	s_waitcnt vmcnt(6)
	v_mfma_f32_16x16x32_bf16 v[28:31], v[128:131], v[148:151], v[28:31]
	v_mfma_f32_16x16x32_bf16 v[24:27], v[128:131], v[152:155], v[24:27]
	v_mfma_f32_16x16x32_bf16 v[20:23], v[128:131], v[156:159], v[20:23]
	v_mfma_f32_16x16x32_bf16 v[16:19], v[128:131], v[160:163], v[16:19]
	global_load_dwordx4 v[124:127], v[38:39], off offset:512
	global_load_dwordx4 v[128:131], v[164:165], off offset:512
	ds_read_b128 v[148:151], v166 offset:36864
	ds_read_b128 v[152:155], v166 offset:37376
	ds_read_b128 v[156:159], v166 offset:37888
	ds_read_b128 v[160:163], v166 offset:38400
	s_waitcnt lgkmcnt(4)
	s_waitcnt vmcnt(7)
	v_mfma_f32_16x16x32_bf16 v[12:15], v[100:103], v[132:135], v[12:15]
	v_mfma_f32_16x16x32_bf16 v[8:11], v[100:103], v[136:139], v[8:11]
	v_mfma_f32_16x16x32_bf16 v[4:7], v[100:103], v[140:143], v[4:7]
	v_mfma_f32_16x16x32_bf16 v[0:3], v[100:103], v[144:147], v[0:3]
	s_waitcnt vmcnt(6)
	v_mfma_f32_16x16x32_bf16 v[28:31], v[104:107], v[132:135], v[28:31]
	v_mfma_f32_16x16x32_bf16 v[24:27], v[104:107], v[136:139], v[24:27]
	v_mfma_f32_16x16x32_bf16 v[20:23], v[104:107], v[140:143], v[20:23]
	v_mfma_f32_16x16x32_bf16 v[16:19], v[104:107], v[144:147], v[16:19]
	global_load_dwordx4 v[100:103], v[38:39], off offset:576
	global_load_dwordx4 v[104:107], v[164:165], off offset:576
	ds_read_b128 v[132:135], v166 offset:40960
	ds_read_b128 v[136:139], v166 offset:41472
	ds_read_b128 v[140:143], v166 offset:41984
	ds_read_b128 v[144:147], v166 offset:42496
	s_waitcnt lgkmcnt(4)
	s_waitcnt vmcnt(7)
	v_mfma_f32_16x16x32_bf16 v[12:15], v[108:111], v[148:151], v[12:15]
	v_mfma_f32_16x16x32_bf16 v[8:11], v[108:111], v[152:155], v[8:11]
	v_mfma_f32_16x16x32_bf16 v[4:7], v[108:111], v[156:159], v[4:7]
	v_mfma_f32_16x16x32_bf16 v[0:3], v[108:111], v[160:163], v[0:3]
	s_waitcnt vmcnt(6)
	v_mfma_f32_16x16x32_bf16 v[28:31], v[112:115], v[148:151], v[28:31]
	v_mfma_f32_16x16x32_bf16 v[24:27], v[112:115], v[152:155], v[24:27]
	v_mfma_f32_16x16x32_bf16 v[20:23], v[112:115], v[156:159], v[20:23]
	v_mfma_f32_16x16x32_bf16 v[16:19], v[112:115], v[160:163], v[16:19]
	global_load_dwordx4 v[108:111], v[38:39], off offset:640
	global_load_dwordx4 v[112:115], v[164:165], off offset:640
	ds_read_b128 v[148:151], v166 offset:45056
	ds_read_b128 v[152:155], v166 offset:45568
	ds_read_b128 v[156:159], v166 offset:46080
	ds_read_b128 v[160:163], v166 offset:46592
	s_waitcnt lgkmcnt(4)
	s_waitcnt vmcnt(7)
	v_mfma_f32_16x16x32_bf16 v[12:15], v[116:119], v[132:135], v[12:15]
	v_mfma_f32_16x16x32_bf16 v[8:11], v[116:119], v[136:139], v[8:11]
	v_mfma_f32_16x16x32_bf16 v[4:7], v[116:119], v[140:143], v[4:7]
	v_mfma_f32_16x16x32_bf16 v[0:3], v[116:119], v[144:147], v[0:3]
	s_waitcnt vmcnt(6)
	v_mfma_f32_16x16x32_bf16 v[28:31], v[120:123], v[132:135], v[28:31]
	v_mfma_f32_16x16x32_bf16 v[24:27], v[120:123], v[136:139], v[24:27]
	v_mfma_f32_16x16x32_bf16 v[20:23], v[120:123], v[140:143], v[20:23]
	v_mfma_f32_16x16x32_bf16 v[16:19], v[120:123], v[144:147], v[16:19]
	global_load_dwordx4 v[116:119], v[38:39], off offset:704
	global_load_dwordx4 v[120:123], v[164:165], off offset:704
	ds_read_b128 v[132:135], v166 offset:49152
	ds_read_b128 v[136:139], v166 offset:49664
	ds_read_b128 v[140:143], v166 offset:50176
	ds_read_b128 v[144:147], v166 offset:50688
	s_waitcnt lgkmcnt(4)
; #define LAS __attribute__((address_space(3)))
; __device__ __forceinline__ void ssm_a_task(unsigned char* ws, LAS unsigned char* lds, int task, int tid) {
;     ...
; #pragma unroll 4
;         for (int ks = 0; ks < 16; ++ks) {
;             bf16x8 bfr[4], afr[2];
; #pragma unroll
;             for (int a = 0; a < 2; ++a) afr[a] = *(const bf16x8*)(WA + (size_t)a * 16 * 1024 + (hh * 16 + ks) * 32);
; #pragma unroll
;             for (int c = 0; c < 4; ++c) bfr[c] = *(const LAS bf16x8*)(lds + SS_UB + (((2 * ks + (kk >> 1)) * 64 + c * 16 + rr) * 32 + (kk & 1) * 16));
; #pragma unroll
;             for (int a = 0; a < 2; ++a)
; #pragma unroll
;                 for (int c = 0; c < 4; ++c) acc[a][c] = __builtin_amdgcn_mfma_f32_16x16x32_bf16(afr[a], bfr[c], acc[a][c], 0, 0, 0);
;         }
;         __syncthreads();
;     }
;     float* S = (float*)(ws + AR_S);
; #pragma unroll
;     for (int a = 0; a < 2; ++a)
; #pragma unroll
;         for (int c = 0; c < 4; ++c) { const int col = cb * 64 + c * 16 + rr; *(f32x4*)(S + ((size_t)(col * NG + g) * 256 + wid * 32 + a * 16 + 4 * kk)) = acc[a][c]; }
	s_waitcnt vmcnt(7)
	v_mfma_f32_16x16x32_bf16 v[12:15], v[124:127], v[148:151], v[12:15]
	v_mfma_f32_16x16x32_bf16 v[8:11], v[124:127], v[152:155], v[8:11]
	v_mfma_f32_16x16x32_bf16 v[4:7], v[124:127], v[156:159], v[4:7]
	v_mfma_f32_16x16x32_bf16 v[0:3], v[124:127], v[160:163], v[0:3]
	s_waitcnt vmcnt(6)
	v_mfma_f32_16x16x32_bf16 v[28:31], v[128:131], v[148:151], v[28:31]
	v_mfma_f32_16x16x32_bf16 v[24:27], v[128:131], v[152:155], v[24:27]
	v_mfma_f32_16x16x32_bf16 v[20:23], v[128:131], v[156:159], v[20:23]
	v_mfma_f32_16x16x32_bf16 v[16:19], v[128:131], v[160:163], v[16:19]
	global_load_dwordx4 v[124:127], v[38:39], off offset:768
	global_load_dwordx4 v[128:131], v[164:165], off offset:768
	ds_read_b128 v[148:151], v166 offset:53248
	ds_read_b128 v[152:155], v166 offset:53760
	ds_read_b128 v[156:159], v166 offset:54272
	ds_read_b128 v[160:163], v166 offset:54784
	s_waitcnt lgkmcnt(4)
	s_waitcnt vmcnt(7)
	v_mfma_f32_16x16x32_bf16 v[12:15], v[100:103], v[132:135], v[12:15]
	v_mfma_f32_16x16x32_bf16 v[8:11], v[100:103], v[136:139], v[8:11]
	v_mfma_f32_16x16x32_bf16 v[4:7], v[100:103], v[140:143], v[4:7]
	v_mfma_f32_16x16x32_bf16 v[0:3], v[100:103], v[144:147], v[0:3]
	s_waitcnt vmcnt(6)
	v_mfma_f32_16x16x32_bf16 v[28:31], v[104:107], v[132:135], v[28:31]
	v_mfma_f32_16x16x32_bf16 v[24:27], v[104:107], v[136:139], v[24:27]
	v_mfma_f32_16x16x32_bf16 v[20:23], v[104:107], v[140:143], v[20:23]
	v_mfma_f32_16x16x32_bf16 v[16:19], v[104:107], v[144:147], v[16:19]
	ds_read_b128 v[132:135], v166 offset:57344
	ds_read_b128 v[136:139], v166 offset:57856
	ds_read_b128 v[140:143], v166 offset:58368
	ds_read_b128 v[144:147], v166 offset:58880
	s_waitcnt lgkmcnt(4)
	s_waitcnt vmcnt(5)
	v_mfma_f32_16x16x32_bf16 v[12:15], v[108:111], v[148:151], v[12:15]
	v_mfma_f32_16x16x32_bf16 v[8:11], v[108:111], v[152:155], v[8:11]
	v_mfma_f32_16x16x32_bf16 v[4:7], v[108:111], v[156:159], v[4:7]
	v_mfma_f32_16x16x32_bf16 v[0:3], v[108:111], v[160:163], v[0:3]
	s_waitcnt vmcnt(4)
	v_mfma_f32_16x16x32_bf16 v[28:31], v[112:115], v[148:151], v[28:31]
	v_mfma_f32_16x16x32_bf16 v[24:27], v[112:115], v[152:155], v[24:27]
	v_mfma_f32_16x16x32_bf16 v[20:23], v[112:115], v[156:159], v[20:23]
	v_mfma_f32_16x16x32_bf16 v[16:19], v[112:115], v[160:163], v[16:19]
	ds_read_b128 v[148:151], v166 offset:61440
	ds_read_b128 v[152:155], v166 offset:61952
	ds_read_b128 v[156:159], v166 offset:62464
	ds_read_b128 v[160:163], v166 offset:62976
	s_waitcnt lgkmcnt(4)
	s_waitcnt vmcnt(3)
	v_mfma_f32_16x16x32_bf16 v[12:15], v[116:119], v[132:135], v[12:15]
	v_mfma_f32_16x16x32_bf16 v[8:11], v[116:119], v[136:139], v[8:11]
	v_mfma_f32_16x16x32_bf16 v[4:7], v[116:119], v[140:143], v[4:7]
	v_mfma_f32_16x16x32_bf16 v[0:3], v[116:119], v[144:147], v[0:3]
	s_waitcnt vmcnt(2)
	v_mfma_f32_16x16x32_bf16 v[28:31], v[120:123], v[132:135], v[28:31]
	v_mfma_f32_16x16x32_bf16 v[24:27], v[120:123], v[136:139], v[24:27]
	v_mfma_f32_16x16x32_bf16 v[20:23], v[120:123], v[140:143], v[20:23]
	v_mfma_f32_16x16x32_bf16 v[16:19], v[120:123], v[144:147], v[16:19]
	s_waitcnt lgkmcnt(0)
	s_waitcnt vmcnt(1)
	v_mfma_f32_16x16x32_bf16 v[12:15], v[124:127], v[148:151], v[12:15]
	v_mfma_f32_16x16x32_bf16 v[8:11], v[124:127], v[152:155], v[8:11]
	v_mfma_f32_16x16x32_bf16 v[4:7], v[124:127], v[156:159], v[4:7]
	v_mfma_f32_16x16x32_bf16 v[0:3], v[124:127], v[160:163], v[0:3]
	s_waitcnt vmcnt(0)
	v_mfma_f32_16x16x32_bf16 v[28:31], v[128:131], v[148:151], v[28:31]
	v_mfma_f32_16x16x32_bf16 v[24:27], v[128:131], v[152:155], v[24:27]
	v_mfma_f32_16x16x32_bf16 v[20:23], v[128:131], v[156:159], v[20:23]
	v_mfma_f32_16x16x32_bf16 v[16:19], v[128:131], v[160:163], v[16:19]
	s_mov_b32 s3, 0x10000
	v_lshl_or_b32 v38, s17, 11, v45
	v_add_u32_e32 v38, s16, v38
	v_ashrrev_i32_e32 v39, 31, v38
	v_lshlrev_b64 v[40:41], 10, v[38:39]
	v_lshl_add_u64 v[40:41], v[32:33], 0, v[40:41]
	s_barrier
	global_store_dwordx4 v[40:41], v[28:31], off
	s_add_i32 s54, s54, s76
	s_cmpk_gt_i32 s54, 0xff
	v_add_u32_e32 v28, 0x200, v38
	v_ashrrev_i32_e32 v29, 31, v28
	v_lshlrev_b64 v[28:29], 10, v[28:29]
	v_lshl_add_u64 v[28:29], v[32:33], 0, v[28:29]
	global_store_dwordx4 v[28:29], v[24:27], off
	s_nop 1
	v_add_u32_e32 v24, 0x400, v38
	v_ashrrev_i32_e32 v25, 31, v24
	v_lshlrev_b64 v[24:25], 10, v[24:25]
	v_lshl_add_u64 v[24:25], v[32:33], 0, v[24:25]
	global_store_dwordx4 v[24:25], v[20:23], off
	s_nop 1
	v_add_u32_e32 v20, 0x600, v38
	v_ashrrev_i32_e32 v21, 31, v20
	v_lshlrev_b64 v[20:21], 10, v[20:21]
	v_lshl_add_u64 v[20:21], v[32:33], 0, v[20:21]
	global_store_dwordx4 v[20:21], v[16:19], off
	global_store_dwordx4 v[40:41], v[12:15], off offset:64
	global_store_dwordx4 v[28:29], v[8:11], off offset:64
	global_store_dwordx4 v[24:25], v[4:7], off offset:64
	global_store_dwordx4 v[20:21], v[0:3], off offset:64
	s_cbranch_scc0 .LBB0_603

; #define LAS __attribute__((address_space(3)))
; template <int PMODE> __device__ __forceinline__ void ssm_c_task(unsigned char* ws, LAS unsigned char* lds, int l, int task, int tid_in) {
;     ...
;     { const u32x4* src = (const u32x4*)((const bf16*)(ws + WS_KT) + (size_t)g * 127 * 256);
; #pragma unroll
;       for (int r = 0; r < 8; ++r) { const int c = r * 512 + tid; if (c < 127 * 32) *(LAS u32x4*)(lds + SS_KT + c * 16) = src[c]; } }
.LBB0_816:
	s_ashr_i32 s56, s54, 3
	s_mul_i32 s6, s56, 0xfe00
	v_readlane_b32 s14, v251, 34
	s_mul_hi_i32 s3, s56, 0xfe00
	v_readlane_b32 s15, v251, 35
	s_add_u32 s50, s14, s6
	s_addc_u32 s51, s15, s3
	s_mov_b64 s[58:59], exec
	s_and_b64 exec, s[58:59], vcc
	v_lshl_add_u64 v[0:1], v[136:137], 4, s[50:51]
	global_load_dwordx4 v[4:7], v[0:1], off
	s_and_b64 exec, s[58:59], s[34:35]
	v_lshl_add_u64 v[0:1], v[138:139], 4, s[50:51]
	global_load_dwordx4 v[8:11], v[0:1], off
	s_and_b64 exec, s[58:59], s[36:37]
	v_lshl_add_u64 v[0:1], v[140:141], 4, s[50:51]
	global_load_dwordx4 v[12:15], v[0:1], off
	s_and_b64 exec, s[58:59], s[38:39]
	v_lshl_add_u64 v[0:1], v[142:143], 4, s[50:51]
	global_load_dwordx4 v[16:19], v[0:1], off
	s_and_b64 exec, s[58:59], s[40:41]
	v_lshl_add_u64 v[0:1], v[144:145], 4, s[50:51]
	global_load_dwordx4 v[20:23], v[0:1], off
	s_and_b64 exec, s[58:59], s[42:43]
	v_lshl_add_u64 v[0:1], v[146:147], 4, s[50:51]
	global_load_dwordx4 v[24:27], v[0:1], off
	s_and_b64 exec, s[58:59], s[44:45]
	v_lshl_add_u64 v[0:1], v[148:149], 4, s[50:51]
	global_load_dwordx4 v[28:31], v[0:1], off
	s_and_b64 exec, s[58:59], s[46:47]
	v_lshl_add_u64 v[0:1], v[150:151], 4, s[50:51]
	global_load_dwordx4 v[32:35], v[0:1], off
	s_waitcnt vmcnt(0)
	s_and_b64 exec, s[58:59], vcc
	ds_write_b128 v223, v[4:7]
	s_and_b64 exec, s[58:59], s[34:35]
	ds_write_b128 v224, v[8:11]
	s_and_b64 exec, s[58:59], s[36:37]
	ds_write_b128 v225, v[12:15]
	s_and_b64 exec, s[58:59], s[38:39]
	ds_write_b128 v226, v[16:19]
	s_and_b64 exec, s[58:59], s[40:41]
	ds_write_b128 v227, v[20:23]
	s_and_b64 exec, s[58:59], s[42:43]
	ds_write_b128 v228, v[24:27]
	s_and_b64 exec, s[58:59], s[44:45]
	ds_write_b128 v229, v[28:31]
	s_and_b64 exec, s[58:59], s[46:47]
	ds_write_b128 v230, v[32:35]

; #define LAS __attribute__((address_space(3)))
; template <int PMODE> __device__ __forceinline__ void ssm_c_task(unsigned char* ws, LAS unsigned char* lds, int l, int task, int tid_in) {
;     ...
; #pragma unroll 2
;         for (int ks = 0; ks < (PMODE == 3 ? 0 : 16); ++ks) {
;             bf16x8 bfr[4];
; #pragma unroll
;             for (int c = 0; c < 4; ++c) bfr[c] = *(const LAS bf16x8*)(lds + SS_UB + (((2 * ks + (kk >> 1)) * 64 + c * 16 + rr) * 32 + (kk & 1) * 16));
;             const int j = hh * 32 + 2 * ks + (kk >> 1);
; #pragma unroll
;             for (int a = 0; a < 8; ++a) { const int i = wid * 8 + a;
;                 const bf16x8 af = *(const LAS bf16x8*)(lds + SS_KT + (i - j + 63) * 512 + rr * 32 + (kk & 1) * 16);
; #pragma unroll
;                 for (int c = 0; c < 4; ++c) acc[a][c] = __builtin_amdgcn_mfma_f32_16x16x32_bf16(af, bfr[c], acc[a][c], 0, 0, 0); }
;         }
.LBB0_835:
	v_add_u32_e32 v171, v170, v217
	v_add_u32_e32 v184, v169, v217
	v_add_u32_e32 v44, 0x10000, v171
	ds_read_b128 v[210:213], v184 offset:4096
	ds_read_b128 v[172:175], v44
	v_add_u32_e32 v44, 0x10200, v171
	ds_read_b128 v[176:179], v44
	v_add_u32_e32 v44, 0x10400, v171
	ds_read_b128 v[180:183], v44
	v_add_u32_e32 v44, 0x10600, v171
	ds_read_b128 v[186:189], v44
	ds_read_b128 v[44:47], v184 offset:1024
	ds_read_b128 v[132:135], v184 offset:1536
	ds_read_b128 v[194:197], v184 offset:2048
	ds_read_b128 v[198:201], v184 offset:2560
	ds_read_b128 v[202:205], v184 offset:3072
	ds_read_b128 v[206:209], v184 offset:3584
	s_waitcnt lgkmcnt(9)
	v_mfma_f32_16x16x32_bf16 v[28:31], v[210:213], v[172:175], v[28:31]
	s_add_i32 s3, s3, -2
	v_add_u32_e32 v170, 0x2000, v170
	v_add_u32_e32 v169, 0xfffff800, v169
	s_waitcnt lgkmcnt(8)
	v_mfma_f32_16x16x32_bf16 v[24:27], v[210:213], v[176:179], v[24:27]
	s_cmp_lg_u32 s3, 0
	s_waitcnt lgkmcnt(7)
	v_mfma_f32_16x16x32_bf16 v[20:23], v[210:213], v[180:183], v[20:23]
	s_waitcnt lgkmcnt(6)
	v_mfma_f32_16x16x32_bf16 v[16:19], v[210:213], v[186:189], v[16:19]
	ds_read_b128 v[210:213], v184 offset:4608
	s_waitcnt lgkmcnt(6)
	v_mfma_f32_16x16x32_bf16 v[128:131], v[44:47], v[172:175], v[128:131]
	v_mfma_f32_16x16x32_bf16 v[124:127], v[44:47], v[176:179], v[124:127]
	v_mfma_f32_16x16x32_bf16 v[120:123], v[44:47], v[180:183], v[120:123]
	s_waitcnt lgkmcnt(5)
	v_mfma_f32_16x16x32_bf16 v[112:115], v[132:135], v[172:175], v[112:115]
	v_mfma_f32_16x16x32_bf16 v[108:111], v[132:135], v[176:179], v[108:111]
	v_mfma_f32_16x16x32_bf16 v[104:107], v[132:135], v[180:183], v[104:107]
	s_waitcnt lgkmcnt(4)
	v_mfma_f32_16x16x32_bf16 v[96:99], v[194:197], v[172:175], v[96:99]
	v_mfma_f32_16x16x32_bf16 v[92:95], v[194:197], v[176:179], v[92:95]
	v_mfma_f32_16x16x32_bf16 v[88:91], v[194:197], v[180:183], v[88:91]
	s_waitcnt lgkmcnt(3)
	v_mfma_f32_16x16x32_bf16 v[80:83], v[198:201], v[172:175], v[80:83]
	v_mfma_f32_16x16x32_bf16 v[76:79], v[198:201], v[176:179], v[76:79]
	v_mfma_f32_16x16x32_bf16 v[72:75], v[198:201], v[180:183], v[72:75]
	s_waitcnt lgkmcnt(2)
	v_mfma_f32_16x16x32_bf16 v[64:67], v[202:205], v[172:175], v[64:67]
	v_mfma_f32_16x16x32_bf16 v[60:63], v[202:205], v[176:179], v[60:63]
	v_mfma_f32_16x16x32_bf16 v[56:59], v[202:205], v[180:183], v[56:59]
	s_waitcnt lgkmcnt(1)
	v_mfma_f32_16x16x32_bf16 v[48:51], v[206:209], v[172:175], v[48:51]
	v_mfma_f32_16x16x32_bf16 v[40:43], v[206:209], v[176:179], v[40:43]
	v_mfma_f32_16x16x32_bf16 v[36:39], v[206:209], v[180:183], v[36:39]
	s_waitcnt lgkmcnt(0)
	v_mfma_f32_16x16x32_bf16 v[12:15], v[210:213], v[172:175], v[12:15]
	v_add_u32_e32 v172, 0x11000, v171
	ds_read_b128 v[172:175], v172
	v_mfma_f32_16x16x32_bf16 v[8:11], v[210:213], v[176:179], v[8:11]
	v_add_u32_e32 v176, 0x11200, v171
	ds_read_b128 v[176:179], v176
	v_mfma_f32_16x16x32_bf16 v[4:7], v[210:213], v[180:183], v[4:7]
	v_add_u32_e32 v180, 0x11400, v171
	v_add_u32_e32 v171, 0x11600, v171
	ds_read_b128 v[180:183], v180
	v_mfma_f32_16x16x32_bf16 v[116:119], v[44:47], v[186:189], v[116:119]
	v_mfma_f32_16x16x32_bf16 v[100:103], v[132:135], v[186:189], v[100:103]
	v_mfma_f32_16x16x32_bf16 v[84:87], v[194:197], v[186:189], v[84:87]
	v_mfma_f32_16x16x32_bf16 v[68:71], v[198:201], v[186:189], v[68:71]
	v_mfma_f32_16x16x32_bf16 v[52:55], v[202:205], v[186:189], v[52:55]
	v_mfma_f32_16x16x32_bf16 v[32:35], v[206:209], v[186:189], v[32:35]
	v_mfma_f32_16x16x32_bf16 v[0:3], v[210:213], v[186:189], v[0:3]
	ds_read_b128 v[186:189], v171
	ds_read_b128 v[210:213], v184
	s_waitcnt lgkmcnt(0)
	v_mfma_f32_16x16x32_bf16 v[128:131], v[210:213], v[172:175], v[128:131]
	v_mfma_f32_16x16x32_bf16 v[124:127], v[210:213], v[176:179], v[124:127]
	v_mfma_f32_16x16x32_bf16 v[120:123], v[210:213], v[180:183], v[120:123]
	v_mfma_f32_16x16x32_bf16 v[116:119], v[210:213], v[186:189], v[116:119]
	ds_read_b128 v[210:213], v184 offset:512
	s_waitcnt lgkmcnt(0)
	v_mfma_f32_16x16x32_bf16 v[112:115], v[210:213], v[172:175], v[112:115]
	v_mfma_f32_16x16x32_bf16 v[108:111], v[210:213], v[176:179], v[108:111]
	v_mfma_f32_16x16x32_bf16 v[104:107], v[210:213], v[180:183], v[104:107]
	v_mfma_f32_16x16x32_bf16 v[100:103], v[210:213], v[186:189], v[100:103]
	v_mfma_f32_16x16x32_bf16 v[96:99], v[44:47], v[172:175], v[96:99]
	v_mfma_f32_16x16x32_bf16 v[92:95], v[44:47], v[176:179], v[92:95]
	v_mfma_f32_16x16x32_bf16 v[88:91], v[44:47], v[180:183], v[88:91]
	v_mfma_f32_16x16x32_bf16 v[84:87], v[44:47], v[186:189], v[84:87]
	v_mfma_f32_16x16x32_bf16 v[80:83], v[132:135], v[172:175], v[80:83]
	v_mfma_f32_16x16x32_bf16 v[76:79], v[132:135], v[176:179], v[76:79]
	v_mfma_f32_16x16x32_bf16 v[72:75], v[132:135], v[180:183], v[72:75]
	v_mfma_f32_16x16x32_bf16 v[68:71], v[132:135], v[186:189], v[68:71]
	v_mfma_f32_16x16x32_bf16 v[64:67], v[194:197], v[172:175], v[64:67]
	v_mfma_f32_16x16x32_bf16 v[60:63], v[194:197], v[176:179], v[60:63]
	v_mfma_f32_16x16x32_bf16 v[56:59], v[194:197], v[180:183], v[56:59]
	v_mfma_f32_16x16x32_bf16 v[52:55], v[194:197], v[186:189], v[52:55]
	v_mfma_f32_16x16x32_bf16 v[48:51], v[198:201], v[172:175], v[48:51]
	v_mfma_f32_16x16x32_bf16 v[40:43], v[198:201], v[176:179], v[40:43]
	v_mfma_f32_16x16x32_bf16 v[36:39], v[198:201], v[180:183], v[36:39]
	v_mfma_f32_16x16x32_bf16 v[32:35], v[198:201], v[186:189], v[32:35]
	v_mfma_f32_16x16x32_bf16 v[28:31], v[202:205], v[172:175], v[28:31]
	v_mfma_f32_16x16x32_bf16 v[24:27], v[202:205], v[176:179], v[24:27]
	v_mfma_f32_16x16x32_bf16 v[20:23], v[202:205], v[180:183], v[20:23]
	v_mfma_f32_16x16x32_bf16 v[16:19], v[202:205], v[186:189], v[16:19]
	v_mfma_f32_16x16x32_bf16 v[12:15], v[206:209], v[172:175], v[12:15]
	v_mfma_f32_16x16x32_bf16 v[8:11], v[206:209], v[176:179], v[8:11]
	v_mfma_f32_16x16x32_bf16 v[4:7], v[206:209], v[180:183], v[4:7]
	v_mfma_f32_16x16x32_bf16 v[0:3], v[206:209], v[186:189], v[0:3]
	s_cbranch_scc1 .LBB0_835
; #define LAS __attribute__((address_space(3)))
; template <int PMODE> __device__ __forceinline__ void ssm_c_task(unsigned char* ws, LAS unsigned char* lds, int l, int task, int tid_in) {
;     ...
;     { const bf16* Hb = (const bf16*)(ws + AR_H); int tid = tid_in; asm volatile("" : "+v"(tid));
;       u32x4 v[4];
; #pragma unroll
;       for (int r = 0; r < 4; ++r) { const int c = r * 512 + tid, col = c & 63, kc = c >> 6; v[r] = *(const u32x4*)(Hb + ((size_t)((cb * 64 + col) * NG + g) * 256 + kc * 8)); }
; #pragma unroll
;       for (int r = 0; r < 4; ++r) { const int c = r * 512 + tid; *(LAS u32x4*)(lds + SS_UB + c * 16) = v[r]; } }
;     __syncthreads();
;     { const bf16* WC = (const bf16*)(ws + WS_WC) + ((size_t)(g * 1024 + wid * 128 + rr) * 256 + 8 * kk);
; #pragma unroll 1
;       for (int ks = 0; ks < 8; ++ks) {
;           bf16x8 bfr[4], afr[8];
; #pragma unroll
;           for (int a = 0; a < 8; ++a) afr[a] = *(const bf16x8*)(WC + (size_t)a * 16 * 256 + ks * 32);
; #pragma unroll
;           for (int c = 0; c < 4; ++c) bfr[c] = *(const LAS bf16x8*)(lds + SS_UB + (((ks * 4 + kk) * 64 + c * 16 + rr) * 16));
; #pragma unroll
;           for (int a = 0; a < 8; ++a)
; #pragma unroll
;               for (int c = 0; c < 4; ++c) acc[a][c] = __builtin_amdgcn_mfma_f32_16x16x32_bf16(afr[a], bfr[c], acc[a][c], 0, 0, 0);
;       } }
	v_mov_b32_e32 v169, v136
	s_barrier
	s_lshl_b32 s3, s16, 11
	v_lshlrev_b32_e32 v44, 5, v169
	v_and_b32_e32 v44, 0x7e0, v44
	s_add_i32 s3, s3, s56
	v_add_u32_e32 v44, s3, v44
	v_ashrrev_i32_e32 v45, 31, v44
	v_lshlrev_b64 v[44:45], 9, v[44:45]
	v_lshl_add_u64 v[174:175], s[22:23], 0, v[44:45]
	v_ashrrev_i32_e32 v44, 3, v169
	v_add_u32_e32 v132, 0x200, v169
	v_and_b32_e32 v44, -8, v44
	v_ashrrev_i32_e32 v132, 3, v132
	v_add_u32_e32 v170, 0x400, v169
	v_ashrrev_i32_e32 v45, 31, v44
	v_and_b32_e32 v132, -8, v132
	v_ashrrev_i32_e32 v170, 3, v170
	v_add_u32_e32 v176, 0x600, v169
	v_lshl_add_u64 v[44:45], v[44:45], 1, v[174:175]
	v_ashrrev_i32_e32 v133, 31, v132
	v_and_b32_e32 v170, -8, v170
	v_ashrrev_i32_e32 v176, 3, v176
	global_load_dwordx4 v[44:47], v[44:45], off
	v_lshl_add_u64 v[132:133], v[132:133], 1, v[174:175]
	v_ashrrev_i32_e32 v171, 31, v170
	v_and_b32_e32 v176, -8, v176
	global_load_dwordx4 v[132:135], v[132:133], off
	v_lshl_add_u64 v[170:171], v[170:171], 1, v[174:175]
	v_ashrrev_i32_e32 v177, 31, v176
	global_load_dwordx4 v[170:173], v[170:171], off
	v_lshl_add_u64 v[174:175], v[176:177], 1, v[174:175]
	global_load_dwordx4 v[174:177], v[174:175], off
	v_lshl_add_u32 v169, v169, 4, 0
	v_add_u32_e32 v169, 0x10000, v169
	s_mov_b64 s[62:63], 0
	s_waitcnt vmcnt(3)
	ds_write_b128 v169, v[44:47]
	s_waitcnt vmcnt(2)
	ds_write_b128 v169, v[132:135] offset:8192
	s_waitcnt vmcnt(1)
	ds_write_b128 v169, v[170:173] offset:16384
	s_waitcnt vmcnt(0)
	ds_write_b128 v169, v[174:177] offset:24576
	v_lshl_add_u32 v44, s56, 10, v218
	v_ashrrev_i32_e32 v45, 31, v44
	v_lshlrev_b64 v[44:45], 9, v[44:45]
	v_lshl_add_u64 v[132:133], v[166:167], 0, v[44:45]
	v_mov_b32_e32 v169, v222
	s_mov_b32 s62, 0xd400000
	s_mov_b32 s63, 0
	s_mov_b32 s50, 0x2000
	s_mov_b32 s51, 0
	v_lshl_add_u64 v[134:135], v[132:133], 0, s[62:63]
	s_mov_b32 s62, 0xffff2040
	s_mov_b32 s63, -1
	global_load_dwordx4 v[170:173], v[134:135], off
	v_lshl_add_u64 v[134:135], v[134:135], 0, s[50:51]
	global_load_dwordx4 v[192:195], v[134:135], off
	v_lshl_add_u64 v[134:135], v[134:135], 0, s[50:51]
	global_load_dwordx4 v[196:199], v[134:135], off
	v_lshl_add_u64 v[134:135], v[134:135], 0, s[50:51]
	global_load_dwordx4 v[200:203], v[134:135], off
	v_lshl_add_u64 v[134:135], v[134:135], 0, s[50:51]
	global_load_dwordx4 v[204:207], v[134:135], off
	v_lshl_add_u64 v[134:135], v[134:135], 0, s[50:51]
	global_load_dwordx4 v[208:211], v[134:135], off
	v_lshl_add_u64 v[134:135], v[134:135], 0, s[50:51]
	global_load_dwordx4 v[212:215], v[134:135], off
	v_lshl_add_u64 v[134:135], v[134:135], 0, s[50:51]
	s_waitcnt lgkmcnt(0)
	s_barrier
.LBB0_837:
	ds_read_b128 v[44:47], v169 offset:0
	ds_read_b128 v[174:177], v169 offset:256
	ds_read_b128 v[178:181], v169 offset:512
	ds_read_b128 v[186:189], v169 offset:768
	s_waitcnt lgkmcnt(0)
	s_waitcnt vmcnt(6)
	v_mfma_f32_16x16x32_bf16 v[128:131], v[170:173], v[44:47], v[128:131]
	v_mfma_f32_16x16x32_bf16 v[124:127], v[170:173], v[174:177], v[124:127]
	v_mfma_f32_16x16x32_bf16 v[120:123], v[170:173], v[178:181], v[120:123]
	v_mfma_f32_16x16x32_bf16 v[116:119], v[170:173], v[186:189], v[116:119]
	global_load_dwordx4 v[170:173], v[134:135], off
	v_lshl_add_u64 v[134:135], v[134:135], 0, s[62:63]
	ds_read_b128 v[232:235], v169 offset:4096
	ds_read_b128 v[236:239], v169 offset:4352
	ds_read_b128 v[240:243], v169 offset:4608
	ds_read_b128 v[244:247], v169 offset:4864
	s_waitcnt vmcnt(6)
	v_mfma_f32_16x16x32_bf16 v[112:115], v[192:195], v[44:47], v[112:115]
	v_mfma_f32_16x16x32_bf16 v[108:111], v[192:195], v[174:177], v[108:111]
	v_mfma_f32_16x16x32_bf16 v[104:107], v[192:195], v[178:181], v[104:107]
	v_mfma_f32_16x16x32_bf16 v[100:103], v[192:195], v[186:189], v[100:103]
	global_load_dwordx4 v[192:195], v[134:135], off
	v_lshl_add_u64 v[134:135], v[134:135], 0, s[50:51]
	s_waitcnt vmcnt(6)
	v_mfma_f32_16x16x32_bf16 v[96:99], v[196:199], v[44:47], v[96:99]
	v_mfma_f32_16x16x32_bf16 v[92:95], v[196:199], v[174:177], v[92:95]
	v_mfma_f32_16x16x32_bf16 v[88:91], v[196:199], v[178:181], v[88:91]
	v_mfma_f32_16x16x32_bf16 v[84:87], v[196:199], v[186:189], v[84:87]
	global_load_dwordx4 v[196:199], v[134:135], off
	v_lshl_add_u64 v[134:135], v[134:135], 0, s[50:51]
	s_waitcnt vmcnt(6)
	v_mfma_f32_16x16x32_bf16 v[80:83], v[200:203], v[44:47], v[80:83]
	v_mfma_f32_16x16x32_bf16 v[76:79], v[200:203], v[174:177], v[76:79]
	v_mfma_f32_16x16x32_bf16 v[72:75], v[200:203], v[178:181], v[72:75]
	v_mfma_f32_16x16x32_bf16 v[68:71], v[200:203], v[186:189], v[68:71]
	global_load_dwordx4 v[200:203], v[134:135], off
	v_lshl_add_u64 v[134:135], v[134:135], 0, s[50:51]
	s_waitcnt vmcnt(6)
	v_mfma_f32_16x16x32_bf16 v[64:67], v[204:207], v[44:47], v[64:67]
	v_mfma_f32_16x16x32_bf16 v[60:63], v[204:207], v[174:177], v[60:63]
	v_mfma_f32_16x16x32_bf16 v[56:59], v[204:207], v[178:181], v[56:59]
	v_mfma_f32_16x16x32_bf16 v[52:55], v[204:207], v[186:189], v[52:55]
	global_load_dwordx4 v[204:207], v[134:135], off
	v_lshl_add_u64 v[134:135], v[134:135], 0, s[50:51]
	s_waitcnt vmcnt(6)
	v_mfma_f32_16x16x32_bf16 v[48:51], v[208:211], v[44:47], v[48:51]
	v_mfma_f32_16x16x32_bf16 v[40:43], v[208:211], v[174:177], v[40:43]
	v_mfma_f32_16x16x32_bf16 v[36:39], v[208:211], v[178:181], v[36:39]
	v_mfma_f32_16x16x32_bf16 v[32:35], v[208:211], v[186:189], v[32:35]
	global_load_dwordx4 v[208:211], v[134:135], off
	v_lshl_add_u64 v[134:135], v[134:135], 0, s[50:51]
	s_waitcnt vmcnt(6)
	v_mfma_f32_16x16x32_bf16 v[28:31], v[212:215], v[44:47], v[28:31]
	v_mfma_f32_16x16x32_bf16 v[24:27], v[212:215], v[174:177], v[24:27]
	v_mfma_f32_16x16x32_bf16 v[20:23], v[212:215], v[178:181], v[20:23]
	v_mfma_f32_16x16x32_bf16 v[16:19], v[212:215], v[186:189], v[16:19]
	global_load_dwordx4 v[212:215], v[134:135], off
	v_lshl_add_u64 v[134:135], v[134:135], 0, s[50:51]
	s_waitcnt vmcnt(6)
; #define LAS __attribute__((address_space(3)))
; template <int PMODE> __device__ __forceinline__ void ssm_c_task(unsigned char* ws, LAS unsigned char* lds, int l, int task, int tid_in) {
;     ...
;     { const bf16* WC = (const bf16*)(ws + WS_WC) + ((size_t)(g * 1024 + wid * 128 + rr) * 256 + 8 * kk);
; #pragma unroll 1
;       for (int ks = 0; ks < 8; ++ks) {
;           bf16x8 bfr[4], afr[8];
; #pragma unroll
;           for (int a = 0; a < 8; ++a) afr[a] = *(const bf16x8*)(WC + (size_t)a * 16 * 256 + ks * 32);
; #pragma unroll
;           for (int c = 0; c < 4; ++c) bfr[c] = *(const LAS bf16x8*)(lds + SS_UB + (((ks * 4 + kk) * 64 + c * 16 + rr) * 16));
; #pragma unroll
;           for (int a = 0; a < 8; ++a)
; #pragma unroll
;               for (int c = 0; c < 4; ++c) acc[a][c] = __builtin_amdgcn_mfma_f32_16x16x32_bf16(afr[a], bfr[c], acc[a][c], 0, 0, 0);
;       } }
	v_mfma_f32_16x16x32_bf16 v[12:15], v[170:173], v[44:47], v[12:15]
	v_mfma_f32_16x16x32_bf16 v[8:11], v[170:173], v[174:177], v[8:11]
	v_mfma_f32_16x16x32_bf16 v[4:7], v[170:173], v[178:181], v[4:7]
	v_mfma_f32_16x16x32_bf16 v[0:3], v[170:173], v[186:189], v[0:3]
	global_load_dwordx4 v[170:173], v[134:135], off
	v_lshl_add_u64 v[134:135], v[134:135], 0, s[50:51]
	s_waitcnt lgkmcnt(0)
	s_waitcnt vmcnt(6)
	v_mfma_f32_16x16x32_bf16 v[128:131], v[192:195], v[232:235], v[128:131]
	v_mfma_f32_16x16x32_bf16 v[124:127], v[192:195], v[236:239], v[124:127]
	v_mfma_f32_16x16x32_bf16 v[120:123], v[192:195], v[240:243], v[120:123]
	v_mfma_f32_16x16x32_bf16 v[116:119], v[192:195], v[244:247], v[116:119]
	global_load_dwordx4 v[192:195], v[134:135], off
	v_lshl_add_u64 v[134:135], v[134:135], 0, s[62:63]
	ds_read_b128 v[44:47], v169 offset:8192
	ds_read_b128 v[174:177], v169 offset:8448
	ds_read_b128 v[178:181], v169 offset:8704
	ds_read_b128 v[186:189], v169 offset:8960
	s_waitcnt vmcnt(6)
	v_mfma_f32_16x16x32_bf16 v[112:115], v[196:199], v[232:235], v[112:115]
	v_mfma_f32_16x16x32_bf16 v[108:111], v[196:199], v[236:239], v[108:111]
	v_mfma_f32_16x16x32_bf16 v[104:107], v[196:199], v[240:243], v[104:107]
	v_mfma_f32_16x16x32_bf16 v[100:103], v[196:199], v[244:247], v[100:103]
	global_load_dwordx4 v[196:199], v[134:135], off
	v_lshl_add_u64 v[134:135], v[134:135], 0, s[50:51]
	s_waitcnt vmcnt(6)
	v_mfma_f32_16x16x32_bf16 v[96:99], v[200:203], v[232:235], v[96:99]
	v_mfma_f32_16x16x32_bf16 v[92:95], v[200:203], v[236:239], v[92:95]
	v_mfma_f32_16x16x32_bf16 v[88:91], v[200:203], v[240:243], v[88:91]
	v_mfma_f32_16x16x32_bf16 v[84:87], v[200:203], v[244:247], v[84:87]
	global_load_dwordx4 v[200:203], v[134:135], off
	v_lshl_add_u64 v[134:135], v[134:135], 0, s[50:51]
	s_waitcnt vmcnt(6)
	v_mfma_f32_16x16x32_bf16 v[80:83], v[204:207], v[232:235], v[80:83]
	v_mfma_f32_16x16x32_bf16 v[76:79], v[204:207], v[236:239], v[76:79]
	v_mfma_f32_16x16x32_bf16 v[72:75], v[204:207], v[240:243], v[72:75]
	v_mfma_f32_16x16x32_bf16 v[68:71], v[204:207], v[244:247], v[68:71]
	global_load_dwordx4 v[204:207], v[134:135], off
	v_lshl_add_u64 v[134:135], v[134:135], 0, s[50:51]
	s_waitcnt vmcnt(6)
	v_mfma_f32_16x16x32_bf16 v[64:67], v[208:211], v[232:235], v[64:67]
	v_mfma_f32_16x16x32_bf16 v[60:63], v[208:211], v[236:239], v[60:63]
	v_mfma_f32_16x16x32_bf16 v[56:59], v[208:211], v[240:243], v[56:59]
	v_mfma_f32_16x16x32_bf16 v[52:55], v[208:211], v[244:247], v[52:55]
	global_load_dwordx4 v[208:211], v[134:135], off
	v_lshl_add_u64 v[134:135], v[134:135], 0, s[50:51]
	s_waitcnt vmcnt(6)
	v_mfma_f32_16x16x32_bf16 v[48:51], v[212:215], v[232:235], v[48:51]
	v_mfma_f32_16x16x32_bf16 v[40:43], v[212:215], v[236:239], v[40:43]
	v_mfma_f32_16x16x32_bf16 v[36:39], v[212:215], v[240:243], v[36:39]
	v_mfma_f32_16x16x32_bf16 v[32:35], v[212:215], v[244:247], v[32:35]
	global_load_dwordx4 v[212:215], v[134:135], off
	v_lshl_add_u64 v[134:135], v[134:135], 0, s[50:51]
	s_waitcnt vmcnt(6)
	v_mfma_f32_16x16x32_bf16 v[28:31], v[170:173], v[232:235], v[28:31]
	v_mfma_f32_16x16x32_bf16 v[24:27], v[170:173], v[236:239], v[24:27]
	v_mfma_f32_16x16x32_bf16 v[20:23], v[170:173], v[240:243], v[20:23]
	v_mfma_f32_16x16x32_bf16 v[16:19], v[170:173], v[244:247], v[16:19]
	global_load_dwordx4 v[170:173], v[134:135], off
	v_lshl_add_u64 v[134:135], v[134:135], 0, s[50:51]
	s_waitcnt vmcnt(6)
	v_mfma_f32_16x16x32_bf16 v[12:15], v[192:195], v[232:235], v[12:15]
	v_mfma_f32_16x16x32_bf16 v[8:11], v[192:195], v[236:239], v[8:11]
	v_mfma_f32_16x16x32_bf16 v[4:7], v[192:195], v[240:243], v[4:7]
	v_mfma_f32_16x16x32_bf16 v[0:3], v[192:195], v[244:247], v[0:3]
	global_load_dwordx4 v[192:195], v[134:135], off
	v_lshl_add_u64 v[134:135], v[134:135], 0, s[50:51]
	s_waitcnt lgkmcnt(0)
	s_waitcnt vmcnt(6)
	v_mfma_f32_16x16x32_bf16 v[128:131], v[196:199], v[44:47], v[128:131]
	v_mfma_f32_16x16x32_bf16 v[124:127], v[196:199], v[174:177], v[124:127]
	v_mfma_f32_16x16x32_bf16 v[120:123], v[196:199], v[178:181], v[120:123]
	v_mfma_f32_16x16x32_bf16 v[116:119], v[196:199], v[186:189], v[116:119]
	global_load_dwordx4 v[196:199], v[134:135], off
	v_lshl_add_u64 v[134:135], v[134:135], 0, s[62:63]
	ds_read_b128 v[232:235], v169 offset:12288
	ds_read_b128 v[236:239], v169 offset:12544
	ds_read_b128 v[240:243], v169 offset:12800
	ds_read_b128 v[244:247], v169 offset:13056
	s_waitcnt vmcnt(6)
	v_mfma_f32_16x16x32_bf16 v[112:115], v[200:203], v[44:47], v[112:115]
	v_mfma_f32_16x16x32_bf16 v[108:111], v[200:203], v[174:177], v[108:111]
	v_mfma_f32_16x16x32_bf16 v[104:107], v[200:203], v[178:181], v[104:107]
	v_mfma_f32_16x16x32_bf16 v[100:103], v[200:203], v[186:189], v[100:103]
	global_load_dwordx4 v[200:203], v[134:135], off
	v_lshl_add_u64 v[134:135], v[134:135], 0, s[50:51]
	s_waitcnt vmcnt(6)
	v_mfma_f32_16x16x32_bf16 v[96:99], v[204:207], v[44:47], v[96:99]
	v_mfma_f32_16x16x32_bf16 v[92:95], v[204:207], v[174:177], v[92:95]
	v_mfma_f32_16x16x32_bf16 v[88:91], v[204:207], v[178:181], v[88:91]
	v_mfma_f32_16x16x32_bf16 v[84:87], v[204:207], v[186:189], v[84:87]
	global_load_dwordx4 v[204:207], v[134:135], off
	v_lshl_add_u64 v[134:135], v[134:135], 0, s[50:51]
	s_waitcnt vmcnt(6)
	v_mfma_f32_16x16x32_bf16 v[80:83], v[208:211], v[44:47], v[80:83]
	v_mfma_f32_16x16x32_bf16 v[76:79], v[208:211], v[174:177], v[76:79]
	v_mfma_f32_16x16x32_bf16 v[72:75], v[208:211], v[178:181], v[72:75]
	v_mfma_f32_16x16x32_bf16 v[68:71], v[208:211], v[186:189], v[68:71]
	global_load_dwordx4 v[208:211], v[134:135], off
	v_lshl_add_u64 v[134:135], v[134:135], 0, s[50:51]
	s_waitcnt vmcnt(6)
; #define LAS __attribute__((address_space(3)))
; template <int PMODE> __device__ __forceinline__ void ssm_c_task(unsigned char* ws, LAS unsigned char* lds, int l, int task, int tid_in) {
;     ...
;     { const bf16* WC = (const bf16*)(ws + WS_WC) + ((size_t)(g * 1024 + wid * 128 + rr) * 256 + 8 * kk);
; #pragma unroll 1
;       for (int ks = 0; ks < 8; ++ks) {
;           bf16x8 bfr[4], afr[8];
; #pragma unroll
;           for (int a = 0; a < 8; ++a) afr[a] = *(const bf16x8*)(WC + (size_t)a * 16 * 256 + ks * 32);
; #pragma unroll
;           for (int c = 0; c < 4; ++c) bfr[c] = *(const LAS bf16x8*)(lds + SS_UB + (((ks * 4 + kk) * 64 + c * 16 + rr) * 16));
; #pragma unroll
;           for (int a = 0; a < 8; ++a)
; #pragma unroll
;               for (int c = 0; c < 4; ++c) acc[a][c] = __builtin_amdgcn_mfma_f32_16x16x32_bf16(afr[a], bfr[c], acc[a][c], 0, 0, 0);
;       } }
	v_mfma_f32_16x16x32_bf16 v[64:67], v[212:215], v[44:47], v[64:67]
	v_mfma_f32_16x16x32_bf16 v[60:63], v[212:215], v[174:177], v[60:63]
	v_mfma_f32_16x16x32_bf16 v[56:59], v[212:215], v[178:181], v[56:59]
	v_mfma_f32_16x16x32_bf16 v[52:55], v[212:215], v[186:189], v[52:55]
	global_load_dwordx4 v[212:215], v[134:135], off
	v_lshl_add_u64 v[134:135], v[134:135], 0, s[50:51]
	s_waitcnt vmcnt(6)
	v_mfma_f32_16x16x32_bf16 v[48:51], v[170:173], v[44:47], v[48:51]
	v_mfma_f32_16x16x32_bf16 v[40:43], v[170:173], v[174:177], v[40:43]
	v_mfma_f32_16x16x32_bf16 v[36:39], v[170:173], v[178:181], v[36:39]
	v_mfma_f32_16x16x32_bf16 v[32:35], v[170:173], v[186:189], v[32:35]
	global_load_dwordx4 v[170:173], v[134:135], off
	v_lshl_add_u64 v[134:135], v[134:135], 0, s[50:51]
	s_waitcnt vmcnt(6)
	v_mfma_f32_16x16x32_bf16 v[28:31], v[192:195], v[44:47], v[28:31]
	v_mfma_f32_16x16x32_bf16 v[24:27], v[192:195], v[174:177], v[24:27]
	v_mfma_f32_16x16x32_bf16 v[20:23], v[192:195], v[178:181], v[20:23]
	v_mfma_f32_16x16x32_bf16 v[16:19], v[192:195], v[186:189], v[16:19]
	global_load_dwordx4 v[192:195], v[134:135], off
	v_lshl_add_u64 v[134:135], v[134:135], 0, s[50:51]
	s_waitcnt vmcnt(6)
	v_mfma_f32_16x16x32_bf16 v[12:15], v[196:199], v[44:47], v[12:15]
	v_mfma_f32_16x16x32_bf16 v[8:11], v[196:199], v[174:177], v[8:11]
	v_mfma_f32_16x16x32_bf16 v[4:7], v[196:199], v[178:181], v[4:7]
	v_mfma_f32_16x16x32_bf16 v[0:3], v[196:199], v[186:189], v[0:3]
	global_load_dwordx4 v[196:199], v[134:135], off
	v_lshl_add_u64 v[134:135], v[134:135], 0, s[50:51]
	s_waitcnt lgkmcnt(0)
	s_waitcnt vmcnt(6)
	v_mfma_f32_16x16x32_bf16 v[128:131], v[200:203], v[232:235], v[128:131]
	v_mfma_f32_16x16x32_bf16 v[124:127], v[200:203], v[236:239], v[124:127]
	v_mfma_f32_16x16x32_bf16 v[120:123], v[200:203], v[240:243], v[120:123]
	v_mfma_f32_16x16x32_bf16 v[116:119], v[200:203], v[244:247], v[116:119]
	global_load_dwordx4 v[200:203], v[134:135], off
	v_lshl_add_u64 v[134:135], v[134:135], 0, s[62:63]
	ds_read_b128 v[44:47], v169 offset:16384
	ds_read_b128 v[174:177], v169 offset:16640
	ds_read_b128 v[178:181], v169 offset:16896
	ds_read_b128 v[186:189], v169 offset:17152
	s_waitcnt vmcnt(6)
	v_mfma_f32_16x16x32_bf16 v[112:115], v[204:207], v[232:235], v[112:115]
	v_mfma_f32_16x16x32_bf16 v[108:111], v[204:207], v[236:239], v[108:111]
	v_mfma_f32_16x16x32_bf16 v[104:107], v[204:207], v[240:243], v[104:107]
	v_mfma_f32_16x16x32_bf16 v[100:103], v[204:207], v[244:247], v[100:103]
	global_load_dwordx4 v[204:207], v[134:135], off
	v_lshl_add_u64 v[134:135], v[134:135], 0, s[50:51]
	s_waitcnt vmcnt(6)
	v_mfma_f32_16x16x32_bf16 v[96:99], v[208:211], v[232:235], v[96:99]
	v_mfma_f32_16x16x32_bf16 v[92:95], v[208:211], v[236:239], v[92:95]
	v_mfma_f32_16x16x32_bf16 v[88:91], v[208:211], v[240:243], v[88:91]
	v_mfma_f32_16x16x32_bf16 v[84:87], v[208:211], v[244:247], v[84:87]
	global_load_dwordx4 v[208:211], v[134:135], off
	v_lshl_add_u64 v[134:135], v[134:135], 0, s[50:51]
	s_waitcnt vmcnt(6)
	v_mfma_f32_16x16x32_bf16 v[80:83], v[212:215], v[232:235], v[80:83]
	v_mfma_f32_16x16x32_bf16 v[76:79], v[212:215], v[236:239], v[76:79]
	v_mfma_f32_16x16x32_bf16 v[72:75], v[212:215], v[240:243], v[72:75]
	v_mfma_f32_16x16x32_bf16 v[68:71], v[212:215], v[244:247], v[68:71]
	global_load_dwordx4 v[212:215], v[134:135], off
	v_lshl_add_u64 v[134:135], v[134:135], 0, s[50:51]
	s_waitcnt vmcnt(6)
	v_mfma_f32_16x16x32_bf16 v[64:67], v[170:173], v[232:235], v[64:67]
	v_mfma_f32_16x16x32_bf16 v[60:63], v[170:173], v[236:239], v[60:63]
	v_mfma_f32_16x16x32_bf16 v[56:59], v[170:173], v[240:243], v[56:59]
	v_mfma_f32_16x16x32_bf16 v[52:55], v[170:173], v[244:247], v[52:55]
	global_load_dwordx4 v[170:173], v[134:135], off
	v_lshl_add_u64 v[134:135], v[134:135], 0, s[50:51]
	s_waitcnt vmcnt(6)
	v_mfma_f32_16x16x32_bf16 v[48:51], v[192:195], v[232:235], v[48:51]
	v_mfma_f32_16x16x32_bf16 v[40:43], v[192:195], v[236:239], v[40:43]
	v_mfma_f32_16x16x32_bf16 v[36:39], v[192:195], v[240:243], v[36:39]
	v_mfma_f32_16x16x32_bf16 v[32:35], v[192:195], v[244:247], v[32:35]
	global_load_dwordx4 v[192:195], v[134:135], off
	v_lshl_add_u64 v[134:135], v[134:135], 0, s[50:51]
	s_waitcnt vmcnt(6)
	v_mfma_f32_16x16x32_bf16 v[28:31], v[196:199], v[232:235], v[28:31]
	v_mfma_f32_16x16x32_bf16 v[24:27], v[196:199], v[236:239], v[24:27]
	v_mfma_f32_16x16x32_bf16 v[20:23], v[196:199], v[240:243], v[20:23]
	v_mfma_f32_16x16x32_bf16 v[16:19], v[196:199], v[244:247], v[16:19]
	global_load_dwordx4 v[196:199], v[134:135], off
	v_lshl_add_u64 v[134:135], v[134:135], 0, s[50:51]
	s_waitcnt vmcnt(6)
	v_mfma_f32_16x16x32_bf16 v[12:15], v[200:203], v[232:235], v[12:15]
	v_mfma_f32_16x16x32_bf16 v[8:11], v[200:203], v[236:239], v[8:11]
	v_mfma_f32_16x16x32_bf16 v[4:7], v[200:203], v[240:243], v[4:7]
	v_mfma_f32_16x16x32_bf16 v[0:3], v[200:203], v[244:247], v[0:3]
	global_load_dwordx4 v[200:203], v[134:135], off
	v_lshl_add_u64 v[134:135], v[134:135], 0, s[50:51]
	s_waitcnt lgkmcnt(0)
	s_waitcnt vmcnt(6)
	v_mfma_f32_16x16x32_bf16 v[128:131], v[204:207], v[44:47], v[128:131]
	v_mfma_f32_16x16x32_bf16 v[124:127], v[204:207], v[174:177], v[124:127]
	v_mfma_f32_16x16x32_bf16 v[120:123], v[204:207], v[178:181], v[120:123]
	v_mfma_f32_16x16x32_bf16 v[116:119], v[204:207], v[186:189], v[116:119]
	global_load_dwordx4 v[204:207], v[134:135], off
	v_lshl_add_u64 v[134:135], v[134:135], 0, s[62:63]
	ds_read_b128 v[232:235], v169 offset:20480
	ds_read_b128 v[236:239], v169 offset:20736
	ds_read_b128 v[240:243], v169 offset:20992
	ds_read_b128 v[244:247], v169 offset:21248
	s_waitcnt vmcnt(6)
; #define LAS __attribute__((address_space(3)))
; template <int PMODE> __device__ __forceinline__ void ssm_c_task(unsigned char* ws, LAS unsigned char* lds, int l, int task, int tid_in) {
;     ...
;     { const bf16* WC = (const bf16*)(ws + WS_WC) + ((size_t)(g * 1024 + wid * 128 + rr) * 256 + 8 * kk);
; #pragma unroll 1
;       for (int ks = 0; ks < 8; ++ks) {
;           bf16x8 bfr[4], afr[8];
; #pragma unroll
;           for (int a = 0; a < 8; ++a) afr[a] = *(const bf16x8*)(WC + (size_t)a * 16 * 256 + ks * 32);
; #pragma unroll
;           for (int c = 0; c < 4; ++c) bfr[c] = *(const LAS bf16x8*)(lds + SS_UB + (((ks * 4 + kk) * 64 + c * 16 + rr) * 16));
; #pragma unroll
;           for (int a = 0; a < 8; ++a)
; #pragma unroll
;               for (int c = 0; c < 4; ++c) acc[a][c] = __builtin_amdgcn_mfma_f32_16x16x32_bf16(afr[a], bfr[c], acc[a][c], 0, 0, 0);
;       } }
	v_mfma_f32_16x16x32_bf16 v[112:115], v[208:211], v[44:47], v[112:115]
	v_mfma_f32_16x16x32_bf16 v[108:111], v[208:211], v[174:177], v[108:111]
	v_mfma_f32_16x16x32_bf16 v[104:107], v[208:211], v[178:181], v[104:107]
	v_mfma_f32_16x16x32_bf16 v[100:103], v[208:211], v[186:189], v[100:103]
	global_load_dwordx4 v[208:211], v[134:135], off
	v_lshl_add_u64 v[134:135], v[134:135], 0, s[50:51]
	s_waitcnt vmcnt(6)
	v_mfma_f32_16x16x32_bf16 v[96:99], v[212:215], v[44:47], v[96:99]
	v_mfma_f32_16x16x32_bf16 v[92:95], v[212:215], v[174:177], v[92:95]
	v_mfma_f32_16x16x32_bf16 v[88:91], v[212:215], v[178:181], v[88:91]
	v_mfma_f32_16x16x32_bf16 v[84:87], v[212:215], v[186:189], v[84:87]
	global_load_dwordx4 v[212:215], v[134:135], off
	v_lshl_add_u64 v[134:135], v[134:135], 0, s[50:51]
	s_waitcnt vmcnt(6)
	v_mfma_f32_16x16x32_bf16 v[80:83], v[170:173], v[44:47], v[80:83]
	v_mfma_f32_16x16x32_bf16 v[76:79], v[170:173], v[174:177], v[76:79]
	v_mfma_f32_16x16x32_bf16 v[72:75], v[170:173], v[178:181], v[72:75]
	v_mfma_f32_16x16x32_bf16 v[68:71], v[170:173], v[186:189], v[68:71]
	global_load_dwordx4 v[170:173], v[134:135], off
	v_lshl_add_u64 v[134:135], v[134:135], 0, s[50:51]
	s_waitcnt vmcnt(6)
	v_mfma_f32_16x16x32_bf16 v[64:67], v[192:195], v[44:47], v[64:67]
	v_mfma_f32_16x16x32_bf16 v[60:63], v[192:195], v[174:177], v[60:63]
	v_mfma_f32_16x16x32_bf16 v[56:59], v[192:195], v[178:181], v[56:59]
	v_mfma_f32_16x16x32_bf16 v[52:55], v[192:195], v[186:189], v[52:55]
	global_load_dwordx4 v[192:195], v[134:135], off
	v_lshl_add_u64 v[134:135], v[134:135], 0, s[50:51]
	s_waitcnt vmcnt(6)
	v_mfma_f32_16x16x32_bf16 v[48:51], v[196:199], v[44:47], v[48:51]
	v_mfma_f32_16x16x32_bf16 v[40:43], v[196:199], v[174:177], v[40:43]
	v_mfma_f32_16x16x32_bf16 v[36:39], v[196:199], v[178:181], v[36:39]
	v_mfma_f32_16x16x32_bf16 v[32:35], v[196:199], v[186:189], v[32:35]
	global_load_dwordx4 v[196:199], v[134:135], off
	v_lshl_add_u64 v[134:135], v[134:135], 0, s[50:51]
	s_waitcnt vmcnt(6)
	v_mfma_f32_16x16x32_bf16 v[28:31], v[200:203], v[44:47], v[28:31]
	v_mfma_f32_16x16x32_bf16 v[24:27], v[200:203], v[174:177], v[24:27]
	v_mfma_f32_16x16x32_bf16 v[20:23], v[200:203], v[178:181], v[20:23]
	v_mfma_f32_16x16x32_bf16 v[16:19], v[200:203], v[186:189], v[16:19]
	global_load_dwordx4 v[200:203], v[134:135], off
	v_lshl_add_u64 v[134:135], v[134:135], 0, s[50:51]
	s_waitcnt vmcnt(6)
	v_mfma_f32_16x16x32_bf16 v[12:15], v[204:207], v[44:47], v[12:15]
	v_mfma_f32_16x16x32_bf16 v[8:11], v[204:207], v[174:177], v[8:11]
	v_mfma_f32_16x16x32_bf16 v[4:7], v[204:207], v[178:181], v[4:7]
	v_mfma_f32_16x16x32_bf16 v[0:3], v[204:207], v[186:189], v[0:3]
	global_load_dwordx4 v[204:207], v[134:135], off
	v_lshl_add_u64 v[134:135], v[134:135], 0, s[50:51]
	s_waitcnt lgkmcnt(0)
	s_waitcnt vmcnt(6)
	v_mfma_f32_16x16x32_bf16 v[128:131], v[208:211], v[232:235], v[128:131]
	v_mfma_f32_16x16x32_bf16 v[124:127], v[208:211], v[236:239], v[124:127]
	v_mfma_f32_16x16x32_bf16 v[120:123], v[208:211], v[240:243], v[120:123]
	v_mfma_f32_16x16x32_bf16 v[116:119], v[208:211], v[244:247], v[116:119]
	global_load_dwordx4 v[208:211], v[134:135], off
	v_lshl_add_u64 v[134:135], v[134:135], 0, s[62:63]
	ds_read_b128 v[44:47], v169 offset:24576
	ds_read_b128 v[174:177], v169 offset:24832
	ds_read_b128 v[178:181], v169 offset:25088
	ds_read_b128 v[186:189], v169 offset:25344
	s_waitcnt vmcnt(6)
	v_mfma_f32_16x16x32_bf16 v[112:115], v[212:215], v[232:235], v[112:115]
	v_mfma_f32_16x16x32_bf16 v[108:111], v[212:215], v[236:239], v[108:111]
	v_mfma_f32_16x16x32_bf16 v[104:107], v[212:215], v[240:243], v[104:107]
	v_mfma_f32_16x16x32_bf16 v[100:103], v[212:215], v[244:247], v[100:103]
	global_load_dwordx4 v[212:215], v[134:135], off
	v_lshl_add_u64 v[134:135], v[134:135], 0, s[50:51]
	s_waitcnt vmcnt(6)
	v_mfma_f32_16x16x32_bf16 v[96:99], v[170:173], v[232:235], v[96:99]
	v_mfma_f32_16x16x32_bf16 v[92:95], v[170:173], v[236:239], v[92:95]
	v_mfma_f32_16x16x32_bf16 v[88:91], v[170:173], v[240:243], v[88:91]
	v_mfma_f32_16x16x32_bf16 v[84:87], v[170:173], v[244:247], v[84:87]
	global_load_dwordx4 v[170:173], v[134:135], off
	v_lshl_add_u64 v[134:135], v[134:135], 0, s[50:51]
	s_waitcnt vmcnt(6)
	v_mfma_f32_16x16x32_bf16 v[80:83], v[192:195], v[232:235], v[80:83]
	v_mfma_f32_16x16x32_bf16 v[76:79], v[192:195], v[236:239], v[76:79]
	v_mfma_f32_16x16x32_bf16 v[72:75], v[192:195], v[240:243], v[72:75]
	v_mfma_f32_16x16x32_bf16 v[68:71], v[192:195], v[244:247], v[68:71]
	global_load_dwordx4 v[192:195], v[134:135], off
	v_lshl_add_u64 v[134:135], v[134:135], 0, s[50:51]
	s_waitcnt vmcnt(6)
	v_mfma_f32_16x16x32_bf16 v[64:67], v[196:199], v[232:235], v[64:67]
	v_mfma_f32_16x16x32_bf16 v[60:63], v[196:199], v[236:239], v[60:63]
	v_mfma_f32_16x16x32_bf16 v[56:59], v[196:199], v[240:243], v[56:59]
	v_mfma_f32_16x16x32_bf16 v[52:55], v[196:199], v[244:247], v[52:55]
	global_load_dwordx4 v[196:199], v[134:135], off
	v_lshl_add_u64 v[134:135], v[134:135], 0, s[50:51]
	s_waitcnt vmcnt(6)
	v_mfma_f32_16x16x32_bf16 v[48:51], v[200:203], v[232:235], v[48:51]
	v_mfma_f32_16x16x32_bf16 v[40:43], v[200:203], v[236:239], v[40:43]
	v_mfma_f32_16x16x32_bf16 v[36:39], v[200:203], v[240:243], v[36:39]
	v_mfma_f32_16x16x32_bf16 v[32:35], v[200:203], v[244:247], v[32:35]
	global_load_dwordx4 v[200:203], v[134:135], off
	v_lshl_add_u64 v[134:135], v[134:135], 0, s[50:51]
	s_waitcnt vmcnt(6)
	v_mfma_f32_16x16x32_bf16 v[28:31], v[204:207], v[232:235], v[28:31]
	v_mfma_f32_16x16x32_bf16 v[24:27], v[204:207], v[236:239], v[24:27]
	v_mfma_f32_16x16x32_bf16 v[20:23], v[204:207], v[240:243], v[20:23]
	v_mfma_f32_16x16x32_bf16 v[16:19], v[204:207], v[244:247], v[16:19]
	global_load_dwordx4 v[204:207], v[134:135], off
	v_lshl_add_u64 v[134:135], v[134:135], 0, s[50:51]
	s_waitcnt vmcnt(6)
; #define LAS __attribute__((address_space(3)))
; template <int PMODE> __device__ __forceinline__ void ssm_c_task(unsigned char* ws, LAS unsigned char* lds, int l, int task, int tid_in) {
;     ...
;     { const bf16* WC = (const bf16*)(ws + WS_WC) + ((size_t)(g * 1024 + wid * 128 + rr) * 256 + 8 * kk);
; #pragma unroll 1
;       for (int ks = 0; ks < 8; ++ks) {
;           bf16x8 bfr[4], afr[8];
; #pragma unroll
;           for (int a = 0; a < 8; ++a) afr[a] = *(const bf16x8*)(WC + (size_t)a * 16 * 256 + ks * 32);
; #pragma unroll
;           for (int c = 0; c < 4; ++c) bfr[c] = *(const LAS bf16x8*)(lds + SS_UB + (((ks * 4 + kk) * 64 + c * 16 + rr) * 16));
; #pragma unroll
;           for (int a = 0; a < 8; ++a)
; #pragma unroll
;               for (int c = 0; c < 4; ++c) acc[a][c] = __builtin_amdgcn_mfma_f32_16x16x32_bf16(afr[a], bfr[c], acc[a][c], 0, 0, 0);
;       } }
;     __syncthreads();
	v_mfma_f32_16x16x32_bf16 v[12:15], v[208:211], v[232:235], v[12:15]
	v_mfma_f32_16x16x32_bf16 v[8:11], v[208:211], v[236:239], v[8:11]
	v_mfma_f32_16x16x32_bf16 v[4:7], v[208:211], v[240:243], v[4:7]
	v_mfma_f32_16x16x32_bf16 v[0:3], v[208:211], v[244:247], v[0:3]
	global_load_dwordx4 v[208:211], v[134:135], off
	v_lshl_add_u64 v[134:135], v[134:135], 0, s[50:51]
	s_waitcnt lgkmcnt(0)
	s_waitcnt vmcnt(6)
	v_mfma_f32_16x16x32_bf16 v[128:131], v[212:215], v[44:47], v[128:131]
	v_mfma_f32_16x16x32_bf16 v[124:127], v[212:215], v[174:177], v[124:127]
	v_mfma_f32_16x16x32_bf16 v[120:123], v[212:215], v[178:181], v[120:123]
	v_mfma_f32_16x16x32_bf16 v[116:119], v[212:215], v[186:189], v[116:119]
	global_load_dwordx4 v[212:215], v[134:135], off
	v_lshl_add_u64 v[134:135], v[134:135], 0, s[62:63]
	ds_read_b128 v[232:235], v169 offset:28672
	ds_read_b128 v[236:239], v169 offset:28928
	ds_read_b128 v[240:243], v169 offset:29184
	ds_read_b128 v[244:247], v169 offset:29440
	s_waitcnt vmcnt(6)
	v_mfma_f32_16x16x32_bf16 v[112:115], v[170:173], v[44:47], v[112:115]
	v_mfma_f32_16x16x32_bf16 v[108:111], v[170:173], v[174:177], v[108:111]
	v_mfma_f32_16x16x32_bf16 v[104:107], v[170:173], v[178:181], v[104:107]
	v_mfma_f32_16x16x32_bf16 v[100:103], v[170:173], v[186:189], v[100:103]
	global_load_dwordx4 v[170:173], v[134:135], off
	v_lshl_add_u64 v[134:135], v[134:135], 0, s[50:51]
	s_waitcnt vmcnt(6)
	v_mfma_f32_16x16x32_bf16 v[96:99], v[192:195], v[44:47], v[96:99]
	v_mfma_f32_16x16x32_bf16 v[92:95], v[192:195], v[174:177], v[92:95]
	v_mfma_f32_16x16x32_bf16 v[88:91], v[192:195], v[178:181], v[88:91]
	v_mfma_f32_16x16x32_bf16 v[84:87], v[192:195], v[186:189], v[84:87]
	global_load_dwordx4 v[192:195], v[134:135], off
	v_lshl_add_u64 v[134:135], v[134:135], 0, s[50:51]
	s_waitcnt vmcnt(6)
	v_mfma_f32_16x16x32_bf16 v[80:83], v[196:199], v[44:47], v[80:83]
	v_mfma_f32_16x16x32_bf16 v[76:79], v[196:199], v[174:177], v[76:79]
	v_mfma_f32_16x16x32_bf16 v[72:75], v[196:199], v[178:181], v[72:75]
	v_mfma_f32_16x16x32_bf16 v[68:71], v[196:199], v[186:189], v[68:71]
	global_load_dwordx4 v[196:199], v[134:135], off
	v_lshl_add_u64 v[134:135], v[134:135], 0, s[50:51]
	s_waitcnt vmcnt(6)
	v_mfma_f32_16x16x32_bf16 v[64:67], v[200:203], v[44:47], v[64:67]
	v_mfma_f32_16x16x32_bf16 v[60:63], v[200:203], v[174:177], v[60:63]
	v_mfma_f32_16x16x32_bf16 v[56:59], v[200:203], v[178:181], v[56:59]
	v_mfma_f32_16x16x32_bf16 v[52:55], v[200:203], v[186:189], v[52:55]
	global_load_dwordx4 v[200:203], v[134:135], off
	v_lshl_add_u64 v[134:135], v[134:135], 0, s[50:51]
	s_waitcnt vmcnt(6)
	v_mfma_f32_16x16x32_bf16 v[48:51], v[204:207], v[44:47], v[48:51]
	v_mfma_f32_16x16x32_bf16 v[40:43], v[204:207], v[174:177], v[40:43]
	v_mfma_f32_16x16x32_bf16 v[36:39], v[204:207], v[178:181], v[36:39]
	v_mfma_f32_16x16x32_bf16 v[32:35], v[204:207], v[186:189], v[32:35]
	global_load_dwordx4 v[204:207], v[134:135], off
	v_lshl_add_u64 v[134:135], v[134:135], 0, s[50:51]
	s_waitcnt vmcnt(6)
	v_mfma_f32_16x16x32_bf16 v[28:31], v[208:211], v[44:47], v[28:31]
	v_mfma_f32_16x16x32_bf16 v[24:27], v[208:211], v[174:177], v[24:27]
	v_mfma_f32_16x16x32_bf16 v[20:23], v[208:211], v[178:181], v[20:23]
	v_mfma_f32_16x16x32_bf16 v[16:19], v[208:211], v[186:189], v[16:19]
	global_load_dwordx4 v[208:211], v[134:135], off
	v_lshl_add_u64 v[134:135], v[134:135], 0, s[50:51]
	s_waitcnt vmcnt(6)
	v_mfma_f32_16x16x32_bf16 v[12:15], v[212:215], v[44:47], v[12:15]
	v_mfma_f32_16x16x32_bf16 v[8:11], v[212:215], v[174:177], v[8:11]
	v_mfma_f32_16x16x32_bf16 v[4:7], v[212:215], v[178:181], v[4:7]
	v_mfma_f32_16x16x32_bf16 v[0:3], v[212:215], v[186:189], v[0:3]
	global_load_dwordx4 v[212:215], v[134:135], off
	v_lshl_add_u64 v[134:135], v[134:135], 0, s[50:51]
	s_waitcnt lgkmcnt(0)
	s_waitcnt vmcnt(6)
	v_mfma_f32_16x16x32_bf16 v[128:131], v[170:173], v[232:235], v[128:131]
	v_mfma_f32_16x16x32_bf16 v[124:127], v[170:173], v[236:239], v[124:127]
	v_mfma_f32_16x16x32_bf16 v[120:123], v[170:173], v[240:243], v[120:123]
	v_mfma_f32_16x16x32_bf16 v[116:119], v[170:173], v[244:247], v[116:119]
	global_load_dwordx4 v[170:173], v[134:135], off
	v_lshl_add_u64 v[134:135], v[134:135], 0, s[62:63]
	s_waitcnt vmcnt(6)
	v_mfma_f32_16x16x32_bf16 v[112:115], v[192:195], v[232:235], v[112:115]
	v_mfma_f32_16x16x32_bf16 v[108:111], v[192:195], v[236:239], v[108:111]
	v_mfma_f32_16x16x32_bf16 v[104:107], v[192:195], v[240:243], v[104:107]
	v_mfma_f32_16x16x32_bf16 v[100:103], v[192:195], v[244:247], v[100:103]
	s_waitcnt vmcnt(5)
	v_mfma_f32_16x16x32_bf16 v[96:99], v[196:199], v[232:235], v[96:99]
	v_mfma_f32_16x16x32_bf16 v[92:95], v[196:199], v[236:239], v[92:95]
	v_mfma_f32_16x16x32_bf16 v[88:91], v[196:199], v[240:243], v[88:91]
	v_mfma_f32_16x16x32_bf16 v[84:87], v[196:199], v[244:247], v[84:87]
	s_waitcnt vmcnt(4)
	v_mfma_f32_16x16x32_bf16 v[80:83], v[200:203], v[232:235], v[80:83]
	v_mfma_f32_16x16x32_bf16 v[76:79], v[200:203], v[236:239], v[76:79]
	v_mfma_f32_16x16x32_bf16 v[72:75], v[200:203], v[240:243], v[72:75]
	v_mfma_f32_16x16x32_bf16 v[68:71], v[200:203], v[244:247], v[68:71]
	s_waitcnt vmcnt(3)
	v_mfma_f32_16x16x32_bf16 v[64:67], v[204:207], v[232:235], v[64:67]
	v_mfma_f32_16x16x32_bf16 v[60:63], v[204:207], v[236:239], v[60:63]
	v_mfma_f32_16x16x32_bf16 v[56:59], v[204:207], v[240:243], v[56:59]
	v_mfma_f32_16x16x32_bf16 v[52:55], v[204:207], v[244:247], v[52:55]
	s_waitcnt vmcnt(2)
	v_mfma_f32_16x16x32_bf16 v[48:51], v[208:211], v[232:235], v[48:51]
	v_mfma_f32_16x16x32_bf16 v[40:43], v[208:211], v[236:239], v[40:43]
	v_mfma_f32_16x16x32_bf16 v[36:39], v[208:211], v[240:243], v[36:39]
	v_mfma_f32_16x16x32_bf16 v[32:35], v[208:211], v[244:247], v[32:35]
	s_waitcnt vmcnt(1)
	v_mfma_f32_16x16x32_bf16 v[28:31], v[212:215], v[232:235], v[28:31]
	v_mfma_f32_16x16x32_bf16 v[24:27], v[212:215], v[236:239], v[24:27]
	v_mfma_f32_16x16x32_bf16 v[20:23], v[212:215], v[240:243], v[20:23]
	v_mfma_f32_16x16x32_bf16 v[16:19], v[212:215], v[244:247], v[16:19]
	s_waitcnt vmcnt(0)
	v_mfma_f32_16x16x32_bf16 v[12:15], v[170:173], v[232:235], v[12:15]
	v_mfma_f32_16x16x32_bf16 v[8:11], v[170:173], v[236:239], v[8:11]
	v_mfma_f32_16x16x32_bf16 v[4:7], v[170:173], v[240:243], v[4:7]
	v_mfma_f32_16x16x32_bf16 v[0:3], v[170:173], v[244:247], v[0:3]
	v_mov_b32_e32 v132, v216
	s_barrier
; __device__ __forceinline__ unsigned pk2(float lo, float hi) { return pg8::cvt_pk_bf16(lo, hi); }
; __device__ __forceinline__ float gelu_tanh(float x) { const float z = 0.7978845608028654f * (x + 0.044715f * x * x * x); const float t = 1.f - 2.f * __builtin_amdgcn_rcpf(__expf(2.f * z) + 1.f); return 0.5f * x * (1.f + t); }
; template <int PMODE> __device__ __forceinline__ void ssm_c_task(unsigned char* ws, LAS unsigned char* lds, int l, int task, int tid_in) {
;     ...
;     int rr_e = rr; asm volatile("" : "+v"(rr_e));
;     bf16* yb = (bf16*)(ws + AR_YG) + ((size_t)g * NTOK + (size_t)cb * 4096 + (size_t)rr_e * 64 + wid * 8) * 16 + 4 * kk;
;     const f32x4 dv = *(const f32x4*)((const float*)(ws + WS_SMALL) + SM_DD + (size_t)l * NG * NP + g * NP + 4 * kk);
; #pragma unroll
;     for (int a0 = 0; a0 < 8; a0 += 4) {
;         u32x2 uw[4][4];
; #pragma unroll
;         for (int a = 0; a < 4; ++a)
; #pragma unroll
;             for (int c = 0; c < 4; ++c) { const int col = cb * 64 + c * 16 + rr_e; const size_t tok = (size_t)col * 64 + wid * 8 + a0 + a; uw[a][c] = *(const u32x2*)(U + tok * 512 + g * 16 + 4 * kk); }
; #pragma unroll
;         for (int a = 0; a < 4; ++a)
; #pragma unroll
;             for (int c = 0; c < 4; ++c) { const int col = cb * 64 + c * 16 + rr_e; const size_t tok = (size_t)col * 64 + wid * 8 + a0 + a;
;                 const f32x4 av = acc[a0 + a][c];
;                 const float y0 = av[0] + dv[0] * bflo(uw[a][c].x), y1 = av[1] + dv[1] * bfhi(uw[a][c].x), y2 = av[2] + dv[2] * bflo(uw[a][c].y), y3 = av[3] + dv[3] * bfhi(uw[a][c].y);
;                 u32x2 o; o.x = pk2(gelu_tanh(y0), gelu_tanh(y1)); o.y = pk2(gelu_tanh(y2), gelu_tanh(y3));
;                 if (PMODE == 4) asm volatile("" :: "v"(o)); else *(u32x2*)(yb + (c * 1024 + a0 + a) * 16) = o; }
	v_mov_b32_e32 v169, v185
	v_lshl_add_u32 v170, s16, 6, v132
	v_ashrrev_i32_e32 v171, 31, v170
	v_lshl_add_u64 v[174:175], s[60:61], 0, v[168:169]
	v_lshlrev_b64 v[44:45], 16, v[170:171]
	v_lshl_add_u64 v[134:135], v[174:175], 0, v[44:45]
	v_lshl_add_u64 v[176:177], v[134:135], 0, v[156:157]
	global_load_dwordx2 v[186:187], v[176:177], off
	v_lshl_add_u64 v[44:45], s[58:59], 2, v[154:155]
	global_load_dwordx4 v[44:47], v[44:45], off
	v_ashrrev_i32_e32 v133, 31, v132
	v_lshlrev_b64 v[132:133], 11, v[132:133]
	v_add_u32_e32 v178, 16, v170
	v_lshl_add_u64 v[172:173], s[88:89], 0, v[152:153]
	s_lshl_b64 s[14:15], s[56:57], 20
	v_lshl_add_u64 v[132:133], s[18:19], 0, v[132:133]
	v_ashrrev_i32_e32 v179, 31, v178
	v_lshlrev_b64 v[172:173], 5, v[172:173]
	v_lshl_add_u64 v[132:133], v[132:133], 0, s[14:15]
	v_lshlrev_b64 v[178:179], 16, v[178:179]
	v_lshl_add_u64 v[132:133], v[132:133], 0, v[172:173]
	v_lshl_add_u64 v[172:173], v[174:175], 0, v[178:179]
	v_lshl_add_u64 v[178:179], v[172:173], 0, v[156:157]
	global_load_dwordx2 v[214:215], v[178:179], off
	v_add_u32_e32 v180, 32, v170
	v_add_u32_e32 v170, 48, v170
	v_ashrrev_i32_e32 v181, 31, v180
	v_ashrrev_i32_e32 v171, 31, v170
	v_lshlrev_b64 v[180:181], 16, v[180:181]
	v_lshlrev_b64 v[182:183], 16, v[170:171]
	v_lshl_add_u64 v[170:171], v[174:175], 0, v[180:181]
	v_lshl_add_u64 v[174:175], v[174:175], 0, v[182:183]
	v_lshl_add_u64 v[132:133], v[132:133], 0, v[168:169]
	v_lshl_add_u64 v[188:189], v[170:171], 0, v[156:157]
	v_lshl_add_u64 v[190:191], v[174:175], 0, v[156:157]
	global_load_dwordx2 v[208:209], v[176:177], off offset:1024
	global_load_dwordx2 v[200:201], v[176:177], off offset:2048
	global_load_dwordx2 v[182:183], v[176:177], off offset:3072
	global_load_dwordx2 v[212:213], v[188:189], off
	global_load_dwordx2 v[206:207], v[178:179], off offset:1024
	global_load_dwordx2 v[198:199], v[178:179], off offset:2048
	global_load_dwordx2 v[180:181], v[178:179], off offset:3072
	global_load_dwordx2 v[210:211], v[190:191], off
	global_load_dwordx2 v[204:205], v[188:189], off offset:1024
	global_load_dwordx2 v[196:197], v[188:189], off offset:2048
	s_nop 0
	global_load_dwordx2 v[178:179], v[188:189], off offset:3072
	global_load_dwordx2 v[202:203], v[190:191], off offset:1024
	global_load_dwordx2 v[194:195], v[190:191], off offset:2048
	global_load_dwordx2 v[176:177], v[190:191], off offset:3072
	s_mov_b32 s3, 0x8000
	s_add_i32 s54, s54, s76
	s_cmpk_gt_i32 s54, 0xff
	s_waitcnt vmcnt(16)
	v_lshlrev_b32_e32 v169, 16, v186
	v_and_b32_e32 v184, 0xffff0000, v186
	v_lshlrev_b32_e32 v186, 16, v187
	s_waitcnt vmcnt(15)
	v_fma_f32 v128, v44, v169, v128
	v_fma_f32 v129, v45, v184, v129
	v_fma_f32 v130, v46, v186, v130
	v_mul_f32_e32 v169, 0x3d372713, v128
	v_mul_f32_e32 v186, 0x3d372713, v129
	v_and_b32_e32 v187, 0xffff0000, v187
	v_mul_f32_e32 v169, v128, v169
	v_mul_f32_e32 v186, v129, v186
	v_fmac_f32_e32 v131, v47, v187
	v_mul_f32_e32 v184, 0.5, v128
	v_mul_f32_e32 v187, 0.5, v129
	v_mul_f32_e32 v188, 0x3d372713, v130
	v_fma_f32 v128, v128, v169, v128
	v_fma_f32 v129, v129, v186, v129
	v_mul_f32_e32 v188, v130, v188
	v_mul_f32_e32 v128, 0x3f4c422a, v128
	v_mul_f32_e32 v129, 0x3f4c422a, v129
	v_mul_f32_e32 v189, 0x3d372713, v131
	v_fma_f32 v169, v130, v188, v130
	v_add_f32_e32 v128, v128, v128
	v_add_f32_e32 v129, v129, v129
	v_mul_f32_e32 v189, v131, v189
	v_mul_f32_e32 v169, 0x3f4c422a, v169
	v_mul_f32_e32 v128, 0x3fb8aa3b, v128
	v_mul_f32_e32 v129, 0x3fb8aa3b, v129
	v_fma_f32 v186, v131, v189, v131
	v_add_f32_e32 v169, v169, v169
	v_exp_f32_e32 v128, v128
	v_exp_f32_e32 v129, v129
	v_mul_f32_e32 v186, 0x3f4c422a, v186
	v_mul_f32_e32 v169, 0x3fb8aa3b, v169
	v_add_f32_e32 v186, v186, v186
	v_exp_f32_e32 v169, v169
	v_mul_f32_e32 v186, 0x3fb8aa3b, v186
	v_exp_f32_e32 v186, v186
	v_add_f32_e32 v128, 1.0, v128
	v_add_f32_e32 v129, 1.0, v129
	v_rcp_f32_e32 v128, v128
	v_rcp_f32_e32 v129, v129
	v_add_f32_e32 v169, 1.0, v169
	v_rcp_f32_e32 v169, v169
	v_add_f32_e32 v186, 1.0, v186
	v_rcp_f32_e32 v186, v186
	v_fma_f32 v128, v128, -2.0, 1.0
	v_fma_f32 v129, v129, -2.0, 1.0
	v_add_f32_e32 v128, 1.0, v128
	v_add_f32_e32 v129, 1.0, v129
	v_fma_f32 v169, v169, -2.0, 1.0
	v_mul_f32_e32 v128, v184, v128
	v_mul_f32_e32 v129, v187, v129
	v_cvt_pk_bf16_f32 v128, v128, v129
	v_mul_f32_e32 v129, 0.5, v130
	v_add_f32_e32 v130, 1.0, v169
	v_mul_f32_e32 v129, v129, v130
	v_fma_f32 v130, v186, -2.0, 1.0
	v_mul_f32_e32 v131, 0.5, v131
	v_add_f32_e32 v130, 1.0, v130
	v_mul_f32_e32 v130, v131, v130
	v_cvt_pk_bf16_f32 v129, v129, v130
	global_store_dwordx2 v[132:133], v[128:129], off
	s_waitcnt vmcnt(15)
; __device__ __forceinline__ unsigned pk2(float lo, float hi) { return pg8::cvt_pk_bf16(lo, hi); }
; __device__ __forceinline__ float gelu_tanh(float x) { const float z = 0.7978845608028654f * (x + 0.044715f * x * x * x); const float t = 1.f - 2.f * __builtin_amdgcn_rcpf(__expf(2.f * z) + 1.f); return 0.5f * x * (1.f + t); }
; template <int PMODE> __device__ __forceinline__ void ssm_c_task(unsigned char* ws, LAS unsigned char* lds, int l, int task, int tid_in) {
;     ...
;         for (int a = 0; a < 4; ++a)
; #pragma unroll
;             for (int c = 0; c < 4; ++c) { const int col = cb * 64 + c * 16 + rr_e; const size_t tok = (size_t)col * 64 + wid * 8 + a0 + a; uw[a][c] = *(const u32x2*)(U + tok * 512 + g * 16 + 4 * kk); }
; #pragma unroll
;         for (int a = 0; a < 4; ++a)
; #pragma unroll
;             for (int c = 0; c < 4; ++c) { const int col = cb * 64 + c * 16 + rr_e; const size_t tok = (size_t)col * 64 + wid * 8 + a0 + a;
;                 const f32x4 av = acc[a0 + a][c];
;                 const float y0 = av[0] + dv[0] * bflo(uw[a][c].x), y1 = av[1] + dv[1] * bfhi(uw[a][c].x), y2 = av[2] + dv[2] * bflo(uw[a][c].y), y3 = av[3] + dv[3] * bfhi(uw[a][c].y);
;                 u32x2 o; o.x = pk2(gelu_tanh(y0), gelu_tanh(y1)); o.y = pk2(gelu_tanh(y2), gelu_tanh(y3));
;                 if (PMODE == 4) asm volatile("" :: "v"(o)); else *(u32x2*)(yb + (c * 1024 + a0 + a) * 16) = o; }
	v_lshlrev_b32_e32 v128, 16, v214
	v_fma_f32 v124, v44, v128, v124
	v_mul_f32_e32 v128, 0x3d372713, v124
	v_mul_f32_e32 v128, v124, v128
	v_fma_f32 v128, v124, v128, v124
	v_mul_f32_e32 v128, 0x3f4c422a, v128
	v_add_f32_e32 v128, v128, v128
	v_mul_f32_e32 v128, 0x3fb8aa3b, v128
	v_exp_f32_e32 v128, v128
	v_and_b32_e32 v129, 0xffff0000, v214
	v_fma_f32 v125, v45, v129, v125
	v_lshlrev_b32_e32 v129, 16, v215
	v_add_f32_e32 v128, 1.0, v128
	v_rcp_f32_e32 v128, v128
	v_fma_f32 v129, v46, v129, v126
	v_and_b32_e32 v126, 0xffff0000, v215
	v_fmac_f32_e32 v127, v47, v126
	v_fma_f32 v126, v128, -2.0, 1.0
	v_mul_f32_e32 v128, 0x3d372713, v125
	v_mul_f32_e32 v128, v125, v128
	v_fma_f32 v128, v125, v128, v125
	v_mul_f32_e32 v128, 0x3f4c422a, v128
	v_add_f32_e32 v128, v128, v128
	v_mul_f32_e32 v128, 0x3fb8aa3b, v128
	v_exp_f32_e32 v128, v128
	v_mul_f32_e32 v124, 0.5, v124
	v_add_f32_e32 v126, 1.0, v126
	v_mul_f32_e32 v124, v124, v126
	v_add_f32_e32 v126, 1.0, v128
	v_mul_f32_e32 v128, 0x3d372713, v129
	v_mul_f32_e32 v128, v129, v128
	v_mul_f32_e32 v130, 0x3d372713, v127
	v_fma_f32 v128, v129, v128, v129
	v_mul_f32_e32 v130, v127, v130
	v_mul_f32_e32 v128, 0x3f4c422a, v128
	v_fma_f32 v130, v127, v130, v127
	v_rcp_f32_e32 v126, v126
	v_add_f32_e32 v128, v128, v128
	v_mul_f32_e32 v130, 0x3f4c422a, v130
	v_mul_f32_e32 v128, 0x3fb8aa3b, v128
	v_add_f32_e32 v130, v130, v130
	v_exp_f32_e32 v128, v128
	v_mul_f32_e32 v130, 0x3fb8aa3b, v130
	v_exp_f32_e32 v130, v130
	v_fma_f32 v126, v126, -2.0, 1.0
	v_mul_f32_e32 v125, 0.5, v125
	v_add_f32_e32 v126, 1.0, v126
	v_add_f32_e32 v128, 1.0, v128
	v_mul_f32_e32 v125, v125, v126
	v_rcp_f32_e32 v128, v128
	v_cvt_pk_bf16_f32 v126, v124, v125
	v_add_f32_e32 v125, 1.0, v130
	v_rcp_f32_e32 v125, v125
	v_fma_f32 v124, v128, -2.0, 1.0
	v_mul_f32_e32 v128, 0.5, v129
	v_add_f32_e32 v124, 1.0, v124
	v_fma_f32 v125, v125, -2.0, 1.0
	v_mul_f32_e32 v124, v128, v124
	v_mul_f32_e32 v127, 0.5, v127
	v_add_f32_e32 v125, 1.0, v125
	v_mul_f32_e32 v125, v127, v125
	v_cvt_pk_bf16_f32 v127, v124, v125
	v_add_co_u32_e64 v124, s[50:51], s3, v132
	s_mov_b32 s3, 0x10000
	s_nop 0
	v_addc_co_u32_e64 v125, s[50:51], 0, v133, s[50:51]
	global_store_dwordx2 v[124:125], v[126:127], off
	s_waitcnt vmcnt(12)
	v_lshlrev_b32_e32 v126, 16, v212
	v_fma_f32 v120, v44, v126, v120
	v_mul_f32_e32 v126, 0x3d372713, v120
	v_mul_f32_e32 v126, v120, v126
	v_fma_f32 v126, v120, v126, v120
	v_mul_f32_e32 v126, 0x3f4c422a, v126
	v_add_f32_e32 v126, v126, v126
	v_mul_f32_e32 v126, 0x3fb8aa3b, v126
	v_exp_f32_e32 v126, v126
	v_and_b32_e32 v127, 0xffff0000, v212
	v_fma_f32 v121, v45, v127, v121
	v_lshlrev_b32_e32 v127, 16, v213
	v_add_f32_e32 v126, 1.0, v126
	v_rcp_f32_e32 v126, v126
	v_fma_f32 v127, v46, v127, v122
	v_and_b32_e32 v122, 0xffff0000, v213
	v_fmac_f32_e32 v123, v47, v122
	v_fma_f32 v122, v126, -2.0, 1.0
	v_mul_f32_e32 v126, 0x3d372713, v121
	v_mul_f32_e32 v126, v121, v126
	v_fma_f32 v126, v121, v126, v121
	v_mul_f32_e32 v126, 0x3f4c422a, v126
	v_add_f32_e32 v126, v126, v126
	v_mul_f32_e32 v126, 0x3fb8aa3b, v126
	v_exp_f32_e32 v126, v126
	v_mul_f32_e32 v120, 0.5, v120
	v_add_f32_e32 v122, 1.0, v122
	v_mul_f32_e32 v120, v120, v122
	v_add_f32_e32 v122, 1.0, v126
	v_mul_f32_e32 v126, 0x3d372713, v127
	v_mul_f32_e32 v126, v127, v126
	v_mul_f32_e32 v128, 0x3d372713, v123
	v_fma_f32 v126, v127, v126, v127
	v_mul_f32_e32 v128, v123, v128
	v_mul_f32_e32 v126, 0x3f4c422a, v126
	v_fma_f32 v128, v123, v128, v123
	v_rcp_f32_e32 v122, v122
	v_add_f32_e32 v126, v126, v126
	v_mul_f32_e32 v128, 0x3f4c422a, v128
	v_mul_f32_e32 v126, 0x3fb8aa3b, v126
	v_add_f32_e32 v128, v128, v128
	v_exp_f32_e32 v126, v126
	v_mul_f32_e32 v128, 0x3fb8aa3b, v128
	v_exp_f32_e32 v128, v128
	v_fma_f32 v122, v122, -2.0, 1.0
	v_mul_f32_e32 v121, 0.5, v121
	v_add_f32_e32 v122, 1.0, v122
	v_add_f32_e32 v126, 1.0, v126
	v_mul_f32_e32 v121, v121, v122
	v_rcp_f32_e32 v126, v126
	v_cvt_pk_bf16_f32 v122, v120, v121
	v_add_f32_e32 v121, 1.0, v128
	v_rcp_f32_e32 v121, v121
	v_fma_f32 v120, v126, -2.0, 1.0
	v_mul_f32_e32 v126, 0.5, v127
	v_add_f32_e32 v120, 1.0, v120
	v_fma_f32 v121, v121, -2.0, 1.0
	v_mul_f32_e32 v120, v126, v120
	v_mul_f32_e32 v123, 0.5, v123
	v_add_f32_e32 v121, 1.0, v121
	v_mul_f32_e32 v121, v123, v121
	v_cvt_pk_bf16_f32 v123, v120, v121
	v_add_co_u32_e64 v120, s[50:51], s3, v132
	s_mov_b32 s3, 0x18000
	s_nop 0
	v_addc_co_u32_e64 v121, s[50:51], 0, v133, s[50:51]
	global_store_dwordx2 v[120:121], v[122:123], off
	s_waitcnt vmcnt(9)
; __device__ __forceinline__ unsigned pk2(float lo, float hi) { return pg8::cvt_pk_bf16(lo, hi); }
; __device__ __forceinline__ float gelu_tanh(float x) { const float z = 0.7978845608028654f * (x + 0.044715f * x * x * x); const float t = 1.f - 2.f * __builtin_amdgcn_rcpf(__expf(2.f * z) + 1.f); return 0.5f * x * (1.f + t); }
; template <int PMODE> __device__ __forceinline__ void ssm_c_task(unsigned char* ws, LAS unsigned char* lds, int l, int task, int tid_in) {
;     ...
;         for (int a = 0; a < 4; ++a)
; #pragma unroll
;             for (int c = 0; c < 4; ++c) { const int col = cb * 64 + c * 16 + rr_e; const size_t tok = (size_t)col * 64 + wid * 8 + a0 + a; uw[a][c] = *(const u32x2*)(U + tok * 512 + g * 16 + 4 * kk); }
; #pragma unroll
;         for (int a = 0; a < 4; ++a)
; #pragma unroll
;             for (int c = 0; c < 4; ++c) { const int col = cb * 64 + c * 16 + rr_e; const size_t tok = (size_t)col * 64 + wid * 8 + a0 + a;
;                 const f32x4 av = acc[a0 + a][c];
;                 const float y0 = av[0] + dv[0] * bflo(uw[a][c].x), y1 = av[1] + dv[1] * bfhi(uw[a][c].x), y2 = av[2] + dv[2] * bflo(uw[a][c].y), y3 = av[3] + dv[3] * bfhi(uw[a][c].y);
;                 u32x2 o; o.x = pk2(gelu_tanh(y0), gelu_tanh(y1)); o.y = pk2(gelu_tanh(y2), gelu_tanh(y3));
;                 if (PMODE == 4) asm volatile("" :: "v"(o)); else *(u32x2*)(yb + (c * 1024 + a0 + a) * 16) = o; }
	v_lshlrev_b32_e32 v122, 16, v210
	v_fma_f32 v116, v44, v122, v116
	v_mul_f32_e32 v122, 0x3d372713, v116
	v_mul_f32_e32 v122, v116, v122
	v_fma_f32 v122, v116, v122, v116
	v_mul_f32_e32 v122, 0x3f4c422a, v122
	v_add_f32_e32 v122, v122, v122
	v_mul_f32_e32 v122, 0x3fb8aa3b, v122
	v_exp_f32_e32 v122, v122
	v_and_b32_e32 v123, 0xffff0000, v210
	v_fma_f32 v117, v45, v123, v117
	v_lshlrev_b32_e32 v123, 16, v211
	v_add_f32_e32 v122, 1.0, v122
	v_rcp_f32_e32 v122, v122
	v_fma_f32 v123, v46, v123, v118
	v_and_b32_e32 v118, 0xffff0000, v211
	v_fmac_f32_e32 v119, v47, v118
	v_fma_f32 v118, v122, -2.0, 1.0
	v_mul_f32_e32 v122, 0x3d372713, v117
	v_mul_f32_e32 v122, v117, v122
	v_fma_f32 v122, v117, v122, v117
	v_mul_f32_e32 v122, 0x3f4c422a, v122
	v_add_f32_e32 v122, v122, v122
	v_mul_f32_e32 v122, 0x3fb8aa3b, v122
	v_exp_f32_e32 v122, v122
	v_mul_f32_e32 v116, 0.5, v116
	v_add_f32_e32 v118, 1.0, v118
	v_mul_f32_e32 v116, v116, v118
	v_add_f32_e32 v118, 1.0, v122
	v_mul_f32_e32 v122, 0x3d372713, v123
	v_mul_f32_e32 v122, v123, v122
	v_mul_f32_e32 v126, 0x3d372713, v119
	v_fma_f32 v122, v123, v122, v123
	v_mul_f32_e32 v126, v119, v126
	v_mul_f32_e32 v122, 0x3f4c422a, v122
	v_fma_f32 v126, v119, v126, v119
	v_rcp_f32_e32 v118, v118
	v_add_f32_e32 v122, v122, v122
	v_mul_f32_e32 v126, 0x3f4c422a, v126
	v_mul_f32_e32 v122, 0x3fb8aa3b, v122
	v_add_f32_e32 v126, v126, v126
	v_exp_f32_e32 v122, v122
	v_mul_f32_e32 v126, 0x3fb8aa3b, v126
	v_exp_f32_e32 v126, v126
	v_fma_f32 v118, v118, -2.0, 1.0
	v_mul_f32_e32 v117, 0.5, v117
	v_add_f32_e32 v118, 1.0, v118
	v_add_f32_e32 v122, 1.0, v122
	v_mul_f32_e32 v117, v117, v118
	v_rcp_f32_e32 v122, v122
	v_cvt_pk_bf16_f32 v118, v116, v117
	v_add_f32_e32 v117, 1.0, v126
	v_rcp_f32_e32 v117, v117
	v_fma_f32 v116, v122, -2.0, 1.0
	v_mul_f32_e32 v122, 0.5, v123
	v_add_f32_e32 v116, 1.0, v116
	v_fma_f32 v117, v117, -2.0, 1.0
	v_mul_f32_e32 v116, v122, v116
	v_mul_f32_e32 v119, 0.5, v119
	v_add_f32_e32 v117, 1.0, v117
	v_mul_f32_e32 v117, v119, v117
	v_cvt_pk_bf16_f32 v119, v116, v117
	v_add_co_u32_e64 v116, s[50:51], s3, v132
	s_nop 1
	v_addc_co_u32_e64 v117, s[50:51], 0, v133, s[50:51]
	global_store_dwordx2 v[116:117], v[118:119], off
	v_lshlrev_b32_e32 v118, 16, v208
	v_fma_f32 v112, v44, v118, v112
	v_mul_f32_e32 v118, 0x3d372713, v112
	v_mul_f32_e32 v118, v112, v118
	v_fma_f32 v118, v112, v118, v112
	v_mul_f32_e32 v118, 0x3f4c422a, v118
	v_add_f32_e32 v118, v118, v118
	v_and_b32_e32 v119, 0xffff0000, v208
	v_mul_f32_e32 v118, 0x3fb8aa3b, v118
	v_fma_f32 v113, v45, v119, v113
	v_lshlrev_b32_e32 v119, 16, v209
	v_exp_f32_e32 v118, v118
	v_fma_f32 v114, v46, v119, v114
	v_and_b32_e32 v119, 0xffff0000, v209
	v_fmac_f32_e32 v115, v47, v119
	v_mul_f32_e32 v119, 0x3d372713, v113
	v_mul_f32_e32 v119, v113, v119
	v_fma_f32 v119, v113, v119, v113
	v_add_f32_e32 v118, 1.0, v118
	v_mul_f32_e32 v119, 0x3f4c422a, v119
	v_rcp_f32_e32 v118, v118
	v_add_f32_e32 v119, v119, v119
	v_mul_f32_e32 v119, 0x3fb8aa3b, v119
	v_exp_f32_e32 v119, v119
	v_fma_f32 v118, v118, -2.0, 1.0
	v_mul_f32_e32 v112, 0.5, v112
	v_add_f32_e32 v118, 1.0, v118
	v_mul_f32_e32 v112, v112, v118
	v_add_f32_e32 v118, 1.0, v119
	v_mul_f32_e32 v119, 0x3d372713, v114
	v_mul_f32_e32 v119, v114, v119
	v_fma_f32 v119, v114, v119, v114
	v_mul_f32_e32 v122, 0x3d372713, v115
	v_mul_f32_e32 v119, 0x3f4c422a, v119
	v_mul_f32_e32 v122, v115, v122
	v_add_f32_e32 v119, v119, v119
	v_fma_f32 v122, v115, v122, v115
	v_mul_f32_e32 v119, 0x3fb8aa3b, v119
	v_mul_f32_e32 v122, 0x3f4c422a, v122
	v_rcp_f32_e32 v118, v118
	v_exp_f32_e32 v119, v119
	v_add_f32_e32 v122, v122, v122
	v_mul_f32_e32 v122, 0x3fb8aa3b, v122
	v_exp_f32_e32 v122, v122
	v_fma_f32 v118, v118, -2.0, 1.0
	v_add_f32_e32 v119, 1.0, v119
	v_mul_f32_e32 v113, 0.5, v113
	v_add_f32_e32 v118, 1.0, v118
	v_rcp_f32_e32 v119, v119
	v_mul_f32_e32 v113, v113, v118
	v_add_f32_e32 v118, 1.0, v122
	v_rcp_f32_e32 v118, v118
	v_cvt_pk_bf16_f32 v112, v112, v113
	v_fma_f32 v113, v119, -2.0, 1.0
	v_mul_f32_e32 v114, 0.5, v114
	v_add_f32_e32 v113, 1.0, v113
	v_mul_f32_e32 v113, v114, v113
	v_fma_f32 v114, v118, -2.0, 1.0
	v_mul_f32_e32 v115, 0.5, v115
	v_add_f32_e32 v114, 1.0, v114
	v_mul_f32_e32 v114, v115, v114
	v_cvt_pk_bf16_f32 v113, v113, v114
	global_store_dwordx2 v[132:133], v[112:113], off offset:32
	v_lshlrev_b32_e32 v112, 16, v206
	v_fma_f32 v108, v44, v112, v108
	v_mul_f32_e32 v112, 0x3d372713, v108
	v_mul_f32_e32 v112, v108, v112
	v_fma_f32 v112, v108, v112, v108
	v_mul_f32_e32 v112, 0x3f4c422a, v112
	v_add_f32_e32 v112, v112, v112
	v_and_b32_e32 v113, 0xffff0000, v206
	v_mul_f32_e32 v112, 0x3fb8aa3b, v112
	v_fma_f32 v109, v45, v113, v109
	v_lshlrev_b32_e32 v113, 16, v207
	v_exp_f32_e32 v112, v112
	v_fma_f32 v110, v46, v113, v110
	v_and_b32_e32 v113, 0xffff0000, v207
	v_fmac_f32_e32 v111, v47, v113
	v_mul_f32_e32 v113, 0x3d372713, v109
	v_mul_f32_e32 v113, v109, v113
	v_fma_f32 v113, v109, v113, v109
	v_add_f32_e32 v112, 1.0, v112
	v_mul_f32_e32 v113, 0x3f4c422a, v113
	v_rcp_f32_e32 v112, v112
	v_add_f32_e32 v113, v113, v113
	v_mul_f32_e32 v113, 0x3fb8aa3b, v113
	v_exp_f32_e32 v113, v113
	v_fma_f32 v112, v112, -2.0, 1.0
	v_mul_f32_e32 v108, 0.5, v108
	v_add_f32_e32 v112, 1.0, v112
	v_mul_f32_e32 v108, v108, v112
	v_add_f32_e32 v112, 1.0, v113
	v_mul_f32_e32 v113, 0x3d372713, v110
	v_mul_f32_e32 v113, v110, v113
	v_fma_f32 v113, v110, v113, v110
	v_mul_f32_e32 v114, 0x3d372713, v111
	v_mul_f32_e32 v113, 0x3f4c422a, v113
	v_mul_f32_e32 v114, v111, v114
	v_add_f32_e32 v113, v113, v113
	v_fma_f32 v114, v111, v114, v111
	v_mul_f32_e32 v113, 0x3fb8aa3b, v113
	v_mul_f32_e32 v114, 0x3f4c422a, v114
	v_rcp_f32_e32 v112, v112
	v_exp_f32_e32 v113, v113
	v_add_f32_e32 v114, v114, v114
	v_mul_f32_e32 v114, 0x3fb8aa3b, v114
	v_exp_f32_e32 v114, v114
	v_fma_f32 v112, v112, -2.0, 1.0
	v_add_f32_e32 v113, 1.0, v113
	v_mul_f32_e32 v109, 0.5, v109
	v_add_f32_e32 v112, 1.0, v112
	v_rcp_f32_e32 v113, v113
	v_mul_f32_e32 v109, v109, v112
	v_add_f32_e32 v112, 1.0, v114
	v_rcp_f32_e32 v112, v112
	v_cvt_pk_bf16_f32 v108, v108, v109
	v_fma_f32 v109, v113, -2.0, 1.0
	v_mul_f32_e32 v110, 0.5, v110
	v_add_f32_e32 v109, 1.0, v109
	v_mul_f32_e32 v109, v110, v109
	v_fma_f32 v110, v112, -2.0, 1.0
	v_mul_f32_e32 v111, 0.5, v111
	v_add_f32_e32 v110, 1.0, v110
	v_mul_f32_e32 v110, v111, v110
	v_cvt_pk_bf16_f32 v109, v109, v110
	global_store_dwordx2 v[124:125], v[108:109], off offset:32
	s_waitcnt vmcnt(11)
; __device__ __forceinline__ unsigned pk2(float lo, float hi) { return pg8::cvt_pk_bf16(lo, hi); }
; __device__ __forceinline__ float gelu_tanh(float x) { const float z = 0.7978845608028654f * (x + 0.044715f * x * x * x); const float t = 1.f - 2.f * __builtin_amdgcn_rcpf(__expf(2.f * z) + 1.f); return 0.5f * x * (1.f + t); }
; template <int PMODE> __device__ __forceinline__ void ssm_c_task(unsigned char* ws, LAS unsigned char* lds, int l, int task, int tid_in) {
;     ...
;         for (int a = 0; a < 4; ++a)
; #pragma unroll
;             for (int c = 0; c < 4; ++c) { const int col = cb * 64 + c * 16 + rr_e; const size_t tok = (size_t)col * 64 + wid * 8 + a0 + a; uw[a][c] = *(const u32x2*)(U + tok * 512 + g * 16 + 4 * kk); }
; #pragma unroll
;         for (int a = 0; a < 4; ++a)
; #pragma unroll
;             for (int c = 0; c < 4; ++c) { const int col = cb * 64 + c * 16 + rr_e; const size_t tok = (size_t)col * 64 + wid * 8 + a0 + a;
;                 const f32x4 av = acc[a0 + a][c];
;                 const float y0 = av[0] + dv[0] * bflo(uw[a][c].x), y1 = av[1] + dv[1] * bfhi(uw[a][c].x), y2 = av[2] + dv[2] * bflo(uw[a][c].y), y3 = av[3] + dv[3] * bfhi(uw[a][c].y);
;                 u32x2 o; o.x = pk2(gelu_tanh(y0), gelu_tanh(y1)); o.y = pk2(gelu_tanh(y2), gelu_tanh(y3));
;                 if (PMODE == 4) asm volatile("" :: "v"(o)); else *(u32x2*)(yb + (c * 1024 + a0 + a) * 16) = o; }
	v_lshlrev_b32_e32 v108, 16, v204
	v_fma_f32 v104, v44, v108, v104
	v_mul_f32_e32 v108, 0x3d372713, v104
	v_mul_f32_e32 v108, v104, v108
	v_fma_f32 v108, v104, v108, v104
	v_mul_f32_e32 v108, 0x3f4c422a, v108
	v_add_f32_e32 v108, v108, v108
	v_and_b32_e32 v109, 0xffff0000, v204
	v_mul_f32_e32 v108, 0x3fb8aa3b, v108
	v_fma_f32 v105, v45, v109, v105
	v_lshlrev_b32_e32 v109, 16, v205
	v_exp_f32_e32 v108, v108
	v_fma_f32 v106, v46, v109, v106
	v_and_b32_e32 v109, 0xffff0000, v205
	v_fmac_f32_e32 v107, v47, v109
	v_mul_f32_e32 v109, 0x3d372713, v105
	v_mul_f32_e32 v109, v105, v109
	v_fma_f32 v109, v105, v109, v105
	v_add_f32_e32 v108, 1.0, v108
	v_mul_f32_e32 v109, 0x3f4c422a, v109
	v_rcp_f32_e32 v108, v108
	v_add_f32_e32 v109, v109, v109
	v_mul_f32_e32 v109, 0x3fb8aa3b, v109
	v_exp_f32_e32 v109, v109
	v_fma_f32 v108, v108, -2.0, 1.0
	v_mul_f32_e32 v104, 0.5, v104
	v_add_f32_e32 v108, 1.0, v108
	v_mul_f32_e32 v104, v104, v108
	v_add_f32_e32 v108, 1.0, v109
	v_mul_f32_e32 v109, 0x3d372713, v106
	v_mul_f32_e32 v109, v106, v109
	v_fma_f32 v109, v106, v109, v106
	v_mul_f32_e32 v110, 0x3d372713, v107
	v_mul_f32_e32 v109, 0x3f4c422a, v109
	v_mul_f32_e32 v110, v107, v110
	v_add_f32_e32 v109, v109, v109
	v_fma_f32 v110, v107, v110, v107
	v_mul_f32_e32 v109, 0x3fb8aa3b, v109
	v_mul_f32_e32 v110, 0x3f4c422a, v110
	v_rcp_f32_e32 v108, v108
	v_exp_f32_e32 v109, v109
	v_add_f32_e32 v110, v110, v110
	v_mul_f32_e32 v110, 0x3fb8aa3b, v110
	v_exp_f32_e32 v110, v110
	v_fma_f32 v108, v108, -2.0, 1.0
	v_add_f32_e32 v109, 1.0, v109
	v_mul_f32_e32 v105, 0.5, v105
	v_add_f32_e32 v108, 1.0, v108
	v_rcp_f32_e32 v109, v109
	v_mul_f32_e32 v105, v105, v108
	v_add_f32_e32 v108, 1.0, v110
	v_rcp_f32_e32 v108, v108
	v_cvt_pk_bf16_f32 v104, v104, v105
	v_fma_f32 v105, v109, -2.0, 1.0
	v_mul_f32_e32 v106, 0.5, v106
	v_add_f32_e32 v105, 1.0, v105
	v_mul_f32_e32 v105, v106, v105
	v_fma_f32 v106, v108, -2.0, 1.0
	v_mul_f32_e32 v107, 0.5, v107
	v_add_f32_e32 v106, 1.0, v106
	v_mul_f32_e32 v106, v107, v106
	v_cvt_pk_bf16_f32 v105, v105, v106
	global_store_dwordx2 v[120:121], v[104:105], off offset:32
	s_waitcnt vmcnt(9)
	v_lshlrev_b32_e32 v104, 16, v202
	v_fma_f32 v100, v44, v104, v100
	v_mul_f32_e32 v104, 0x3d372713, v100
	v_mul_f32_e32 v104, v100, v104
	v_fma_f32 v104, v100, v104, v100
	v_mul_f32_e32 v104, 0x3f4c422a, v104
	v_add_f32_e32 v104, v104, v104
	v_and_b32_e32 v105, 0xffff0000, v202
	v_mul_f32_e32 v104, 0x3fb8aa3b, v104
	v_fma_f32 v101, v45, v105, v101
	v_lshlrev_b32_e32 v105, 16, v203
	v_exp_f32_e32 v104, v104
	v_fma_f32 v102, v46, v105, v102
	v_and_b32_e32 v105, 0xffff0000, v203
	v_fmac_f32_e32 v103, v47, v105
	v_mul_f32_e32 v105, 0x3d372713, v101
	v_mul_f32_e32 v105, v101, v105
	v_fma_f32 v105, v101, v105, v101
	v_add_f32_e32 v104, 1.0, v104
	v_mul_f32_e32 v105, 0x3f4c422a, v105
	v_rcp_f32_e32 v104, v104
	v_add_f32_e32 v105, v105, v105
	v_mul_f32_e32 v105, 0x3fb8aa3b, v105
	v_exp_f32_e32 v105, v105
	v_fma_f32 v104, v104, -2.0, 1.0
	v_mul_f32_e32 v100, 0.5, v100
	v_add_f32_e32 v104, 1.0, v104
	v_mul_f32_e32 v100, v100, v104
	v_add_f32_e32 v104, 1.0, v105
	v_mul_f32_e32 v105, 0x3d372713, v102
	v_mul_f32_e32 v105, v102, v105
	v_fma_f32 v105, v102, v105, v102
	v_mul_f32_e32 v106, 0x3d372713, v103
	v_mul_f32_e32 v105, 0x3f4c422a, v105
	v_mul_f32_e32 v106, v103, v106
	v_add_f32_e32 v105, v105, v105
	v_fma_f32 v106, v103, v106, v103
	v_mul_f32_e32 v105, 0x3fb8aa3b, v105
	v_mul_f32_e32 v106, 0x3f4c422a, v106
	v_rcp_f32_e32 v104, v104
	v_exp_f32_e32 v105, v105
	v_add_f32_e32 v106, v106, v106
	v_mul_f32_e32 v106, 0x3fb8aa3b, v106
	v_exp_f32_e32 v106, v106
	v_fma_f32 v104, v104, -2.0, 1.0
	v_add_f32_e32 v105, 1.0, v105
	v_mul_f32_e32 v101, 0.5, v101
	v_add_f32_e32 v104, 1.0, v104
	v_rcp_f32_e32 v105, v105
	v_mul_f32_e32 v101, v101, v104
	v_add_f32_e32 v104, 1.0, v106
	v_rcp_f32_e32 v104, v104
	v_cvt_pk_bf16_f32 v100, v100, v101
	v_fma_f32 v101, v105, -2.0, 1.0
	v_mul_f32_e32 v102, 0.5, v102
	v_add_f32_e32 v101, 1.0, v101
	v_mul_f32_e32 v101, v102, v101
	v_fma_f32 v102, v104, -2.0, 1.0
	v_mul_f32_e32 v103, 0.5, v103
	v_add_f32_e32 v102, 1.0, v102
	v_mul_f32_e32 v102, v103, v102
	v_cvt_pk_bf16_f32 v101, v101, v102
	global_store_dwordx2 v[116:117], v[100:101], off offset:32
	v_lshlrev_b32_e32 v100, 16, v200
	v_fma_f32 v96, v44, v100, v96
	v_mul_f32_e32 v100, 0x3d372713, v96
	v_mul_f32_e32 v100, v96, v100
	v_fma_f32 v100, v96, v100, v96
	v_mul_f32_e32 v100, 0x3f4c422a, v100
	v_add_f32_e32 v100, v100, v100
	v_and_b32_e32 v101, 0xffff0000, v200
	v_mul_f32_e32 v100, 0x3fb8aa3b, v100
	v_fma_f32 v97, v45, v101, v97
	v_lshlrev_b32_e32 v101, 16, v201
	v_exp_f32_e32 v100, v100
	v_fma_f32 v98, v46, v101, v98
	v_and_b32_e32 v101, 0xffff0000, v201
	v_fmac_f32_e32 v99, v47, v101
	v_mul_f32_e32 v101, 0x3d372713, v97
	v_mul_f32_e32 v101, v97, v101
	v_fma_f32 v101, v97, v101, v97
	v_add_f32_e32 v100, 1.0, v100
	v_mul_f32_e32 v101, 0x3f4c422a, v101
	v_rcp_f32_e32 v100, v100
	v_add_f32_e32 v101, v101, v101
	v_mul_f32_e32 v101, 0x3fb8aa3b, v101
	v_exp_f32_e32 v101, v101
	v_fma_f32 v100, v100, -2.0, 1.0
	v_mul_f32_e32 v96, 0.5, v96
	v_add_f32_e32 v100, 1.0, v100
	v_mul_f32_e32 v96, v96, v100
	v_add_f32_e32 v100, 1.0, v101
	v_mul_f32_e32 v101, 0x3d372713, v98
	v_mul_f32_e32 v101, v98, v101
	v_fma_f32 v101, v98, v101, v98
	v_mul_f32_e32 v102, 0x3d372713, v99
	v_mul_f32_e32 v101, 0x3f4c422a, v101
	v_mul_f32_e32 v102, v99, v102
	v_add_f32_e32 v101, v101, v101
	v_fma_f32 v102, v99, v102, v99
	v_mul_f32_e32 v101, 0x3fb8aa3b, v101
	v_mul_f32_e32 v102, 0x3f4c422a, v102
	v_rcp_f32_e32 v100, v100
	v_exp_f32_e32 v101, v101
	v_add_f32_e32 v102, v102, v102
	v_mul_f32_e32 v102, 0x3fb8aa3b, v102
	v_exp_f32_e32 v102, v102
; __device__ __forceinline__ unsigned pk2(float lo, float hi) { return pg8::cvt_pk_bf16(lo, hi); }
; __device__ __forceinline__ float gelu_tanh(float x) { const float z = 0.7978845608028654f * (x + 0.044715f * x * x * x); const float t = 1.f - 2.f * __builtin_amdgcn_rcpf(__expf(2.f * z) + 1.f); return 0.5f * x * (1.f + t); }
; template <int PMODE> __device__ __forceinline__ void ssm_c_task(unsigned char* ws, LAS unsigned char* lds, int l, int task, int tid_in) {
;     ...
;         for (int a = 0; a < 4; ++a)
; #pragma unroll
;             for (int c = 0; c < 4; ++c) { const int col = cb * 64 + c * 16 + rr_e; const size_t tok = (size_t)col * 64 + wid * 8 + a0 + a; uw[a][c] = *(const u32x2*)(U + tok * 512 + g * 16 + 4 * kk); }
; #pragma unroll
;         for (int a = 0; a < 4; ++a)
; #pragma unroll
;             for (int c = 0; c < 4; ++c) { const int col = cb * 64 + c * 16 + rr_e; const size_t tok = (size_t)col * 64 + wid * 8 + a0 + a;
;                 const f32x4 av = acc[a0 + a][c];
;                 const float y0 = av[0] + dv[0] * bflo(uw[a][c].x), y1 = av[1] + dv[1] * bfhi(uw[a][c].x), y2 = av[2] + dv[2] * bflo(uw[a][c].y), y3 = av[3] + dv[3] * bfhi(uw[a][c].y);
;                 u32x2 o; o.x = pk2(gelu_tanh(y0), gelu_tanh(y1)); o.y = pk2(gelu_tanh(y2), gelu_tanh(y3));
;                 if (PMODE == 4) asm volatile("" :: "v"(o)); else *(u32x2*)(yb + (c * 1024 + a0 + a) * 16) = o; }
	v_fma_f32 v100, v100, -2.0, 1.0
	v_add_f32_e32 v101, 1.0, v101
	v_mul_f32_e32 v97, 0.5, v97
	v_add_f32_e32 v100, 1.0, v100
	v_rcp_f32_e32 v101, v101
	v_mul_f32_e32 v97, v97, v100
	v_add_f32_e32 v100, 1.0, v102
	v_rcp_f32_e32 v100, v100
	v_cvt_pk_bf16_f32 v96, v96, v97
	v_fma_f32 v97, v101, -2.0, 1.0
	v_mul_f32_e32 v98, 0.5, v98
	v_add_f32_e32 v97, 1.0, v97
	v_mul_f32_e32 v97, v98, v97
	v_fma_f32 v98, v100, -2.0, 1.0
	v_mul_f32_e32 v99, 0.5, v99
	v_add_f32_e32 v98, 1.0, v98
	v_mul_f32_e32 v98, v99, v98
	v_cvt_pk_bf16_f32 v97, v97, v98
	global_store_dwordx2 v[132:133], v[96:97], off offset:64
	v_lshlrev_b32_e32 v96, 16, v198
	v_fma_f32 v92, v44, v96, v92
	v_mul_f32_e32 v96, 0x3d372713, v92
	v_mul_f32_e32 v96, v92, v96
	v_fma_f32 v96, v92, v96, v92
	v_mul_f32_e32 v96, 0x3f4c422a, v96
	v_add_f32_e32 v96, v96, v96
	v_and_b32_e32 v97, 0xffff0000, v198
	v_mul_f32_e32 v96, 0x3fb8aa3b, v96
	v_fma_f32 v93, v45, v97, v93
	v_lshlrev_b32_e32 v97, 16, v199
	v_exp_f32_e32 v96, v96
	v_fma_f32 v94, v46, v97, v94
	v_and_b32_e32 v97, 0xffff0000, v199
	v_fmac_f32_e32 v95, v47, v97
	v_mul_f32_e32 v97, 0x3d372713, v93
	v_mul_f32_e32 v97, v93, v97
	v_fma_f32 v97, v93, v97, v93
	v_add_f32_e32 v96, 1.0, v96
	v_mul_f32_e32 v97, 0x3f4c422a, v97
	v_rcp_f32_e32 v96, v96
	v_add_f32_e32 v97, v97, v97
	v_mul_f32_e32 v97, 0x3fb8aa3b, v97
	v_exp_f32_e32 v97, v97
	v_fma_f32 v96, v96, -2.0, 1.0
	v_mul_f32_e32 v92, 0.5, v92
	v_add_f32_e32 v96, 1.0, v96
	v_mul_f32_e32 v92, v92, v96
	v_add_f32_e32 v96, 1.0, v97
	v_mul_f32_e32 v97, 0x3d372713, v94
	v_mul_f32_e32 v97, v94, v97
	v_fma_f32 v97, v94, v97, v94
	v_mul_f32_e32 v98, 0x3d372713, v95
	v_mul_f32_e32 v97, 0x3f4c422a, v97
	v_mul_f32_e32 v98, v95, v98
	v_add_f32_e32 v97, v97, v97
	v_fma_f32 v98, v95, v98, v95
	v_mul_f32_e32 v97, 0x3fb8aa3b, v97
	v_mul_f32_e32 v98, 0x3f4c422a, v98
	v_rcp_f32_e32 v96, v96
	v_exp_f32_e32 v97, v97
	v_add_f32_e32 v98, v98, v98
	v_mul_f32_e32 v98, 0x3fb8aa3b, v98
	v_exp_f32_e32 v98, v98
	v_fma_f32 v96, v96, -2.0, 1.0
	v_add_f32_e32 v97, 1.0, v97
	v_mul_f32_e32 v93, 0.5, v93
	v_add_f32_e32 v96, 1.0, v96
	v_rcp_f32_e32 v97, v97
	v_mul_f32_e32 v93, v93, v96
	v_add_f32_e32 v96, 1.0, v98
	v_rcp_f32_e32 v96, v96
	v_cvt_pk_bf16_f32 v92, v92, v93
	v_fma_f32 v93, v97, -2.0, 1.0
	v_mul_f32_e32 v94, 0.5, v94
	v_add_f32_e32 v93, 1.0, v93
	v_mul_f32_e32 v93, v94, v93
	v_fma_f32 v94, v96, -2.0, 1.0
	v_mul_f32_e32 v95, 0.5, v95
	v_add_f32_e32 v94, 1.0, v94
	v_mul_f32_e32 v94, v95, v94
	v_cvt_pk_bf16_f32 v93, v93, v94
	global_store_dwordx2 v[124:125], v[92:93], off offset:64
	v_lshlrev_b32_e32 v92, 16, v196
	v_fma_f32 v88, v44, v92, v88
	v_mul_f32_e32 v92, 0x3d372713, v88
	v_mul_f32_e32 v92, v88, v92
	v_fma_f32 v92, v88, v92, v88
	v_mul_f32_e32 v92, 0x3f4c422a, v92
	v_add_f32_e32 v92, v92, v92
	v_and_b32_e32 v93, 0xffff0000, v196
	v_mul_f32_e32 v92, 0x3fb8aa3b, v92
	v_fma_f32 v89, v45, v93, v89
	v_lshlrev_b32_e32 v93, 16, v197
	v_exp_f32_e32 v92, v92
	v_fma_f32 v90, v46, v93, v90
	v_and_b32_e32 v93, 0xffff0000, v197
	v_fmac_f32_e32 v91, v47, v93
	v_mul_f32_e32 v93, 0x3d372713, v89
	v_mul_f32_e32 v93, v89, v93
	v_fma_f32 v93, v89, v93, v89
	v_add_f32_e32 v92, 1.0, v92
	v_mul_f32_e32 v93, 0x3f4c422a, v93
	v_rcp_f32_e32 v92, v92
	v_add_f32_e32 v93, v93, v93
	v_mul_f32_e32 v93, 0x3fb8aa3b, v93
	v_exp_f32_e32 v93, v93
	v_fma_f32 v92, v92, -2.0, 1.0
	v_mul_f32_e32 v88, 0.5, v88
	v_add_f32_e32 v92, 1.0, v92
	v_mul_f32_e32 v88, v88, v92
	v_add_f32_e32 v92, 1.0, v93
	v_mul_f32_e32 v93, 0x3d372713, v90
	v_mul_f32_e32 v93, v90, v93
	v_fma_f32 v93, v90, v93, v90
	v_mul_f32_e32 v94, 0x3d372713, v91
	v_mul_f32_e32 v93, 0x3f4c422a, v93
	v_mul_f32_e32 v94, v91, v94
	v_add_f32_e32 v93, v93, v93
	v_fma_f32 v94, v91, v94, v91
	v_mul_f32_e32 v93, 0x3fb8aa3b, v93
	v_mul_f32_e32 v94, 0x3f4c422a, v94
	v_rcp_f32_e32 v92, v92
	v_exp_f32_e32 v93, v93
	v_add_f32_e32 v94, v94, v94
	v_mul_f32_e32 v94, 0x3fb8aa3b, v94
	v_exp_f32_e32 v94, v94
	v_fma_f32 v92, v92, -2.0, 1.0
	v_add_f32_e32 v93, 1.0, v93
	v_mul_f32_e32 v89, 0.5, v89
	v_add_f32_e32 v92, 1.0, v92
	v_rcp_f32_e32 v93, v93
	v_mul_f32_e32 v89, v89, v92
	v_add_f32_e32 v92, 1.0, v94
	v_rcp_f32_e32 v92, v92
	v_cvt_pk_bf16_f32 v88, v88, v89
	v_fma_f32 v89, v93, -2.0, 1.0
	v_mul_f32_e32 v90, 0.5, v90
	v_add_f32_e32 v89, 1.0, v89
	v_mul_f32_e32 v89, v90, v89
	v_fma_f32 v90, v92, -2.0, 1.0
	v_mul_f32_e32 v91, 0.5, v91
	v_add_f32_e32 v90, 1.0, v90
	v_mul_f32_e32 v90, v91, v90
	v_cvt_pk_bf16_f32 v89, v89, v90
	global_store_dwordx2 v[120:121], v[88:89], off offset:64
	s_waitcnt vmcnt(12)
; __device__ __forceinline__ unsigned pk2(float lo, float hi) { return pg8::cvt_pk_bf16(lo, hi); }
; __device__ __forceinline__ float gelu_tanh(float x) { const float z = 0.7978845608028654f * (x + 0.044715f * x * x * x); const float t = 1.f - 2.f * __builtin_amdgcn_rcpf(__expf(2.f * z) + 1.f); return 0.5f * x * (1.f + t); }
; template <int PMODE> __device__ __forceinline__ void ssm_c_task(unsigned char* ws, LAS unsigned char* lds, int l, int task, int tid_in) {
;     ...
;         for (int a = 0; a < 4; ++a)
; #pragma unroll
;             for (int c = 0; c < 4; ++c) { const int col = cb * 64 + c * 16 + rr_e; const size_t tok = (size_t)col * 64 + wid * 8 + a0 + a; uw[a][c] = *(const u32x2*)(U + tok * 512 + g * 16 + 4 * kk); }
; #pragma unroll
;         for (int a = 0; a < 4; ++a)
; #pragma unroll
;             for (int c = 0; c < 4; ++c) { const int col = cb * 64 + c * 16 + rr_e; const size_t tok = (size_t)col * 64 + wid * 8 + a0 + a;
;                 const f32x4 av = acc[a0 + a][c];
;                 const float y0 = av[0] + dv[0] * bflo(uw[a][c].x), y1 = av[1] + dv[1] * bfhi(uw[a][c].x), y2 = av[2] + dv[2] * bflo(uw[a][c].y), y3 = av[3] + dv[3] * bfhi(uw[a][c].y);
;                 u32x2 o; o.x = pk2(gelu_tanh(y0), gelu_tanh(y1)); o.y = pk2(gelu_tanh(y2), gelu_tanh(y3));
;                 if (PMODE == 4) asm volatile("" :: "v"(o)); else *(u32x2*)(yb + (c * 1024 + a0 + a) * 16) = o; }
	v_lshlrev_b32_e32 v88, 16, v194
	v_fma_f32 v84, v44, v88, v84
	v_mul_f32_e32 v88, 0x3d372713, v84
	v_mul_f32_e32 v88, v84, v88
	v_fma_f32 v88, v84, v88, v84
	v_mul_f32_e32 v88, 0x3f4c422a, v88
	v_add_f32_e32 v88, v88, v88
	v_and_b32_e32 v89, 0xffff0000, v194
	v_mul_f32_e32 v88, 0x3fb8aa3b, v88
	v_fma_f32 v85, v45, v89, v85
	v_lshlrev_b32_e32 v89, 16, v195
	v_exp_f32_e32 v88, v88
	v_fma_f32 v86, v46, v89, v86
	v_and_b32_e32 v89, 0xffff0000, v195
	v_fmac_f32_e32 v87, v47, v89
	v_mul_f32_e32 v89, 0x3d372713, v85
	v_mul_f32_e32 v89, v85, v89
	v_fma_f32 v89, v85, v89, v85
	v_add_f32_e32 v88, 1.0, v88
	v_mul_f32_e32 v89, 0x3f4c422a, v89
	v_rcp_f32_e32 v88, v88
	v_add_f32_e32 v89, v89, v89
	v_mul_f32_e32 v89, 0x3fb8aa3b, v89
	v_exp_f32_e32 v89, v89
	v_fma_f32 v88, v88, -2.0, 1.0
	v_mul_f32_e32 v84, 0.5, v84
	v_add_f32_e32 v88, 1.0, v88
	v_mul_f32_e32 v84, v84, v88
	v_add_f32_e32 v88, 1.0, v89
	v_mul_f32_e32 v89, 0x3d372713, v86
	v_mul_f32_e32 v89, v86, v89
	v_fma_f32 v89, v86, v89, v86
	v_mul_f32_e32 v90, 0x3d372713, v87
	v_mul_f32_e32 v89, 0x3f4c422a, v89
	v_mul_f32_e32 v90, v87, v90
	v_add_f32_e32 v89, v89, v89
	v_fma_f32 v90, v87, v90, v87
	v_mul_f32_e32 v89, 0x3fb8aa3b, v89
	v_mul_f32_e32 v90, 0x3f4c422a, v90
	v_rcp_f32_e32 v88, v88
	v_exp_f32_e32 v89, v89
	v_add_f32_e32 v90, v90, v90
	v_mul_f32_e32 v90, 0x3fb8aa3b, v90
	v_exp_f32_e32 v90, v90
	v_fma_f32 v88, v88, -2.0, 1.0
	v_add_f32_e32 v89, 1.0, v89
	v_mul_f32_e32 v85, 0.5, v85
	v_add_f32_e32 v88, 1.0, v88
	v_rcp_f32_e32 v89, v89
	v_mul_f32_e32 v85, v85, v88
	v_add_f32_e32 v88, 1.0, v90
	v_rcp_f32_e32 v88, v88
	v_cvt_pk_bf16_f32 v84, v84, v85
	v_fma_f32 v85, v89, -2.0, 1.0
	v_mul_f32_e32 v86, 0.5, v86
	v_add_f32_e32 v85, 1.0, v85
	v_mul_f32_e32 v85, v86, v85
	v_fma_f32 v86, v88, -2.0, 1.0
	v_mul_f32_e32 v87, 0.5, v87
	v_add_f32_e32 v86, 1.0, v86
	v_mul_f32_e32 v86, v87, v86
	v_cvt_pk_bf16_f32 v85, v85, v86
	global_store_dwordx2 v[116:117], v[84:85], off offset:64
	v_lshlrev_b32_e32 v84, 16, v182
	v_fma_f32 v80, v44, v84, v80
	v_mul_f32_e32 v84, 0x3d372713, v80
	v_mul_f32_e32 v84, v80, v84
	v_fma_f32 v84, v80, v84, v80
	v_mul_f32_e32 v84, 0x3f4c422a, v84
	v_add_f32_e32 v84, v84, v84
	v_and_b32_e32 v85, 0xffff0000, v182
	v_mul_f32_e32 v84, 0x3fb8aa3b, v84
	v_fma_f32 v81, v45, v85, v81
	v_lshlrev_b32_e32 v85, 16, v183
	v_exp_f32_e32 v84, v84
	v_fma_f32 v82, v46, v85, v82
	v_and_b32_e32 v85, 0xffff0000, v183
	v_fmac_f32_e32 v83, v47, v85
	v_mul_f32_e32 v85, 0x3d372713, v81
	v_mul_f32_e32 v85, v81, v85
	v_fma_f32 v85, v81, v85, v81
	v_add_f32_e32 v84, 1.0, v84
	v_mul_f32_e32 v85, 0x3f4c422a, v85
	v_rcp_f32_e32 v84, v84
	v_add_f32_e32 v85, v85, v85
	v_mul_f32_e32 v85, 0x3fb8aa3b, v85
	v_exp_f32_e32 v85, v85
	v_fma_f32 v84, v84, -2.0, 1.0
	v_mul_f32_e32 v80, 0.5, v80
	v_add_f32_e32 v84, 1.0, v84
	v_mul_f32_e32 v80, v80, v84
	v_add_f32_e32 v84, 1.0, v85
	v_mul_f32_e32 v85, 0x3d372713, v82
	v_mul_f32_e32 v85, v82, v85
	v_fma_f32 v85, v82, v85, v82
	v_mul_f32_e32 v86, 0x3d372713, v83
	v_mul_f32_e32 v85, 0x3f4c422a, v85
	v_mul_f32_e32 v86, v83, v86
	v_add_f32_e32 v85, v85, v85
	v_fma_f32 v86, v83, v86, v83
	v_mul_f32_e32 v85, 0x3fb8aa3b, v85
	v_mul_f32_e32 v86, 0x3f4c422a, v86
	v_rcp_f32_e32 v84, v84
	v_exp_f32_e32 v85, v85
	v_add_f32_e32 v86, v86, v86
	v_mul_f32_e32 v86, 0x3fb8aa3b, v86
	v_exp_f32_e32 v86, v86
	v_fma_f32 v84, v84, -2.0, 1.0
	v_add_f32_e32 v85, 1.0, v85
	v_mul_f32_e32 v81, 0.5, v81
	v_add_f32_e32 v84, 1.0, v84
	v_rcp_f32_e32 v85, v85
	v_mul_f32_e32 v81, v81, v84
	v_add_f32_e32 v84, 1.0, v86
	v_rcp_f32_e32 v84, v84
	v_cvt_pk_bf16_f32 v80, v80, v81
	v_fma_f32 v81, v85, -2.0, 1.0
	v_mul_f32_e32 v82, 0.5, v82
	v_add_f32_e32 v81, 1.0, v81
	v_mul_f32_e32 v81, v82, v81
	v_fma_f32 v82, v84, -2.0, 1.0
	v_mul_f32_e32 v83, 0.5, v83
	v_add_f32_e32 v82, 1.0, v82
	v_mul_f32_e32 v82, v83, v82
	v_cvt_pk_bf16_f32 v81, v81, v82
	global_store_dwordx2 v[132:133], v[80:81], off offset:96
	v_lshlrev_b32_e32 v80, 16, v180
	v_fma_f32 v76, v44, v80, v76
	v_mul_f32_e32 v80, 0x3d372713, v76
	v_mul_f32_e32 v80, v76, v80
	v_fma_f32 v80, v76, v80, v76
	v_mul_f32_e32 v80, 0x3f4c422a, v80
	v_add_f32_e32 v80, v80, v80
	v_and_b32_e32 v81, 0xffff0000, v180
	v_mul_f32_e32 v80, 0x3fb8aa3b, v80
	v_fma_f32 v77, v45, v81, v77
	v_lshlrev_b32_e32 v81, 16, v181
	v_exp_f32_e32 v80, v80
	v_fma_f32 v78, v46, v81, v78
	v_and_b32_e32 v81, 0xffff0000, v181
	v_fmac_f32_e32 v79, v47, v81
	v_mul_f32_e32 v81, 0x3d372713, v77
	v_mul_f32_e32 v81, v77, v81
	v_fma_f32 v81, v77, v81, v77
	v_add_f32_e32 v80, 1.0, v80
	v_mul_f32_e32 v81, 0x3f4c422a, v81
	v_rcp_f32_e32 v80, v80
	v_add_f32_e32 v81, v81, v81
	v_mul_f32_e32 v81, 0x3fb8aa3b, v81
	v_exp_f32_e32 v81, v81
	v_fma_f32 v80, v80, -2.0, 1.0
	v_mul_f32_e32 v76, 0.5, v76
	v_add_f32_e32 v80, 1.0, v80
	v_mul_f32_e32 v76, v76, v80
	v_add_f32_e32 v80, 1.0, v81
	v_mul_f32_e32 v81, 0x3d372713, v78
	v_mul_f32_e32 v81, v78, v81
	v_fma_f32 v81, v78, v81, v78
	v_mul_f32_e32 v82, 0x3d372713, v79
	v_mul_f32_e32 v81, 0x3f4c422a, v81
	v_mul_f32_e32 v82, v79, v82
	v_add_f32_e32 v81, v81, v81
	v_fma_f32 v82, v79, v82, v79
	v_mul_f32_e32 v81, 0x3fb8aa3b, v81
	v_mul_f32_e32 v82, 0x3f4c422a, v82
	v_rcp_f32_e32 v80, v80
	v_exp_f32_e32 v81, v81
	v_add_f32_e32 v82, v82, v82
	v_mul_f32_e32 v82, 0x3fb8aa3b, v82
	v_exp_f32_e32 v82, v82
	v_fma_f32 v80, v80, -2.0, 1.0
	v_add_f32_e32 v81, 1.0, v81
	v_mul_f32_e32 v77, 0.5, v77
	v_add_f32_e32 v80, 1.0, v80
	v_rcp_f32_e32 v81, v81
	v_mul_f32_e32 v77, v77, v80
	v_add_f32_e32 v80, 1.0, v82
	v_rcp_f32_e32 v80, v80
	v_cvt_pk_bf16_f32 v76, v76, v77
	v_fma_f32 v77, v81, -2.0, 1.0
	v_mul_f32_e32 v78, 0.5, v78
	v_add_f32_e32 v77, 1.0, v77
	v_mul_f32_e32 v77, v78, v77
; __device__ __forceinline__ unsigned pk2(float lo, float hi) { return pg8::cvt_pk_bf16(lo, hi); }
; __device__ __forceinline__ float gelu_tanh(float x) { const float z = 0.7978845608028654f * (x + 0.044715f * x * x * x); const float t = 1.f - 2.f * __builtin_amdgcn_rcpf(__expf(2.f * z) + 1.f); return 0.5f * x * (1.f + t); }
; template <int PMODE> __device__ __forceinline__ void ssm_c_task(unsigned char* ws, LAS unsigned char* lds, int l, int task, int tid_in) {
;     ...
;     for (int a0 = 0; a0 < 8; a0 += 4) {
;         u32x2 uw[4][4];
; #pragma unroll
;         for (int a = 0; a < 4; ++a)
; #pragma unroll
;             for (int c = 0; c < 4; ++c) { const int col = cb * 64 + c * 16 + rr_e; const size_t tok = (size_t)col * 64 + wid * 8 + a0 + a; uw[a][c] = *(const u32x2*)(U + tok * 512 + g * 16 + 4 * kk); }
; #pragma unroll
;         for (int a = 0; a < 4; ++a)
; #pragma unroll
;             for (int c = 0; c < 4; ++c) { const int col = cb * 64 + c * 16 + rr_e; const size_t tok = (size_t)col * 64 + wid * 8 + a0 + a;
;                 const f32x4 av = acc[a0 + a][c];
;                 const float y0 = av[0] + dv[0] * bflo(uw[a][c].x), y1 = av[1] + dv[1] * bfhi(uw[a][c].x), y2 = av[2] + dv[2] * bflo(uw[a][c].y), y3 = av[3] + dv[3] * bfhi(uw[a][c].y);
;                 u32x2 o; o.x = pk2(gelu_tanh(y0), gelu_tanh(y1)); o.y = pk2(gelu_tanh(y2), gelu_tanh(y3));
;                 if (PMODE == 4) asm volatile("" :: "v"(o)); else *(u32x2*)(yb + (c * 1024 + a0 + a) * 16) = o; }
	v_fma_f32 v78, v80, -2.0, 1.0
	v_mul_f32_e32 v79, 0.5, v79
	v_add_f32_e32 v78, 1.0, v78
	v_mul_f32_e32 v78, v79, v78
	v_cvt_pk_bf16_f32 v77, v77, v78
	global_store_dwordx2 v[124:125], v[76:77], off offset:96
	v_lshlrev_b32_e32 v76, 16, v178
	v_fma_f32 v72, v44, v76, v72
	v_mul_f32_e32 v76, 0x3d372713, v72
	v_mul_f32_e32 v76, v72, v76
	v_fma_f32 v76, v72, v76, v72
	v_mul_f32_e32 v76, 0x3f4c422a, v76
	v_add_f32_e32 v76, v76, v76
	v_and_b32_e32 v77, 0xffff0000, v178
	v_mul_f32_e32 v76, 0x3fb8aa3b, v76
	v_fma_f32 v73, v45, v77, v73
	v_lshlrev_b32_e32 v77, 16, v179
	v_exp_f32_e32 v76, v76
	v_fma_f32 v74, v46, v77, v74
	v_and_b32_e32 v77, 0xffff0000, v179
	v_fmac_f32_e32 v75, v47, v77
	v_mul_f32_e32 v77, 0x3d372713, v73
	v_mul_f32_e32 v77, v73, v77
	v_fma_f32 v77, v73, v77, v73
	v_add_f32_e32 v76, 1.0, v76
	v_mul_f32_e32 v77, 0x3f4c422a, v77
	v_rcp_f32_e32 v76, v76
	v_add_f32_e32 v77, v77, v77
	v_mul_f32_e32 v77, 0x3fb8aa3b, v77
	v_exp_f32_e32 v77, v77
	v_fma_f32 v76, v76, -2.0, 1.0
	v_mul_f32_e32 v72, 0.5, v72
	v_add_f32_e32 v76, 1.0, v76
	v_mul_f32_e32 v72, v72, v76
	v_add_f32_e32 v76, 1.0, v77
	v_mul_f32_e32 v77, 0x3d372713, v74
	v_mul_f32_e32 v77, v74, v77
	v_fma_f32 v77, v74, v77, v74
	v_mul_f32_e32 v78, 0x3d372713, v75
	v_mul_f32_e32 v77, 0x3f4c422a, v77
	v_mul_f32_e32 v78, v75, v78
	v_add_f32_e32 v77, v77, v77
	v_fma_f32 v78, v75, v78, v75
	v_mul_f32_e32 v77, 0x3fb8aa3b, v77
	v_mul_f32_e32 v78, 0x3f4c422a, v78
	v_rcp_f32_e32 v76, v76
	v_exp_f32_e32 v77, v77
	v_add_f32_e32 v78, v78, v78
	v_mul_f32_e32 v78, 0x3fb8aa3b, v78
	v_exp_f32_e32 v78, v78
	v_fma_f32 v76, v76, -2.0, 1.0
	v_add_f32_e32 v77, 1.0, v77
	v_mul_f32_e32 v73, 0.5, v73
	v_add_f32_e32 v76, 1.0, v76
	v_rcp_f32_e32 v77, v77
	v_mul_f32_e32 v73, v73, v76
	v_add_f32_e32 v76, 1.0, v78
	v_rcp_f32_e32 v76, v76
	v_cvt_pk_bf16_f32 v72, v72, v73
	v_fma_f32 v73, v77, -2.0, 1.0
	v_mul_f32_e32 v74, 0.5, v74
	v_add_f32_e32 v73, 1.0, v73
	v_mul_f32_e32 v73, v74, v73
	v_fma_f32 v74, v76, -2.0, 1.0
	v_mul_f32_e32 v75, 0.5, v75
	v_add_f32_e32 v74, 1.0, v74
	v_mul_f32_e32 v74, v75, v74
	v_cvt_pk_bf16_f32 v73, v73, v74
	global_store_dwordx2 v[120:121], v[72:73], off offset:96
	s_waitcnt vmcnt(15)
	v_lshlrev_b32_e32 v72, 16, v176
	v_fma_f32 v68, v44, v72, v68
	v_mul_f32_e32 v72, 0x3d372713, v68
	v_mul_f32_e32 v72, v68, v72
	v_fma_f32 v72, v68, v72, v68
	v_mul_f32_e32 v72, 0x3f4c422a, v72
	v_add_f32_e32 v72, v72, v72
	v_and_b32_e32 v73, 0xffff0000, v176
	v_mul_f32_e32 v72, 0x3fb8aa3b, v72
	v_fma_f32 v69, v45, v73, v69
	v_lshlrev_b32_e32 v73, 16, v177
	v_exp_f32_e32 v72, v72
	v_fma_f32 v70, v46, v73, v70
	v_and_b32_e32 v73, 0xffff0000, v177
	v_fmac_f32_e32 v71, v47, v73
	v_mul_f32_e32 v73, 0x3d372713, v69
	v_mul_f32_e32 v73, v69, v73
	v_fma_f32 v73, v69, v73, v69
	v_add_f32_e32 v72, 1.0, v72
	v_mul_f32_e32 v73, 0x3f4c422a, v73
	v_rcp_f32_e32 v72, v72
	v_add_f32_e32 v73, v73, v73
	v_mul_f32_e32 v73, 0x3fb8aa3b, v73
	v_exp_f32_e32 v73, v73
	v_fma_f32 v72, v72, -2.0, 1.0
	v_mul_f32_e32 v68, 0.5, v68
	v_add_f32_e32 v72, 1.0, v72
	v_mul_f32_e32 v68, v68, v72
	v_add_f32_e32 v72, 1.0, v73
	v_mul_f32_e32 v73, 0x3d372713, v70
	v_mul_f32_e32 v73, v70, v73
	v_fma_f32 v73, v70, v73, v70
	v_mul_f32_e32 v74, 0x3d372713, v71
	v_mul_f32_e32 v73, 0x3f4c422a, v73
	v_mul_f32_e32 v74, v71, v74
	v_add_f32_e32 v73, v73, v73
	v_fma_f32 v74, v71, v74, v71
	v_mul_f32_e32 v73, 0x3fb8aa3b, v73
	v_mul_f32_e32 v74, 0x3f4c422a, v74
	v_rcp_f32_e32 v72, v72
	v_exp_f32_e32 v73, v73
	v_add_f32_e32 v74, v74, v74
	v_mul_f32_e32 v74, 0x3fb8aa3b, v74
	v_exp_f32_e32 v74, v74
	v_fma_f32 v72, v72, -2.0, 1.0
	v_add_f32_e32 v73, 1.0, v73
	v_mul_f32_e32 v69, 0.5, v69
	v_add_f32_e32 v72, 1.0, v72
	v_rcp_f32_e32 v73, v73
	v_mul_f32_e32 v69, v69, v72
	v_add_f32_e32 v72, 1.0, v74
	v_rcp_f32_e32 v72, v72
	v_cvt_pk_bf16_f32 v68, v68, v69
	v_fma_f32 v69, v73, -2.0, 1.0
	v_mul_f32_e32 v70, 0.5, v70
	v_add_f32_e32 v69, 1.0, v69
	v_mul_f32_e32 v69, v70, v69
	v_fma_f32 v70, v72, -2.0, 1.0
	v_mul_f32_e32 v71, 0.5, v71
	v_add_f32_e32 v70, 1.0, v70
	v_mul_f32_e32 v70, v71, v70
	v_cvt_pk_bf16_f32 v69, v69, v70
	global_store_dwordx2 v[116:117], v[68:69], off offset:96
	v_lshl_add_u64 v[68:69], v[134:135], 0, v[158:159]
	global_load_dwordx2 v[98:99], v[68:69], off
	v_lshl_add_u64 v[68:69], v[172:173], 0, v[158:159]
	v_lshl_add_u64 v[70:71], v[170:171], 0, v[158:159]
	v_lshl_add_u64 v[72:73], v[174:175], 0, v[158:159]
	global_load_dwordx2 v[96:97], v[68:69], off
	global_load_dwordx2 v[94:95], v[70:71], off
	global_load_dwordx2 v[92:93], v[72:73], off
	v_lshl_add_u64 v[68:69], v[134:135], 0, v[160:161]
	v_lshl_add_u64 v[70:71], v[172:173], 0, v[160:161]
	v_lshl_add_u64 v[72:73], v[170:171], 0, v[160:161]
	v_lshl_add_u64 v[74:75], v[174:175], 0, v[160:161]
	global_load_dwordx2 v[90:91], v[68:69], off
	global_load_dwordx2 v[88:89], v[70:71], off
	global_load_dwordx2 v[86:87], v[72:73], off
	global_load_dwordx2 v[84:85], v[74:75], off
	v_lshl_add_u64 v[68:69], v[134:135], 0, v[162:163]
	v_lshl_add_u64 v[70:71], v[172:173], 0, v[162:163]
	v_lshl_add_u64 v[72:73], v[170:171], 0, v[162:163]
	v_lshl_add_u64 v[74:75], v[174:175], 0, v[162:163]
	global_load_dwordx2 v[82:83], v[68:69], off
	global_load_dwordx2 v[80:81], v[70:71], off
	global_load_dwordx2 v[78:79], v[72:73], off
	global_load_dwordx2 v[76:77], v[74:75], off
	v_lshl_add_u64 v[68:69], v[134:135], 0, v[164:165]
	v_lshl_add_u64 v[70:71], v[172:173], 0, v[164:165]
	v_lshl_add_u64 v[100:101], v[170:171], 0, v[164:165]
	v_lshl_add_u64 v[102:103], v[174:175], 0, v[164:165]
	global_load_dwordx2 v[74:75], v[68:69], off
	global_load_dwordx2 v[72:73], v[70:71], off
	s_nop 0
	global_load_dwordx2 v[70:71], v[100:101], off
	global_load_dwordx2 v[68:69], v[102:103], off
	s_waitcnt vmcnt(15)
; __device__ __forceinline__ unsigned pk2(float lo, float hi) { return pg8::cvt_pk_bf16(lo, hi); }
; __device__ __forceinline__ float gelu_tanh(float x) { const float z = 0.7978845608028654f * (x + 0.044715f * x * x * x); const float t = 1.f - 2.f * __builtin_amdgcn_rcpf(__expf(2.f * z) + 1.f); return 0.5f * x * (1.f + t); }
; template <int PMODE> __device__ __forceinline__ void ssm_c_task(unsigned char* ws, LAS unsigned char* lds, int l, int task, int tid_in) {
;     ...
;         for (int a = 0; a < 4; ++a)
; #pragma unroll
;             for (int c = 0; c < 4; ++c) { const int col = cb * 64 + c * 16 + rr_e; const size_t tok = (size_t)col * 64 + wid * 8 + a0 + a; uw[a][c] = *(const u32x2*)(U + tok * 512 + g * 16 + 4 * kk); }
; #pragma unroll
;         for (int a = 0; a < 4; ++a)
; #pragma unroll
;             for (int c = 0; c < 4; ++c) { const int col = cb * 64 + c * 16 + rr_e; const size_t tok = (size_t)col * 64 + wid * 8 + a0 + a;
;                 const f32x4 av = acc[a0 + a][c];
;                 const float y0 = av[0] + dv[0] * bflo(uw[a][c].x), y1 = av[1] + dv[1] * bfhi(uw[a][c].x), y2 = av[2] + dv[2] * bflo(uw[a][c].y), y3 = av[3] + dv[3] * bfhi(uw[a][c].y);
;                 u32x2 o; o.x = pk2(gelu_tanh(y0), gelu_tanh(y1)); o.y = pk2(gelu_tanh(y2), gelu_tanh(y3));
;                 if (PMODE == 4) asm volatile("" :: "v"(o)); else *(u32x2*)(yb + (c * 1024 + a0 + a) * 16) = o; }
	v_lshlrev_b32_e32 v100, 16, v98
	v_fma_f32 v64, v44, v100, v64
	v_mul_f32_e32 v100, 0x3d372713, v64
	v_mul_f32_e32 v100, v64, v100
	v_fma_f32 v100, v64, v100, v64
	v_mul_f32_e32 v100, 0x3f4c422a, v100
	v_add_f32_e32 v100, v100, v100
	v_mul_f32_e32 v100, 0x3fb8aa3b, v100
	v_and_b32_e32 v98, 0xffff0000, v98
	v_exp_f32_e32 v100, v100
	v_fma_f32 v65, v45, v98, v65
	v_lshlrev_b32_e32 v98, 16, v99
	v_fma_f32 v66, v46, v98, v66
	v_and_b32_e32 v98, 0xffff0000, v99
	v_mul_f32_e32 v99, 0x3d372713, v65
	v_mul_f32_e32 v99, v65, v99
	v_fma_f32 v99, v65, v99, v65
	v_add_f32_e32 v100, 1.0, v100
	v_mul_f32_e32 v99, 0x3f4c422a, v99
	v_rcp_f32_e32 v100, v100
	v_add_f32_e32 v99, v99, v99
	v_mul_f32_e32 v99, 0x3fb8aa3b, v99
	v_exp_f32_e32 v99, v99
	v_fmac_f32_e32 v67, v47, v98
	v_fma_f32 v98, v100, -2.0, 1.0
	v_mul_f32_e32 v64, 0.5, v64
	v_add_f32_e32 v98, 1.0, v98
	v_mul_f32_e32 v64, v64, v98
	v_add_f32_e32 v98, 1.0, v99
	v_mul_f32_e32 v99, 0x3d372713, v66
	v_mul_f32_e32 v99, v66, v99
	v_fma_f32 v99, v66, v99, v66
	v_mul_f32_e32 v100, 0x3d372713, v67
	v_mul_f32_e32 v99, 0x3f4c422a, v99
	v_mul_f32_e32 v100, v67, v100
	v_add_f32_e32 v99, v99, v99
	v_fma_f32 v100, v67, v100, v67
	v_mul_f32_e32 v99, 0x3fb8aa3b, v99
	v_mul_f32_e32 v100, 0x3f4c422a, v100
	v_rcp_f32_e32 v98, v98
	v_exp_f32_e32 v99, v99
	v_add_f32_e32 v100, v100, v100
	v_mul_f32_e32 v100, 0x3fb8aa3b, v100
	v_exp_f32_e32 v100, v100
	v_fma_f32 v98, v98, -2.0, 1.0
	v_add_f32_e32 v99, 1.0, v99
	v_mul_f32_e32 v65, 0.5, v65
	v_add_f32_e32 v98, 1.0, v98
	v_rcp_f32_e32 v99, v99
	v_mul_f32_e32 v65, v65, v98
	v_add_f32_e32 v98, 1.0, v100
	v_rcp_f32_e32 v98, v98
	v_cvt_pk_bf16_f32 v64, v64, v65
	v_fma_f32 v65, v99, -2.0, 1.0
	v_mul_f32_e32 v66, 0.5, v66
	v_add_f32_e32 v65, 1.0, v65
	v_mul_f32_e32 v65, v66, v65
	v_fma_f32 v66, v98, -2.0, 1.0
	v_mul_f32_e32 v67, 0.5, v67
	v_add_f32_e32 v66, 1.0, v66
	v_mul_f32_e32 v66, v67, v66
	v_cvt_pk_bf16_f32 v65, v65, v66
	global_store_dwordx2 v[132:133], v[64:65], off offset:128
	s_waitcnt vmcnt(15)
	v_lshlrev_b32_e32 v64, 16, v96
	v_fma_f32 v60, v44, v64, v60
	v_mul_f32_e32 v64, 0x3d372713, v60
	v_mul_f32_e32 v64, v60, v64
	v_fma_f32 v64, v60, v64, v60
	v_mul_f32_e32 v64, 0x3f4c422a, v64
	v_add_f32_e32 v64, v64, v64
	v_and_b32_e32 v65, 0xffff0000, v96
	v_mul_f32_e32 v64, 0x3fb8aa3b, v64
	v_fma_f32 v61, v45, v65, v61
	v_lshlrev_b32_e32 v65, 16, v97
	v_exp_f32_e32 v64, v64
	v_fma_f32 v62, v46, v65, v62
	v_and_b32_e32 v65, 0xffff0000, v97
	v_fmac_f32_e32 v63, v47, v65
	v_mul_f32_e32 v65, 0x3d372713, v61
	v_mul_f32_e32 v65, v61, v65
	v_fma_f32 v65, v61, v65, v61
	v_add_f32_e32 v64, 1.0, v64
	v_mul_f32_e32 v65, 0x3f4c422a, v65
	v_rcp_f32_e32 v64, v64
	v_add_f32_e32 v65, v65, v65
	v_mul_f32_e32 v65, 0x3fb8aa3b, v65
	v_exp_f32_e32 v65, v65
	v_fma_f32 v64, v64, -2.0, 1.0
	v_mul_f32_e32 v60, 0.5, v60
	v_add_f32_e32 v64, 1.0, v64
	v_mul_f32_e32 v60, v60, v64
	v_add_f32_e32 v64, 1.0, v65
	v_mul_f32_e32 v65, 0x3d372713, v62
	v_mul_f32_e32 v65, v62, v65
	v_fma_f32 v65, v62, v65, v62
	v_mul_f32_e32 v66, 0x3d372713, v63
	v_mul_f32_e32 v65, 0x3f4c422a, v65
	v_mul_f32_e32 v66, v63, v66
	v_add_f32_e32 v65, v65, v65
	v_fma_f32 v66, v63, v66, v63
	v_mul_f32_e32 v65, 0x3fb8aa3b, v65
	v_mul_f32_e32 v66, 0x3f4c422a, v66
	v_rcp_f32_e32 v64, v64
	v_exp_f32_e32 v65, v65
	v_add_f32_e32 v66, v66, v66
	v_mul_f32_e32 v66, 0x3fb8aa3b, v66
	v_exp_f32_e32 v66, v66
	v_fma_f32 v64, v64, -2.0, 1.0
	v_add_f32_e32 v65, 1.0, v65
	v_mul_f32_e32 v61, 0.5, v61
	v_add_f32_e32 v64, 1.0, v64
	v_rcp_f32_e32 v65, v65
	v_mul_f32_e32 v61, v61, v64
	v_add_f32_e32 v64, 1.0, v66
	v_rcp_f32_e32 v64, v64
	v_cvt_pk_bf16_f32 v60, v60, v61
	v_fma_f32 v61, v65, -2.0, 1.0
	v_mul_f32_e32 v62, 0.5, v62
	v_add_f32_e32 v61, 1.0, v61
	v_mul_f32_e32 v61, v62, v61
	v_fma_f32 v62, v64, -2.0, 1.0
	v_mul_f32_e32 v63, 0.5, v63
	v_add_f32_e32 v62, 1.0, v62
	v_mul_f32_e32 v62, v63, v62
	v_cvt_pk_bf16_f32 v61, v61, v62
	global_store_dwordx2 v[124:125], v[60:61], off offset:128
	s_waitcnt vmcnt(15)
	v_lshlrev_b32_e32 v60, 16, v94
	v_fma_f32 v56, v44, v60, v56
	v_mul_f32_e32 v60, 0x3d372713, v56
	v_mul_f32_e32 v60, v56, v60
	v_fma_f32 v60, v56, v60, v56
	v_mul_f32_e32 v60, 0x3f4c422a, v60
	v_add_f32_e32 v60, v60, v60
	v_and_b32_e32 v61, 0xffff0000, v94
	v_mul_f32_e32 v60, 0x3fb8aa3b, v60
	v_fma_f32 v57, v45, v61, v57
	v_lshlrev_b32_e32 v61, 16, v95
	v_exp_f32_e32 v60, v60
	v_fma_f32 v58, v46, v61, v58
	v_and_b32_e32 v61, 0xffff0000, v95
	v_fmac_f32_e32 v59, v47, v61
	v_mul_f32_e32 v61, 0x3d372713, v57
	v_mul_f32_e32 v61, v57, v61
	v_fma_f32 v61, v57, v61, v57
	v_add_f32_e32 v60, 1.0, v60
	v_mul_f32_e32 v61, 0x3f4c422a, v61
	v_rcp_f32_e32 v60, v60
	v_add_f32_e32 v61, v61, v61
	v_mul_f32_e32 v61, 0x3fb8aa3b, v61
	v_exp_f32_e32 v61, v61
	v_fma_f32 v60, v60, -2.0, 1.0
	v_mul_f32_e32 v56, 0.5, v56
	v_add_f32_e32 v60, 1.0, v60
	v_mul_f32_e32 v56, v56, v60
	v_add_f32_e32 v60, 1.0, v61
	v_mul_f32_e32 v61, 0x3d372713, v58
	v_mul_f32_e32 v61, v58, v61
	v_fma_f32 v61, v58, v61, v58
	v_mul_f32_e32 v62, 0x3d372713, v59
	v_mul_f32_e32 v61, 0x3f4c422a, v61
	v_mul_f32_e32 v62, v59, v62
	v_add_f32_e32 v61, v61, v61
	v_fma_f32 v62, v59, v62, v59
	v_mul_f32_e32 v61, 0x3fb8aa3b, v61
	v_mul_f32_e32 v62, 0x3f4c422a, v62
	v_rcp_f32_e32 v60, v60
	v_exp_f32_e32 v61, v61
	v_add_f32_e32 v62, v62, v62
	v_mul_f32_e32 v62, 0x3fb8aa3b, v62
	v_exp_f32_e32 v62, v62
	v_fma_f32 v60, v60, -2.0, 1.0
	v_add_f32_e32 v61, 1.0, v61
	v_mul_f32_e32 v57, 0.5, v57
	v_add_f32_e32 v60, 1.0, v60
	v_rcp_f32_e32 v61, v61
	v_mul_f32_e32 v57, v57, v60
	v_add_f32_e32 v60, 1.0, v62
	v_rcp_f32_e32 v60, v60
	v_cvt_pk_bf16_f32 v56, v56, v57
	v_fma_f32 v57, v61, -2.0, 1.0
	v_mul_f32_e32 v58, 0.5, v58
	v_add_f32_e32 v57, 1.0, v57
	v_mul_f32_e32 v57, v58, v57
	v_fma_f32 v58, v60, -2.0, 1.0
	v_mul_f32_e32 v59, 0.5, v59
	v_add_f32_e32 v58, 1.0, v58
	v_mul_f32_e32 v58, v59, v58
	v_cvt_pk_bf16_f32 v57, v57, v58
	global_store_dwordx2 v[120:121], v[56:57], off offset:128
	s_waitcnt vmcnt(15)
; __device__ __forceinline__ unsigned pk2(float lo, float hi) { return pg8::cvt_pk_bf16(lo, hi); }
; __device__ __forceinline__ float gelu_tanh(float x) { const float z = 0.7978845608028654f * (x + 0.044715f * x * x * x); const float t = 1.f - 2.f * __builtin_amdgcn_rcpf(__expf(2.f * z) + 1.f); return 0.5f * x * (1.f + t); }
; template <int PMODE> __device__ __forceinline__ void ssm_c_task(unsigned char* ws, LAS unsigned char* lds, int l, int task, int tid_in) {
;     ...
;         for (int a = 0; a < 4; ++a)
; #pragma unroll
;             for (int c = 0; c < 4; ++c) { const int col = cb * 64 + c * 16 + rr_e; const size_t tok = (size_t)col * 64 + wid * 8 + a0 + a; uw[a][c] = *(const u32x2*)(U + tok * 512 + g * 16 + 4 * kk); }
; #pragma unroll
;         for (int a = 0; a < 4; ++a)
; #pragma unroll
;             for (int c = 0; c < 4; ++c) { const int col = cb * 64 + c * 16 + rr_e; const size_t tok = (size_t)col * 64 + wid * 8 + a0 + a;
;                 const f32x4 av = acc[a0 + a][c];
;                 const float y0 = av[0] + dv[0] * bflo(uw[a][c].x), y1 = av[1] + dv[1] * bfhi(uw[a][c].x), y2 = av[2] + dv[2] * bflo(uw[a][c].y), y3 = av[3] + dv[3] * bfhi(uw[a][c].y);
;                 u32x2 o; o.x = pk2(gelu_tanh(y0), gelu_tanh(y1)); o.y = pk2(gelu_tanh(y2), gelu_tanh(y3));
;                 if (PMODE == 4) asm volatile("" :: "v"(o)); else *(u32x2*)(yb + (c * 1024 + a0 + a) * 16) = o; }
	v_lshlrev_b32_e32 v56, 16, v92
	v_fma_f32 v52, v44, v56, v52
	v_mul_f32_e32 v56, 0x3d372713, v52
	v_mul_f32_e32 v56, v52, v56
	v_fma_f32 v56, v52, v56, v52
	v_mul_f32_e32 v56, 0x3f4c422a, v56
	v_add_f32_e32 v56, v56, v56
	v_and_b32_e32 v57, 0xffff0000, v92
	v_mul_f32_e32 v56, 0x3fb8aa3b, v56
	v_fma_f32 v53, v45, v57, v53
	v_lshlrev_b32_e32 v57, 16, v93
	v_exp_f32_e32 v56, v56
	v_fma_f32 v54, v46, v57, v54
	v_and_b32_e32 v57, 0xffff0000, v93
	v_fmac_f32_e32 v55, v47, v57
	v_mul_f32_e32 v57, 0x3d372713, v53
	v_mul_f32_e32 v57, v53, v57
	v_fma_f32 v57, v53, v57, v53
	v_add_f32_e32 v56, 1.0, v56
	v_mul_f32_e32 v57, 0x3f4c422a, v57
	v_rcp_f32_e32 v56, v56
	v_add_f32_e32 v57, v57, v57
	v_mul_f32_e32 v57, 0x3fb8aa3b, v57
	v_exp_f32_e32 v57, v57
	v_fma_f32 v56, v56, -2.0, 1.0
	v_mul_f32_e32 v52, 0.5, v52
	v_add_f32_e32 v56, 1.0, v56
	v_mul_f32_e32 v52, v52, v56
	v_add_f32_e32 v56, 1.0, v57
	v_mul_f32_e32 v57, 0x3d372713, v54
	v_mul_f32_e32 v57, v54, v57
	v_fma_f32 v57, v54, v57, v54
	v_mul_f32_e32 v58, 0x3d372713, v55
	v_mul_f32_e32 v57, 0x3f4c422a, v57
	v_mul_f32_e32 v58, v55, v58
	v_add_f32_e32 v57, v57, v57
	v_fma_f32 v58, v55, v58, v55
	v_mul_f32_e32 v57, 0x3fb8aa3b, v57
	v_mul_f32_e32 v58, 0x3f4c422a, v58
	v_rcp_f32_e32 v56, v56
	v_exp_f32_e32 v57, v57
	v_add_f32_e32 v58, v58, v58
	v_mul_f32_e32 v58, 0x3fb8aa3b, v58
	v_exp_f32_e32 v58, v58
	v_fma_f32 v56, v56, -2.0, 1.0
	v_add_f32_e32 v57, 1.0, v57
	v_mul_f32_e32 v53, 0.5, v53
	v_add_f32_e32 v56, 1.0, v56
	v_rcp_f32_e32 v57, v57
	v_mul_f32_e32 v53, v53, v56
	v_add_f32_e32 v56, 1.0, v58
	v_rcp_f32_e32 v56, v56
	v_cvt_pk_bf16_f32 v52, v52, v53
	v_fma_f32 v53, v57, -2.0, 1.0
	v_mul_f32_e32 v54, 0.5, v54
	v_add_f32_e32 v53, 1.0, v53
	v_mul_f32_e32 v53, v54, v53
	v_fma_f32 v54, v56, -2.0, 1.0
	v_mul_f32_e32 v55, 0.5, v55
	v_add_f32_e32 v54, 1.0, v54
	v_mul_f32_e32 v54, v55, v54
	v_cvt_pk_bf16_f32 v53, v53, v54
	global_store_dwordx2 v[116:117], v[52:53], off offset:128
	s_waitcnt vmcnt(15)
	v_lshlrev_b32_e32 v52, 16, v90
	v_fma_f32 v48, v44, v52, v48
	v_mul_f32_e32 v52, 0x3d372713, v48
	v_mul_f32_e32 v52, v48, v52
	v_fma_f32 v52, v48, v52, v48
	v_mul_f32_e32 v52, 0x3f4c422a, v52
	v_add_f32_e32 v52, v52, v52
	v_and_b32_e32 v53, 0xffff0000, v90
	v_mul_f32_e32 v52, 0x3fb8aa3b, v52
	v_fma_f32 v49, v45, v53, v49
	v_lshlrev_b32_e32 v53, 16, v91
	v_exp_f32_e32 v52, v52
	v_fma_f32 v50, v46, v53, v50
	v_and_b32_e32 v53, 0xffff0000, v91
	v_fmac_f32_e32 v51, v47, v53
	v_mul_f32_e32 v53, 0x3d372713, v49
	v_mul_f32_e32 v53, v49, v53
	v_fma_f32 v53, v49, v53, v49
	v_add_f32_e32 v52, 1.0, v52
	v_mul_f32_e32 v53, 0x3f4c422a, v53
	v_rcp_f32_e32 v52, v52
	v_add_f32_e32 v53, v53, v53
	v_mul_f32_e32 v53, 0x3fb8aa3b, v53
	v_exp_f32_e32 v53, v53
	v_fma_f32 v52, v52, -2.0, 1.0
	v_mul_f32_e32 v48, 0.5, v48
	v_add_f32_e32 v52, 1.0, v52
	v_mul_f32_e32 v48, v48, v52
	v_add_f32_e32 v52, 1.0, v53
	v_mul_f32_e32 v53, 0x3d372713, v50
	v_mul_f32_e32 v53, v50, v53
	v_fma_f32 v53, v50, v53, v50
	v_mul_f32_e32 v54, 0x3d372713, v51
	v_mul_f32_e32 v53, 0x3f4c422a, v53
	v_mul_f32_e32 v54, v51, v54
	v_add_f32_e32 v53, v53, v53
	v_fma_f32 v54, v51, v54, v51
	v_mul_f32_e32 v53, 0x3fb8aa3b, v53
	v_mul_f32_e32 v54, 0x3f4c422a, v54
	v_rcp_f32_e32 v52, v52
	v_exp_f32_e32 v53, v53
	v_add_f32_e32 v54, v54, v54
	v_mul_f32_e32 v54, 0x3fb8aa3b, v54
	v_exp_f32_e32 v54, v54
	v_fma_f32 v52, v52, -2.0, 1.0
	v_add_f32_e32 v53, 1.0, v53
	v_mul_f32_e32 v49, 0.5, v49
	v_add_f32_e32 v52, 1.0, v52
	v_rcp_f32_e32 v53, v53
	v_mul_f32_e32 v49, v49, v52
	v_add_f32_e32 v52, 1.0, v54
	v_rcp_f32_e32 v52, v52
	v_cvt_pk_bf16_f32 v48, v48, v49
	v_fma_f32 v49, v53, -2.0, 1.0
	v_mul_f32_e32 v50, 0.5, v50
	v_add_f32_e32 v49, 1.0, v49
	v_mul_f32_e32 v49, v50, v49
	v_fma_f32 v50, v52, -2.0, 1.0
	v_mul_f32_e32 v51, 0.5, v51
	v_add_f32_e32 v50, 1.0, v50
	v_mul_f32_e32 v50, v51, v50
	v_cvt_pk_bf16_f32 v49, v49, v50
	global_store_dwordx2 v[132:133], v[48:49], off offset:160
	s_waitcnt vmcnt(15)
	v_lshlrev_b32_e32 v48, 16, v88
	v_fma_f32 v40, v44, v48, v40
	v_mul_f32_e32 v48, 0x3d372713, v40
	v_mul_f32_e32 v48, v40, v48
	v_fma_f32 v48, v40, v48, v40
	v_mul_f32_e32 v48, 0x3f4c422a, v48
	v_add_f32_e32 v48, v48, v48
	v_and_b32_e32 v49, 0xffff0000, v88
	v_mul_f32_e32 v48, 0x3fb8aa3b, v48
	v_fma_f32 v41, v45, v49, v41
	v_lshlrev_b32_e32 v49, 16, v89
	v_exp_f32_e32 v48, v48
	v_fma_f32 v42, v46, v49, v42
	v_and_b32_e32 v49, 0xffff0000, v89
	v_fmac_f32_e32 v43, v47, v49
	v_mul_f32_e32 v49, 0x3d372713, v41
	v_mul_f32_e32 v49, v41, v49
	v_fma_f32 v49, v41, v49, v41
	v_add_f32_e32 v48, 1.0, v48
	v_mul_f32_e32 v49, 0x3f4c422a, v49
	v_rcp_f32_e32 v48, v48
	v_add_f32_e32 v49, v49, v49
	v_mul_f32_e32 v49, 0x3fb8aa3b, v49
	v_exp_f32_e32 v49, v49
	v_fma_f32 v48, v48, -2.0, 1.0
	v_mul_f32_e32 v40, 0.5, v40
	v_add_f32_e32 v48, 1.0, v48
	v_mul_f32_e32 v40, v40, v48
	v_add_f32_e32 v48, 1.0, v49
	v_mul_f32_e32 v49, 0x3d372713, v42
	v_mul_f32_e32 v49, v42, v49
	v_fma_f32 v49, v42, v49, v42
	v_mul_f32_e32 v50, 0x3d372713, v43
	v_mul_f32_e32 v49, 0x3f4c422a, v49
	v_mul_f32_e32 v50, v43, v50
	v_add_f32_e32 v49, v49, v49
	v_fma_f32 v50, v43, v50, v43
	v_mul_f32_e32 v49, 0x3fb8aa3b, v49
	v_mul_f32_e32 v50, 0x3f4c422a, v50
	v_rcp_f32_e32 v48, v48
	v_exp_f32_e32 v49, v49
	v_add_f32_e32 v50, v50, v50
	v_mul_f32_e32 v50, 0x3fb8aa3b, v50
	v_exp_f32_e32 v50, v50
	v_fma_f32 v48, v48, -2.0, 1.0
	v_add_f32_e32 v49, 1.0, v49
	v_mul_f32_e32 v41, 0.5, v41
	v_add_f32_e32 v48, 1.0, v48
	v_rcp_f32_e32 v49, v49
	v_mul_f32_e32 v41, v41, v48
	v_add_f32_e32 v48, 1.0, v50
	v_rcp_f32_e32 v48, v48
	v_cvt_pk_bf16_f32 v40, v40, v41
	v_fma_f32 v41, v49, -2.0, 1.0
	v_mul_f32_e32 v42, 0.5, v42
	v_add_f32_e32 v41, 1.0, v41
	v_mul_f32_e32 v41, v42, v41
	v_fma_f32 v42, v48, -2.0, 1.0
	v_mul_f32_e32 v43, 0.5, v43
	v_add_f32_e32 v42, 1.0, v42
	v_mul_f32_e32 v42, v43, v42
	v_cvt_pk_bf16_f32 v41, v41, v42
	global_store_dwordx2 v[124:125], v[40:41], off offset:160
	s_waitcnt vmcnt(15)
; __device__ __forceinline__ unsigned pk2(float lo, float hi) { return pg8::cvt_pk_bf16(lo, hi); }
; __device__ __forceinline__ float gelu_tanh(float x) { const float z = 0.7978845608028654f * (x + 0.044715f * x * x * x); const float t = 1.f - 2.f * __builtin_amdgcn_rcpf(__expf(2.f * z) + 1.f); return 0.5f * x * (1.f + t); }
; template <int PMODE> __device__ __forceinline__ void ssm_c_task(unsigned char* ws, LAS unsigned char* lds, int l, int task, int tid_in) {
;     ...
;         for (int a = 0; a < 4; ++a)
; #pragma unroll
;             for (int c = 0; c < 4; ++c) { const int col = cb * 64 + c * 16 + rr_e; const size_t tok = (size_t)col * 64 + wid * 8 + a0 + a; uw[a][c] = *(const u32x2*)(U + tok * 512 + g * 16 + 4 * kk); }
; #pragma unroll
;         for (int a = 0; a < 4; ++a)
; #pragma unroll
;             for (int c = 0; c < 4; ++c) { const int col = cb * 64 + c * 16 + rr_e; const size_t tok = (size_t)col * 64 + wid * 8 + a0 + a;
;                 const f32x4 av = acc[a0 + a][c];
;                 const float y0 = av[0] + dv[0] * bflo(uw[a][c].x), y1 = av[1] + dv[1] * bfhi(uw[a][c].x), y2 = av[2] + dv[2] * bflo(uw[a][c].y), y3 = av[3] + dv[3] * bfhi(uw[a][c].y);
;                 u32x2 o; o.x = pk2(gelu_tanh(y0), gelu_tanh(y1)); o.y = pk2(gelu_tanh(y2), gelu_tanh(y3));
;                 if (PMODE == 4) asm volatile("" :: "v"(o)); else *(u32x2*)(yb + (c * 1024 + a0 + a) * 16) = o; }
	v_lshlrev_b32_e32 v40, 16, v86
	v_fma_f32 v36, v44, v40, v36
	v_mul_f32_e32 v40, 0x3d372713, v36
	v_mul_f32_e32 v40, v36, v40
	v_fma_f32 v40, v36, v40, v36
	v_mul_f32_e32 v40, 0x3f4c422a, v40
	v_add_f32_e32 v40, v40, v40
	v_and_b32_e32 v41, 0xffff0000, v86
	v_mul_f32_e32 v40, 0x3fb8aa3b, v40
	v_fma_f32 v37, v45, v41, v37
	v_lshlrev_b32_e32 v41, 16, v87
	v_exp_f32_e32 v40, v40
	v_fma_f32 v38, v46, v41, v38
	v_and_b32_e32 v41, 0xffff0000, v87
	v_fmac_f32_e32 v39, v47, v41
	v_mul_f32_e32 v41, 0x3d372713, v37
	v_mul_f32_e32 v41, v37, v41
	v_fma_f32 v41, v37, v41, v37
	v_add_f32_e32 v40, 1.0, v40
	v_mul_f32_e32 v41, 0x3f4c422a, v41
	v_rcp_f32_e32 v40, v40
	v_add_f32_e32 v41, v41, v41
	v_mul_f32_e32 v41, 0x3fb8aa3b, v41
	v_exp_f32_e32 v41, v41
	v_fma_f32 v40, v40, -2.0, 1.0
	v_mul_f32_e32 v36, 0.5, v36
	v_add_f32_e32 v40, 1.0, v40
	v_mul_f32_e32 v36, v36, v40
	v_add_f32_e32 v40, 1.0, v41
	v_mul_f32_e32 v41, 0x3d372713, v38
	v_mul_f32_e32 v41, v38, v41
	v_fma_f32 v41, v38, v41, v38
	v_mul_f32_e32 v42, 0x3d372713, v39
	v_mul_f32_e32 v41, 0x3f4c422a, v41
	v_mul_f32_e32 v42, v39, v42
	v_add_f32_e32 v41, v41, v41
	v_fma_f32 v42, v39, v42, v39
	v_mul_f32_e32 v41, 0x3fb8aa3b, v41
	v_mul_f32_e32 v42, 0x3f4c422a, v42
	v_rcp_f32_e32 v40, v40
	v_exp_f32_e32 v41, v41
	v_add_f32_e32 v42, v42, v42
	v_mul_f32_e32 v42, 0x3fb8aa3b, v42
	v_exp_f32_e32 v42, v42
	v_fma_f32 v40, v40, -2.0, 1.0
	v_add_f32_e32 v41, 1.0, v41
	v_mul_f32_e32 v37, 0.5, v37
	v_add_f32_e32 v40, 1.0, v40
	v_rcp_f32_e32 v41, v41
	v_mul_f32_e32 v37, v37, v40
	v_add_f32_e32 v40, 1.0, v42
	v_rcp_f32_e32 v40, v40
	v_cvt_pk_bf16_f32 v36, v36, v37
	v_fma_f32 v37, v41, -2.0, 1.0
	v_mul_f32_e32 v38, 0.5, v38
	v_add_f32_e32 v37, 1.0, v37
	v_mul_f32_e32 v37, v38, v37
	v_fma_f32 v38, v40, -2.0, 1.0
	v_mul_f32_e32 v39, 0.5, v39
	v_add_f32_e32 v38, 1.0, v38
	v_mul_f32_e32 v38, v39, v38
	v_cvt_pk_bf16_f32 v37, v37, v38
	global_store_dwordx2 v[120:121], v[36:37], off offset:160
	s_waitcnt vmcnt(15)
	v_lshlrev_b32_e32 v36, 16, v84
	v_fma_f32 v32, v44, v36, v32
	v_mul_f32_e32 v36, 0x3d372713, v32
	v_mul_f32_e32 v36, v32, v36
	v_fma_f32 v36, v32, v36, v32
	v_mul_f32_e32 v36, 0x3f4c422a, v36
	v_add_f32_e32 v36, v36, v36
	v_and_b32_e32 v37, 0xffff0000, v84
	v_mul_f32_e32 v36, 0x3fb8aa3b, v36
	v_fma_f32 v33, v45, v37, v33
	v_lshlrev_b32_e32 v37, 16, v85
	v_exp_f32_e32 v36, v36
	v_fma_f32 v34, v46, v37, v34
	v_and_b32_e32 v37, 0xffff0000, v85
	v_fmac_f32_e32 v35, v47, v37
	v_mul_f32_e32 v37, 0x3d372713, v33
	v_mul_f32_e32 v37, v33, v37
	v_fma_f32 v37, v33, v37, v33
	v_add_f32_e32 v36, 1.0, v36
	v_mul_f32_e32 v37, 0x3f4c422a, v37
	v_rcp_f32_e32 v36, v36
	v_add_f32_e32 v37, v37, v37
	v_mul_f32_e32 v37, 0x3fb8aa3b, v37
	v_exp_f32_e32 v37, v37
	v_fma_f32 v36, v36, -2.0, 1.0
	v_mul_f32_e32 v32, 0.5, v32
	v_add_f32_e32 v36, 1.0, v36
	v_mul_f32_e32 v32, v32, v36
	v_add_f32_e32 v36, 1.0, v37
	v_mul_f32_e32 v37, 0x3d372713, v34
	v_mul_f32_e32 v37, v34, v37
	v_fma_f32 v37, v34, v37, v34
	v_mul_f32_e32 v38, 0x3d372713, v35
	v_mul_f32_e32 v37, 0x3f4c422a, v37
	v_mul_f32_e32 v38, v35, v38
	v_add_f32_e32 v37, v37, v37
	v_fma_f32 v38, v35, v38, v35
	v_mul_f32_e32 v37, 0x3fb8aa3b, v37
	v_mul_f32_e32 v38, 0x3f4c422a, v38
	v_rcp_f32_e32 v36, v36
	v_exp_f32_e32 v37, v37
	v_add_f32_e32 v38, v38, v38
	v_mul_f32_e32 v38, 0x3fb8aa3b, v38
	v_exp_f32_e32 v38, v38
	v_fma_f32 v36, v36, -2.0, 1.0
	v_add_f32_e32 v37, 1.0, v37
	v_mul_f32_e32 v33, 0.5, v33
	v_add_f32_e32 v36, 1.0, v36
	v_rcp_f32_e32 v37, v37
	v_mul_f32_e32 v33, v33, v36
	v_add_f32_e32 v36, 1.0, v38
	v_rcp_f32_e32 v36, v36
	v_cvt_pk_bf16_f32 v32, v32, v33
	v_fma_f32 v33, v37, -2.0, 1.0
	v_mul_f32_e32 v34, 0.5, v34
	v_add_f32_e32 v33, 1.0, v33
	v_mul_f32_e32 v33, v34, v33
	v_fma_f32 v34, v36, -2.0, 1.0
	v_mul_f32_e32 v35, 0.5, v35
	v_add_f32_e32 v34, 1.0, v34
	v_mul_f32_e32 v34, v35, v34
	v_cvt_pk_bf16_f32 v33, v33, v34
	global_store_dwordx2 v[116:117], v[32:33], off offset:160
	s_waitcnt vmcnt(15)
	v_lshlrev_b32_e32 v32, 16, v82
	v_fma_f32 v28, v44, v32, v28
	v_mul_f32_e32 v32, 0x3d372713, v28
	v_mul_f32_e32 v32, v28, v32
	v_fma_f32 v32, v28, v32, v28
	v_mul_f32_e32 v32, 0x3f4c422a, v32
	v_add_f32_e32 v32, v32, v32
	v_and_b32_e32 v33, 0xffff0000, v82
	v_mul_f32_e32 v32, 0x3fb8aa3b, v32
	v_fma_f32 v29, v45, v33, v29
	v_lshlrev_b32_e32 v33, 16, v83
	v_exp_f32_e32 v32, v32
	v_fma_f32 v30, v46, v33, v30
	v_and_b32_e32 v33, 0xffff0000, v83
	v_fmac_f32_e32 v31, v47, v33
	v_mul_f32_e32 v33, 0x3d372713, v29
	v_mul_f32_e32 v33, v29, v33
	v_fma_f32 v33, v29, v33, v29
	v_add_f32_e32 v32, 1.0, v32
	v_mul_f32_e32 v33, 0x3f4c422a, v33
	v_rcp_f32_e32 v32, v32
	v_add_f32_e32 v33, v33, v33
	v_mul_f32_e32 v33, 0x3fb8aa3b, v33
	v_exp_f32_e32 v33, v33
	v_fma_f32 v32, v32, -2.0, 1.0
	v_mul_f32_e32 v28, 0.5, v28
	v_add_f32_e32 v32, 1.0, v32
	v_mul_f32_e32 v28, v28, v32
	v_add_f32_e32 v32, 1.0, v33
	v_mul_f32_e32 v33, 0x3d372713, v30
	v_mul_f32_e32 v33, v30, v33
	v_fma_f32 v33, v30, v33, v30
	v_mul_f32_e32 v34, 0x3d372713, v31
	v_mul_f32_e32 v33, 0x3f4c422a, v33
	v_mul_f32_e32 v34, v31, v34
	v_add_f32_e32 v33, v33, v33
	v_fma_f32 v34, v31, v34, v31
	v_mul_f32_e32 v33, 0x3fb8aa3b, v33
	v_mul_f32_e32 v34, 0x3f4c422a, v34
	v_rcp_f32_e32 v32, v32
	v_exp_f32_e32 v33, v33
	v_add_f32_e32 v34, v34, v34
	v_mul_f32_e32 v34, 0x3fb8aa3b, v34
	v_exp_f32_e32 v34, v34
	v_fma_f32 v32, v32, -2.0, 1.0
	v_add_f32_e32 v33, 1.0, v33
	v_mul_f32_e32 v29, 0.5, v29
	v_add_f32_e32 v32, 1.0, v32
	v_rcp_f32_e32 v33, v33
	v_mul_f32_e32 v29, v29, v32
	v_add_f32_e32 v32, 1.0, v34
	v_rcp_f32_e32 v32, v32
	v_cvt_pk_bf16_f32 v28, v28, v29
	v_fma_f32 v29, v33, -2.0, 1.0
	v_mul_f32_e32 v30, 0.5, v30
	v_add_f32_e32 v29, 1.0, v29
	v_mul_f32_e32 v29, v30, v29
	v_fma_f32 v30, v32, -2.0, 1.0
	v_mul_f32_e32 v31, 0.5, v31
	v_add_f32_e32 v30, 1.0, v30
	v_mul_f32_e32 v30, v31, v30
	v_cvt_pk_bf16_f32 v29, v29, v30
	global_store_dwordx2 v[132:133], v[28:29], off offset:192
	s_waitcnt vmcnt(15)
; __device__ __forceinline__ unsigned pk2(float lo, float hi) { return pg8::cvt_pk_bf16(lo, hi); }
; __device__ __forceinline__ float gelu_tanh(float x) { const float z = 0.7978845608028654f * (x + 0.044715f * x * x * x); const float t = 1.f - 2.f * __builtin_amdgcn_rcpf(__expf(2.f * z) + 1.f); return 0.5f * x * (1.f + t); }
; template <int PMODE> __device__ __forceinline__ void ssm_c_task(unsigned char* ws, LAS unsigned char* lds, int l, int task, int tid_in) {
;     ...
;         for (int a = 0; a < 4; ++a)
; #pragma unroll
;             for (int c = 0; c < 4; ++c) { const int col = cb * 64 + c * 16 + rr_e; const size_t tok = (size_t)col * 64 + wid * 8 + a0 + a; uw[a][c] = *(const u32x2*)(U + tok * 512 + g * 16 + 4 * kk); }
; #pragma unroll
;         for (int a = 0; a < 4; ++a)
; #pragma unroll
;             for (int c = 0; c < 4; ++c) { const int col = cb * 64 + c * 16 + rr_e; const size_t tok = (size_t)col * 64 + wid * 8 + a0 + a;
;                 const f32x4 av = acc[a0 + a][c];
;                 const float y0 = av[0] + dv[0] * bflo(uw[a][c].x), y1 = av[1] + dv[1] * bfhi(uw[a][c].x), y2 = av[2] + dv[2] * bflo(uw[a][c].y), y3 = av[3] + dv[3] * bfhi(uw[a][c].y);
;                 u32x2 o; o.x = pk2(gelu_tanh(y0), gelu_tanh(y1)); o.y = pk2(gelu_tanh(y2), gelu_tanh(y3));
;                 if (PMODE == 4) asm volatile("" :: "v"(o)); else *(u32x2*)(yb + (c * 1024 + a0 + a) * 16) = o; }
	v_lshlrev_b32_e32 v28, 16, v80
	v_fma_f32 v24, v44, v28, v24
	v_mul_f32_e32 v28, 0x3d372713, v24
	v_mul_f32_e32 v28, v24, v28
	v_fma_f32 v28, v24, v28, v24
	v_mul_f32_e32 v28, 0x3f4c422a, v28
	v_add_f32_e32 v28, v28, v28
	v_and_b32_e32 v29, 0xffff0000, v80
	v_mul_f32_e32 v28, 0x3fb8aa3b, v28
	v_fma_f32 v25, v45, v29, v25
	v_lshlrev_b32_e32 v29, 16, v81
	v_exp_f32_e32 v28, v28
	v_fma_f32 v26, v46, v29, v26
	v_and_b32_e32 v29, 0xffff0000, v81
	v_fmac_f32_e32 v27, v47, v29
	v_mul_f32_e32 v29, 0x3d372713, v25
	v_mul_f32_e32 v29, v25, v29
	v_fma_f32 v29, v25, v29, v25
	v_add_f32_e32 v28, 1.0, v28
	v_mul_f32_e32 v29, 0x3f4c422a, v29
	v_rcp_f32_e32 v28, v28
	v_add_f32_e32 v29, v29, v29
	v_mul_f32_e32 v29, 0x3fb8aa3b, v29
	v_exp_f32_e32 v29, v29
	v_fma_f32 v28, v28, -2.0, 1.0
	v_mul_f32_e32 v24, 0.5, v24
	v_add_f32_e32 v28, 1.0, v28
	v_mul_f32_e32 v24, v24, v28
	v_add_f32_e32 v28, 1.0, v29
	v_mul_f32_e32 v29, 0x3d372713, v26
	v_mul_f32_e32 v29, v26, v29
	v_fma_f32 v29, v26, v29, v26
	v_mul_f32_e32 v30, 0x3d372713, v27
	v_mul_f32_e32 v29, 0x3f4c422a, v29
	v_mul_f32_e32 v30, v27, v30
	v_add_f32_e32 v29, v29, v29
	v_fma_f32 v30, v27, v30, v27
	v_mul_f32_e32 v29, 0x3fb8aa3b, v29
	v_mul_f32_e32 v30, 0x3f4c422a, v30
	v_rcp_f32_e32 v28, v28
	v_exp_f32_e32 v29, v29
	v_add_f32_e32 v30, v30, v30
	v_mul_f32_e32 v30, 0x3fb8aa3b, v30
	v_exp_f32_e32 v30, v30
	v_fma_f32 v28, v28, -2.0, 1.0
	v_add_f32_e32 v29, 1.0, v29
	v_mul_f32_e32 v25, 0.5, v25
	v_add_f32_e32 v28, 1.0, v28
	v_rcp_f32_e32 v29, v29
	v_mul_f32_e32 v25, v25, v28
	v_add_f32_e32 v28, 1.0, v30
	v_rcp_f32_e32 v28, v28
	v_cvt_pk_bf16_f32 v24, v24, v25
	v_fma_f32 v25, v29, -2.0, 1.0
	v_mul_f32_e32 v26, 0.5, v26
	v_add_f32_e32 v25, 1.0, v25
	v_mul_f32_e32 v25, v26, v25
	v_fma_f32 v26, v28, -2.0, 1.0
	v_mul_f32_e32 v27, 0.5, v27
	v_add_f32_e32 v26, 1.0, v26
	v_mul_f32_e32 v26, v27, v26
	v_cvt_pk_bf16_f32 v25, v25, v26
	global_store_dwordx2 v[124:125], v[24:25], off offset:192
	s_waitcnt vmcnt(15)
	v_lshlrev_b32_e32 v24, 16, v78
	v_fma_f32 v20, v44, v24, v20
	v_mul_f32_e32 v24, 0x3d372713, v20
	v_mul_f32_e32 v24, v20, v24
	v_fma_f32 v24, v20, v24, v20
	v_mul_f32_e32 v24, 0x3f4c422a, v24
	v_add_f32_e32 v24, v24, v24
	v_and_b32_e32 v25, 0xffff0000, v78
	v_mul_f32_e32 v24, 0x3fb8aa3b, v24
	v_fma_f32 v21, v45, v25, v21
	v_lshlrev_b32_e32 v25, 16, v79
	v_exp_f32_e32 v24, v24
	v_fma_f32 v22, v46, v25, v22
	v_and_b32_e32 v25, 0xffff0000, v79
	v_fmac_f32_e32 v23, v47, v25
	v_mul_f32_e32 v25, 0x3d372713, v21
	v_mul_f32_e32 v25, v21, v25
	v_fma_f32 v25, v21, v25, v21
	v_add_f32_e32 v24, 1.0, v24
	v_mul_f32_e32 v25, 0x3f4c422a, v25
	v_rcp_f32_e32 v24, v24
	v_add_f32_e32 v25, v25, v25
	v_mul_f32_e32 v25, 0x3fb8aa3b, v25
	v_exp_f32_e32 v25, v25
	v_fma_f32 v24, v24, -2.0, 1.0
	v_mul_f32_e32 v20, 0.5, v20
	v_add_f32_e32 v24, 1.0, v24
	v_mul_f32_e32 v20, v20, v24
	v_add_f32_e32 v24, 1.0, v25
	v_mul_f32_e32 v25, 0x3d372713, v22
	v_mul_f32_e32 v25, v22, v25
	v_fma_f32 v25, v22, v25, v22
	v_mul_f32_e32 v26, 0x3d372713, v23
	v_mul_f32_e32 v25, 0x3f4c422a, v25
	v_mul_f32_e32 v26, v23, v26
	v_add_f32_e32 v25, v25, v25
	v_fma_f32 v26, v23, v26, v23
	v_mul_f32_e32 v25, 0x3fb8aa3b, v25
	v_mul_f32_e32 v26, 0x3f4c422a, v26
	v_rcp_f32_e32 v24, v24
	v_exp_f32_e32 v25, v25
	v_add_f32_e32 v26, v26, v26
	v_mul_f32_e32 v26, 0x3fb8aa3b, v26
	v_exp_f32_e32 v26, v26
	v_fma_f32 v24, v24, -2.0, 1.0
	v_add_f32_e32 v25, 1.0, v25
	v_mul_f32_e32 v21, 0.5, v21
	v_add_f32_e32 v24, 1.0, v24
	v_rcp_f32_e32 v25, v25
	v_mul_f32_e32 v21, v21, v24
	v_add_f32_e32 v24, 1.0, v26
	v_rcp_f32_e32 v24, v24
	v_cvt_pk_bf16_f32 v20, v20, v21
	v_fma_f32 v21, v25, -2.0, 1.0
	v_mul_f32_e32 v22, 0.5, v22
	v_add_f32_e32 v21, 1.0, v21
	v_mul_f32_e32 v21, v22, v21
	v_fma_f32 v22, v24, -2.0, 1.0
	v_mul_f32_e32 v23, 0.5, v23
	v_add_f32_e32 v22, 1.0, v22
	v_mul_f32_e32 v22, v23, v22
	v_cvt_pk_bf16_f32 v21, v21, v22
	global_store_dwordx2 v[120:121], v[20:21], off offset:192
	s_waitcnt vmcnt(15)
	v_lshlrev_b32_e32 v20, 16, v76
	v_fma_f32 v16, v44, v20, v16
	v_mul_f32_e32 v20, 0x3d372713, v16
	v_mul_f32_e32 v20, v16, v20
	v_fma_f32 v20, v16, v20, v16
	v_mul_f32_e32 v20, 0x3f4c422a, v20
	v_add_f32_e32 v20, v20, v20
	v_and_b32_e32 v21, 0xffff0000, v76
	v_mul_f32_e32 v20, 0x3fb8aa3b, v20
	v_fma_f32 v17, v45, v21, v17
	v_lshlrev_b32_e32 v21, 16, v77
	v_exp_f32_e32 v20, v20
	v_fma_f32 v18, v46, v21, v18
	v_and_b32_e32 v21, 0xffff0000, v77
	v_fmac_f32_e32 v19, v47, v21
	v_mul_f32_e32 v21, 0x3d372713, v17
	v_mul_f32_e32 v21, v17, v21
	v_fma_f32 v21, v17, v21, v17
	v_add_f32_e32 v20, 1.0, v20
	v_mul_f32_e32 v21, 0x3f4c422a, v21
	v_rcp_f32_e32 v20, v20
	v_add_f32_e32 v21, v21, v21
	v_mul_f32_e32 v21, 0x3fb8aa3b, v21
	v_exp_f32_e32 v21, v21
	v_fma_f32 v20, v20, -2.0, 1.0
	v_mul_f32_e32 v16, 0.5, v16
	v_add_f32_e32 v20, 1.0, v20
	v_mul_f32_e32 v16, v16, v20
	v_add_f32_e32 v20, 1.0, v21
	v_mul_f32_e32 v21, 0x3d372713, v18
	v_mul_f32_e32 v21, v18, v21
	v_fma_f32 v21, v18, v21, v18
	v_mul_f32_e32 v22, 0x3d372713, v19
	v_mul_f32_e32 v21, 0x3f4c422a, v21
	v_mul_f32_e32 v22, v19, v22
	v_add_f32_e32 v21, v21, v21
	v_fma_f32 v22, v19, v22, v19
	v_mul_f32_e32 v21, 0x3fb8aa3b, v21
	v_mul_f32_e32 v22, 0x3f4c422a, v22
	v_rcp_f32_e32 v20, v20
	v_exp_f32_e32 v21, v21
	v_add_f32_e32 v22, v22, v22
	v_mul_f32_e32 v22, 0x3fb8aa3b, v22
	v_exp_f32_e32 v22, v22
	v_fma_f32 v20, v20, -2.0, 1.0
	v_add_f32_e32 v21, 1.0, v21
	v_mul_f32_e32 v17, 0.5, v17
	v_add_f32_e32 v20, 1.0, v20
	v_rcp_f32_e32 v21, v21
	v_mul_f32_e32 v17, v17, v20
	v_add_f32_e32 v20, 1.0, v22
	v_rcp_f32_e32 v20, v20
	v_cvt_pk_bf16_f32 v16, v16, v17
	v_fma_f32 v17, v21, -2.0, 1.0
	v_mul_f32_e32 v18, 0.5, v18
	v_add_f32_e32 v17, 1.0, v17
	v_mul_f32_e32 v17, v18, v17
	v_fma_f32 v18, v20, -2.0, 1.0
	v_mul_f32_e32 v19, 0.5, v19
	v_add_f32_e32 v18, 1.0, v18
	v_mul_f32_e32 v18, v19, v18
	v_cvt_pk_bf16_f32 v17, v17, v18
	global_store_dwordx2 v[116:117], v[16:17], off offset:192
	s_waitcnt vmcnt(15)
; __device__ __forceinline__ unsigned pk2(float lo, float hi) { return pg8::cvt_pk_bf16(lo, hi); }
; __device__ __forceinline__ float gelu_tanh(float x) { const float z = 0.7978845608028654f * (x + 0.044715f * x * x * x); const float t = 1.f - 2.f * __builtin_amdgcn_rcpf(__expf(2.f * z) + 1.f); return 0.5f * x * (1.f + t); }
; template <int PMODE> __device__ __forceinline__ void ssm_c_task(unsigned char* ws, LAS unsigned char* lds, int l, int task, int tid_in) {
;     ...
;         for (int a = 0; a < 4; ++a)
; #pragma unroll
;             for (int c = 0; c < 4; ++c) { const int col = cb * 64 + c * 16 + rr_e; const size_t tok = (size_t)col * 64 + wid * 8 + a0 + a; uw[a][c] = *(const u32x2*)(U + tok * 512 + g * 16 + 4 * kk); }
; #pragma unroll
;         for (int a = 0; a < 4; ++a)
; #pragma unroll
;             for (int c = 0; c < 4; ++c) { const int col = cb * 64 + c * 16 + rr_e; const size_t tok = (size_t)col * 64 + wid * 8 + a0 + a;
;                 const f32x4 av = acc[a0 + a][c];
;                 const float y0 = av[0] + dv[0] * bflo(uw[a][c].x), y1 = av[1] + dv[1] * bfhi(uw[a][c].x), y2 = av[2] + dv[2] * bflo(uw[a][c].y), y3 = av[3] + dv[3] * bfhi(uw[a][c].y);
;                 u32x2 o; o.x = pk2(gelu_tanh(y0), gelu_tanh(y1)); o.y = pk2(gelu_tanh(y2), gelu_tanh(y3));
;                 if (PMODE == 4) asm volatile("" :: "v"(o)); else *(u32x2*)(yb + (c * 1024 + a0 + a) * 16) = o; }
	v_lshlrev_b32_e32 v16, 16, v74
	v_fma_f32 v12, v44, v16, v12
	v_mul_f32_e32 v16, 0x3d372713, v12
	v_mul_f32_e32 v16, v12, v16
	v_fma_f32 v16, v12, v16, v12
	v_mul_f32_e32 v16, 0x3f4c422a, v16
	v_add_f32_e32 v16, v16, v16
	v_and_b32_e32 v17, 0xffff0000, v74
	v_mul_f32_e32 v16, 0x3fb8aa3b, v16
	v_fma_f32 v13, v45, v17, v13
	v_lshlrev_b32_e32 v17, 16, v75
	v_exp_f32_e32 v16, v16
	v_fma_f32 v14, v46, v17, v14
	v_and_b32_e32 v17, 0xffff0000, v75
	v_fmac_f32_e32 v15, v47, v17
	v_mul_f32_e32 v17, 0x3d372713, v13
	v_mul_f32_e32 v17, v13, v17
	v_fma_f32 v17, v13, v17, v13
	v_add_f32_e32 v16, 1.0, v16
	v_mul_f32_e32 v17, 0x3f4c422a, v17
	v_rcp_f32_e32 v16, v16
	v_add_f32_e32 v17, v17, v17
	v_mul_f32_e32 v17, 0x3fb8aa3b, v17
	v_exp_f32_e32 v17, v17
	v_fma_f32 v16, v16, -2.0, 1.0
	v_mul_f32_e32 v12, 0.5, v12
	v_add_f32_e32 v16, 1.0, v16
	v_mul_f32_e32 v12, v12, v16
	v_add_f32_e32 v16, 1.0, v17
	v_mul_f32_e32 v17, 0x3d372713, v14
	v_mul_f32_e32 v17, v14, v17
	v_fma_f32 v17, v14, v17, v14
	v_mul_f32_e32 v18, 0x3d372713, v15
	v_mul_f32_e32 v17, 0x3f4c422a, v17
	v_mul_f32_e32 v18, v15, v18
	v_add_f32_e32 v17, v17, v17
	v_fma_f32 v18, v15, v18, v15
	v_mul_f32_e32 v17, 0x3fb8aa3b, v17
	v_mul_f32_e32 v18, 0x3f4c422a, v18
	v_rcp_f32_e32 v16, v16
	v_exp_f32_e32 v17, v17
	v_add_f32_e32 v18, v18, v18
	v_mul_f32_e32 v18, 0x3fb8aa3b, v18
	v_exp_f32_e32 v18, v18
	v_fma_f32 v16, v16, -2.0, 1.0
	v_add_f32_e32 v17, 1.0, v17
	v_mul_f32_e32 v13, 0.5, v13
	v_add_f32_e32 v16, 1.0, v16
	v_rcp_f32_e32 v17, v17
	v_mul_f32_e32 v13, v13, v16
	v_add_f32_e32 v16, 1.0, v18
	v_rcp_f32_e32 v16, v16
	v_cvt_pk_bf16_f32 v12, v12, v13
	v_fma_f32 v13, v17, -2.0, 1.0
	v_mul_f32_e32 v14, 0.5, v14
	v_add_f32_e32 v13, 1.0, v13
	v_mul_f32_e32 v13, v14, v13
	v_fma_f32 v14, v16, -2.0, 1.0
	v_mul_f32_e32 v15, 0.5, v15
	v_add_f32_e32 v14, 1.0, v14
	v_mul_f32_e32 v14, v15, v14
	v_cvt_pk_bf16_f32 v13, v13, v14
	global_store_dwordx2 v[132:133], v[12:13], off offset:224
	s_waitcnt vmcnt(15)
	v_lshlrev_b32_e32 v12, 16, v72
	v_fma_f32 v8, v44, v12, v8
	v_mul_f32_e32 v12, 0x3d372713, v8
	v_mul_f32_e32 v12, v8, v12
	v_fma_f32 v12, v8, v12, v8
	v_mul_f32_e32 v12, 0x3f4c422a, v12
	v_add_f32_e32 v12, v12, v12
	v_and_b32_e32 v13, 0xffff0000, v72
	v_mul_f32_e32 v12, 0x3fb8aa3b, v12
	v_fma_f32 v9, v45, v13, v9
	v_lshlrev_b32_e32 v13, 16, v73
	v_exp_f32_e32 v12, v12
	v_fma_f32 v10, v46, v13, v10
	v_and_b32_e32 v13, 0xffff0000, v73
	v_fmac_f32_e32 v11, v47, v13
	v_mul_f32_e32 v13, 0x3d372713, v9
	v_mul_f32_e32 v13, v9, v13
	v_fma_f32 v13, v9, v13, v9
	v_add_f32_e32 v12, 1.0, v12
	v_mul_f32_e32 v13, 0x3f4c422a, v13
	v_rcp_f32_e32 v12, v12
	v_add_f32_e32 v13, v13, v13
	v_mul_f32_e32 v13, 0x3fb8aa3b, v13
	v_exp_f32_e32 v13, v13
	v_fma_f32 v12, v12, -2.0, 1.0
	v_mul_f32_e32 v8, 0.5, v8
	v_add_f32_e32 v12, 1.0, v12
	v_mul_f32_e32 v8, v8, v12
	v_add_f32_e32 v12, 1.0, v13
	v_mul_f32_e32 v13, 0x3d372713, v10
	v_mul_f32_e32 v13, v10, v13
	v_fma_f32 v13, v10, v13, v10
	v_mul_f32_e32 v14, 0x3d372713, v11
	v_mul_f32_e32 v13, 0x3f4c422a, v13
	v_mul_f32_e32 v14, v11, v14
	v_add_f32_e32 v13, v13, v13
	v_fma_f32 v14, v11, v14, v11
	v_mul_f32_e32 v13, 0x3fb8aa3b, v13
	v_mul_f32_e32 v14, 0x3f4c422a, v14
	v_rcp_f32_e32 v12, v12
	v_exp_f32_e32 v13, v13
	v_add_f32_e32 v14, v14, v14
	v_mul_f32_e32 v14, 0x3fb8aa3b, v14
	v_exp_f32_e32 v14, v14
	v_fma_f32 v12, v12, -2.0, 1.0
	v_add_f32_e32 v13, 1.0, v13
	v_mul_f32_e32 v9, 0.5, v9
	v_add_f32_e32 v12, 1.0, v12
	v_rcp_f32_e32 v13, v13
	v_mul_f32_e32 v9, v9, v12
	v_add_f32_e32 v12, 1.0, v14
	v_rcp_f32_e32 v12, v12
	v_cvt_pk_bf16_f32 v8, v8, v9
	v_fma_f32 v9, v13, -2.0, 1.0
	v_mul_f32_e32 v10, 0.5, v10
	v_add_f32_e32 v9, 1.0, v9
	v_mul_f32_e32 v9, v10, v9
	v_fma_f32 v10, v12, -2.0, 1.0
	v_mul_f32_e32 v11, 0.5, v11
	v_add_f32_e32 v10, 1.0, v10
	v_mul_f32_e32 v10, v11, v10
	v_cvt_pk_bf16_f32 v9, v9, v10
	global_store_dwordx2 v[124:125], v[8:9], off offset:224
	s_waitcnt vmcnt(15)
; __device__ __forceinline__ unsigned pk2(float lo, float hi) { return pg8::cvt_pk_bf16(lo, hi); }
; __device__ __forceinline__ float gelu_tanh(float x) { const float z = 0.7978845608028654f * (x + 0.044715f * x * x * x); const float t = 1.f - 2.f * __builtin_amdgcn_rcpf(__expf(2.f * z) + 1.f); return 0.5f * x * (1.f + t); }
; template <int PMODE> __device__ __forceinline__ void ssm_c_task(unsigned char* ws, LAS unsigned char* lds, int l, int task, int tid_in) {
;     ...
;         for (int a = 0; a < 4; ++a)
; #pragma unroll
;             for (int c = 0; c < 4; ++c) { const int col = cb * 64 + c * 16 + rr_e; const size_t tok = (size_t)col * 64 + wid * 8 + a0 + a;
;                 const f32x4 av = acc[a0 + a][c];
;                 const float y0 = av[0] + dv[0] * bflo(uw[a][c].x), y1 = av[1] + dv[1] * bfhi(uw[a][c].x), y2 = av[2] + dv[2] * bflo(uw[a][c].y), y3 = av[3] + dv[3] * bfhi(uw[a][c].y);
;                 u32x2 o; o.x = pk2(gelu_tanh(y0), gelu_tanh(y1)); o.y = pk2(gelu_tanh(y2), gelu_tanh(y3));
;                 if (PMODE == 4) asm volatile("" :: "v"(o)); else *(u32x2*)(yb + (c * 1024 + a0 + a) * 16) = o; }
	v_lshlrev_b32_e32 v8, 16, v70
	v_fma_f32 v4, v44, v8, v4
	v_mul_f32_e32 v8, 0x3d372713, v4
	v_mul_f32_e32 v8, v4, v8
	v_fma_f32 v8, v4, v8, v4
	v_mul_f32_e32 v8, 0x3f4c422a, v8
	v_add_f32_e32 v8, v8, v8
	v_and_b32_e32 v9, 0xffff0000, v70
	v_mul_f32_e32 v8, 0x3fb8aa3b, v8
	v_fma_f32 v5, v45, v9, v5
	v_lshlrev_b32_e32 v9, 16, v71
	v_exp_f32_e32 v8, v8
	v_fma_f32 v6, v46, v9, v6
	v_and_b32_e32 v9, 0xffff0000, v71
	v_fmac_f32_e32 v7, v47, v9
	v_mul_f32_e32 v9, 0x3d372713, v5
	v_mul_f32_e32 v9, v5, v9
	v_fma_f32 v9, v5, v9, v5
	v_add_f32_e32 v8, 1.0, v8
	v_mul_f32_e32 v9, 0x3f4c422a, v9
	v_rcp_f32_e32 v8, v8
	v_add_f32_e32 v9, v9, v9
	v_mul_f32_e32 v9, 0x3fb8aa3b, v9
	v_exp_f32_e32 v9, v9
	v_fma_f32 v8, v8, -2.0, 1.0
	v_mul_f32_e32 v4, 0.5, v4
	v_add_f32_e32 v8, 1.0, v8
	v_mul_f32_e32 v4, v4, v8
	v_add_f32_e32 v8, 1.0, v9
	v_mul_f32_e32 v9, 0x3d372713, v6
	v_mul_f32_e32 v9, v6, v9
	v_fma_f32 v9, v6, v9, v6
	v_mul_f32_e32 v10, 0x3d372713, v7
	v_mul_f32_e32 v9, 0x3f4c422a, v9
	v_mul_f32_e32 v10, v7, v10
	v_add_f32_e32 v9, v9, v9
	v_fma_f32 v10, v7, v10, v7
	v_mul_f32_e32 v9, 0x3fb8aa3b, v9
	v_mul_f32_e32 v10, 0x3f4c422a, v10
	v_rcp_f32_e32 v8, v8
	v_exp_f32_e32 v9, v9
	v_add_f32_e32 v10, v10, v10
	v_mul_f32_e32 v10, 0x3fb8aa3b, v10
	v_exp_f32_e32 v10, v10
	v_fma_f32 v8, v8, -2.0, 1.0
	v_add_f32_e32 v9, 1.0, v9
	v_mul_f32_e32 v5, 0.5, v5
	v_add_f32_e32 v8, 1.0, v8
	v_rcp_f32_e32 v9, v9
	v_mul_f32_e32 v5, v5, v8
	v_add_f32_e32 v8, 1.0, v10
	v_rcp_f32_e32 v8, v8
	v_cvt_pk_bf16_f32 v4, v4, v5
	v_fma_f32 v5, v9, -2.0, 1.0
	v_mul_f32_e32 v6, 0.5, v6
	v_add_f32_e32 v5, 1.0, v5
	v_mul_f32_e32 v5, v6, v5
	v_fma_f32 v6, v8, -2.0, 1.0
	v_mul_f32_e32 v7, 0.5, v7
	v_add_f32_e32 v6, 1.0, v6
	v_mul_f32_e32 v6, v7, v6
	v_cvt_pk_bf16_f32 v5, v5, v6
	global_store_dwordx2 v[120:121], v[4:5], off offset:224
	s_waitcnt vmcnt(15)
	v_lshlrev_b32_e32 v4, 16, v68
	v_fma_f32 v0, v44, v4, v0
	v_mul_f32_e32 v4, 0x3d372713, v0
	v_mul_f32_e32 v4, v0, v4
	v_fma_f32 v4, v0, v4, v0
	v_mul_f32_e32 v4, 0x3f4c422a, v4
	v_add_f32_e32 v4, v4, v4
	v_and_b32_e32 v5, 0xffff0000, v68
	v_mul_f32_e32 v4, 0x3fb8aa3b, v4
	v_fma_f32 v1, v45, v5, v1
	v_lshlrev_b32_e32 v5, 16, v69
	v_exp_f32_e32 v4, v4
	v_fma_f32 v2, v46, v5, v2
	v_and_b32_e32 v5, 0xffff0000, v69
	v_fmac_f32_e32 v3, v47, v5
	v_mul_f32_e32 v5, 0x3d372713, v1
	v_mul_f32_e32 v5, v1, v5
	v_fma_f32 v5, v1, v5, v1
	v_add_f32_e32 v4, 1.0, v4
	v_mul_f32_e32 v5, 0x3f4c422a, v5
	v_rcp_f32_e32 v4, v4
	v_add_f32_e32 v5, v5, v5
	v_mul_f32_e32 v5, 0x3fb8aa3b, v5
	v_exp_f32_e32 v5, v5
	v_fma_f32 v4, v4, -2.0, 1.0
	v_mul_f32_e32 v0, 0.5, v0
	v_add_f32_e32 v4, 1.0, v4
	v_mul_f32_e32 v0, v0, v4
	v_add_f32_e32 v4, 1.0, v5
	v_mul_f32_e32 v5, 0x3d372713, v2
	v_mul_f32_e32 v5, v2, v5
	v_fma_f32 v5, v2, v5, v2
	v_mul_f32_e32 v6, 0x3d372713, v3
	v_mul_f32_e32 v5, 0x3f4c422a, v5
	v_mul_f32_e32 v6, v3, v6
	v_add_f32_e32 v5, v5, v5
	v_fma_f32 v6, v3, v6, v3
	v_mul_f32_e32 v5, 0x3fb8aa3b, v5
	v_mul_f32_e32 v6, 0x3f4c422a, v6
	v_rcp_f32_e32 v4, v4
	v_exp_f32_e32 v5, v5
	v_add_f32_e32 v6, v6, v6
	v_mul_f32_e32 v6, 0x3fb8aa3b, v6
	v_exp_f32_e32 v6, v6
	v_fma_f32 v4, v4, -2.0, 1.0
	v_add_f32_e32 v5, 1.0, v5
	v_mul_f32_e32 v1, 0.5, v1
	v_add_f32_e32 v4, 1.0, v4
	v_rcp_f32_e32 v5, v5
	v_mul_f32_e32 v1, v1, v4
	v_add_f32_e32 v4, 1.0, v6
	v_rcp_f32_e32 v4, v4
	v_cvt_pk_bf16_f32 v0, v0, v1
	v_fma_f32 v1, v5, -2.0, 1.0
	v_mul_f32_e32 v2, 0.5, v2
	v_add_f32_e32 v1, 1.0, v1
	v_mul_f32_e32 v1, v2, v1
	v_fma_f32 v2, v4, -2.0, 1.0
	v_mul_f32_e32 v3, 0.5, v3
	v_add_f32_e32 v2, 1.0, v2
	v_mul_f32_e32 v2, v3, v2
	v_cvt_pk_bf16_f32 v1, v1, v2
	global_store_dwordx2 v[116:117], v[0:1], off offset:224
	s_cbranch_scc0 .LBB0_816
